# PREP: absorbed-weight inner loops rewritten (batched loads, counted vmcnt), transpose tiles batched-load fast path; scan: unroll 4, unconditional y write
# speedup vs baseline: 1.0531x; 1.0119x over previous
; __device__ __forceinline__ float red4(float x) { x += dppf(x, 0); x += dppf(x, 1); return x; }
; __device__ __forceinline__ void scan_phase(const Params& p, int j, unsigned char* smem) {
;     ...
; #pragma unroll 2
;             for (int t = 0; t < 16; ++t) {
;                 const float* op = OPS + t * 320 + kq * 16;
;                 f32x4 A4[4], B4[4], W4[4], K4[4], R4[4];
; #pragma unroll
;                 for (int i = 0; i < 4; ++i) A4[i] = *(const f32x4*)(op + i * 4);
; #pragma unroll
;                 for (int i = 0; i < 4; ++i) { W4[i] = *(const f32x4*)(op + 128 + i * 4); B4[i] = *(const f32x4*)(op + 64 + i * 4); K4[i] = *(const f32x4*)(op + 192 + i * 4); }
; #pragma unroll
;                 for (int i = 0; i < 4; ++i) R4[i] = *(const f32x4*)(op + 256 + i * 4);
;                 const float vv = VB[t * 64 + vrow];
;                 f32x2 s0 = {0.f, 0.f}, s1 = {0.f, 0.f};
; #pragma unroll
;                 for (int i = 0; i < 4; ++i) { s0 += S[2 * i] * (f32x2){A4[i][0], A4[i][1]}; s1 += S[2 * i + 1] * (f32x2){A4[i][2], A4[i][3]}; }
;                 const float sa = red4((s0[0] + s0[1]) + (s1[0] + s1[1]));
;                 const f32x2 sa2 = {sa, sa}, vv2 = {vv, vv};
; #pragma unroll
;                 for (int i = 0; i < 4; ++i) {
;                     S[2 * i] = S[2 * i] * (f32x2){W4[i][0], W4[i][1]} + sa2 * (f32x2){B4[i][0], B4[i][1]} + vv2 * (f32x2){K4[i][0], K4[i][1]};
;                     S[2 * i + 1] = S[2 * i + 1] * (f32x2){W4[i][2], W4[i][3]} + sa2 * (f32x2){B4[i][2], B4[i][3]} + vv2 * (f32x2){K4[i][2], K4[i][3]};
;                 }
;                 f32x2 y0 = {0.f, 0.f}, y1 = {0.f, 0.f};
; #pragma unroll
;                 for (int i = 0; i < 4; ++i) { y0 += S[2 * i] * (f32x2){R4[i][0], R4[i][1]}; y1 += S[2 * i + 1] * (f32x2){R4[i][2], R4[i][3]}; }
;                 const float y = red4((y0[0] + y0[1]) + (y1[0] + y1[1]));
;                 if (kq == 0) YB[t * 64 + vrow] = y;
;             }
.LBB0_510:
	s_addk_i32 s7, 0x400
	s_cmp_eq_u32 s7, 0
	v_add_u32_e32 v64, 0x1400, v64
	s_cbranch_scc1 .LBB0_504
	v_add_u32_e32 v66, s7, v65
.LBB0_511:
	v_pk_mul_f32 v[152:153], v[38:39], v[68:69]
	v_mul_f32_dpp v154, v68, v46 row_ror:8 row_mask:0xf bank_mask:0xf
	v_mul_f32_dpp v155, v69, v47 row_ror:8 row_mask:0xf bank_mask:0xf
	v_pk_fma_f32 v[152:153], v[40:41], v[70:71], v[152:153]
	v_fmac_f32_dpp v154, v70, v48 row_ror:8 row_mask:0xf bank_mask:0xf
	v_fmac_f32_dpp v155, v71, v49 row_ror:8 row_mask:0xf bank_mask:0xf
	v_pk_fma_f32 v[152:153], v[42:43], v[72:73], v[152:153]
	v_fmac_f32_dpp v154, v72, v50 row_ror:8 row_mask:0xf bank_mask:0xf
	v_fmac_f32_dpp v155, v73, v51 row_ror:8 row_mask:0xf bank_mask:0xf
	v_pk_fma_f32 v[152:153], v[44:45], v[74:75], v[152:153]
	v_fmac_f32_dpp v154, v74, v52 row_ror:8 row_mask:0xf bank_mask:0xf
	v_fmac_f32_dpp v155, v75, v53 row_ror:8 row_mask:0xf bank_mask:0xf
	v_add_f32_e32 v154, v154, v155
	v_add_f32_e32 v152, v152, v153
	v_add_f32_e32 v152, v152, v154
	v_pk_mul_f32 v[38:39], v[38:39], v[84:85]
	v_pk_mul_f32 v[40:41], v[40:41], v[86:87]
	v_add_f32_dpp v162, v152, v152 quad_perm:[1,0,3,2] row_mask:0xf bank_mask:0xf bound_ctrl:1
	v_pk_mul_f32 v[42:43], v[42:43], v[88:89]
	v_pk_mul_f32 v[44:45], v[44:45], v[90:91]
	v_add_f32_dpp v156, v162, v162 quad_perm:[2,3,0,1] row_mask:0xf bank_mask:0xf bound_ctrl:1
	v_mul_f32_dpp v46, v84, v46 row_ror:8 row_mask:0xf bank_mask:0xf
	v_mul_f32_dpp v47, v85, v47 row_ror:8 row_mask:0xf bank_mask:0xf
	v_mul_f32_dpp v48, v86, v48 row_ror:8 row_mask:0xf bank_mask:0xf
	v_mul_f32_dpp v49, v87, v49 row_ror:8 row_mask:0xf bank_mask:0xf
	v_mul_f32_dpp v50, v88, v50 row_ror:8 row_mask:0xf bank_mask:0xf
	v_mul_f32_dpp v51, v89, v51 row_ror:8 row_mask:0xf bank_mask:0xf
	v_mul_f32_dpp v52, v90, v52 row_ror:8 row_mask:0xf bank_mask:0xf
	v_mul_f32_dpp v53, v91, v53 row_ror:8 row_mask:0xf bank_mask:0xf
	v_pk_fma_f32 v[38:39], v[76:77], v[156:157], v[38:39] op_sel_hi:[1,0,1]
	v_pk_fma_f32 v[40:41], v[78:79], v[156:157], v[40:41] op_sel_hi:[1,0,1]
	v_pk_fma_f32 v[42:43], v[80:81], v[156:157], v[42:43] op_sel_hi:[1,0,1]
	v_pk_fma_f32 v[44:45], v[82:83], v[156:157], v[44:45] op_sel_hi:[1,0,1]
	v_fmac_f32_dpp v46, v76, v156 row_ror:8 row_mask:0xf bank_mask:0xf
	v_fmac_f32_dpp v47, v77, v156 row_ror:8 row_mask:0xf bank_mask:0xf
	v_fmac_f32_dpp v48, v78, v156 row_ror:8 row_mask:0xf bank_mask:0xf
	v_fmac_f32_dpp v49, v79, v156 row_ror:8 row_mask:0xf bank_mask:0xf
	v_fmac_f32_dpp v50, v80, v156 row_ror:8 row_mask:0xf bank_mask:0xf
	v_fmac_f32_dpp v51, v81, v156 row_ror:8 row_mask:0xf bank_mask:0xf
	v_fmac_f32_dpp v52, v82, v156 row_ror:8 row_mask:0xf bank_mask:0xf
	v_fmac_f32_dpp v53, v83, v156 row_ror:8 row_mask:0xf bank_mask:0xf
	v_pk_fma_f32 v[38:39], v[92:93], v[108:109], v[38:39] op_sel_hi:[1,0,1]
	v_pk_fma_f32 v[40:41], v[94:95], v[108:109], v[40:41] op_sel_hi:[1,0,1]
	v_pk_fma_f32 v[42:43], v[96:97], v[108:109], v[42:43] op_sel_hi:[1,0,1]
	v_pk_fma_f32 v[44:45], v[98:99], v[108:109], v[44:45] op_sel_hi:[1,0,1]
	v_fmac_f32_dpp v46, v92, v108 row_ror:8 row_mask:0xf bank_mask:0xf
	v_fmac_f32_dpp v47, v93, v108 row_ror:8 row_mask:0xf bank_mask:0xf
	v_fmac_f32_dpp v48, v94, v108 row_ror:8 row_mask:0xf bank_mask:0xf
	v_fmac_f32_dpp v49, v95, v108 row_ror:8 row_mask:0xf bank_mask:0xf
	v_fmac_f32_dpp v50, v96, v108 row_ror:8 row_mask:0xf bank_mask:0xf
	v_fmac_f32_dpp v51, v97, v108 row_ror:8 row_mask:0xf bank_mask:0xf
	v_fmac_f32_dpp v52, v98, v108 row_ror:8 row_mask:0xf bank_mask:0xf
	v_fmac_f32_dpp v53, v99, v108 row_ror:8 row_mask:0xf bank_mask:0xf
	v_pk_mul_f32 v[158:159], v[38:39], v[100:101]
	v_mul_f32_dpp v160, v100, v46 row_ror:8 row_mask:0xf bank_mask:0xf
	v_mul_f32_dpp v161, v101, v47 row_ror:8 row_mask:0xf bank_mask:0xf
	v_pk_fma_f32 v[158:159], v[40:41], v[102:103], v[158:159]
	v_fmac_f32_dpp v160, v102, v48 row_ror:8 row_mask:0xf bank_mask:0xf
	v_fmac_f32_dpp v161, v103, v49 row_ror:8 row_mask:0xf bank_mask:0xf
	v_pk_fma_f32 v[158:159], v[42:43], v[104:105], v[158:159]
	v_fmac_f32_dpp v160, v104, v50 row_ror:8 row_mask:0xf bank_mask:0xf
	v_fmac_f32_dpp v161, v105, v51 row_ror:8 row_mask:0xf bank_mask:0xf
	v_pk_fma_f32 v[158:159], v[44:45], v[106:107], v[158:159]
	v_fmac_f32_dpp v160, v106, v52 row_ror:8 row_mask:0xf bank_mask:0xf
	v_fmac_f32_dpp v161, v107, v53 row_ror:8 row_mask:0xf bank_mask:0xf
	v_add_f32_e32 v160, v160, v161
	v_add_f32_e32 v158, v158, v159
	v_add_f32_e32 v158, v158, v160
	s_waitcnt lgkmcnt(0)
; __device__ __forceinline__ float red4(float x) { x += dppf(x, 0); x += dppf(x, 1); return x; }
; __device__ __forceinline__ void scan_phase(const Params& p, int j, unsigned char* smem) {
;     ...
;             for (int t = 0; t < 16; ++t) {
;                 const float* op = OPS + t * 320 + kq * 16;
;                 f32x4 A4[4], B4[4], W4[4], K4[4], R4[4];
; #pragma unroll
;                 for (int i = 0; i < 4; ++i) A4[i] = *(const f32x4*)(op + i * 4);
; #pragma unroll
;                 for (int i = 0; i < 4; ++i) { W4[i] = *(const f32x4*)(op + 128 + i * 4); B4[i] = *(const f32x4*)(op + 64 + i * 4); K4[i] = *(const f32x4*)(op + 192 + i * 4); }
; #pragma unroll
;                 for (int i = 0; i < 4; ++i) R4[i] = *(const f32x4*)(op + 256 + i * 4);
;                 const float vv = VB[t * 64 + vrow];
;                 f32x2 s0 = {0.f, 0.f}, s1 = {0.f, 0.f};
; #pragma unroll
;                 for (int i = 0; i < 4; ++i) { s0 += S[2 * i] * (f32x2){A4[i][0], A4[i][1]}; s1 += S[2 * i + 1] * (f32x2){A4[i][2], A4[i][3]}; }
;                 const float sa = red4((s0[0] + s0[1]) + (s1[0] + s1[1]));
;                 const f32x2 sa2 = {sa, sa}, vv2 = {vv, vv};
; #pragma unroll
;                 for (int i = 0; i < 4; ++i) {
;                     S[2 * i] = S[2 * i] * (f32x2){W4[i][0], W4[i][1]} + sa2 * (f32x2){B4[i][0], B4[i][1]} + vv2 * (f32x2){K4[i][0], K4[i][1]};
;                     S[2 * i + 1] = S[2 * i + 1] * (f32x2){W4[i][2], W4[i][3]} + sa2 * (f32x2){B4[i][2], B4[i][3]} + vv2 * (f32x2){K4[i][2], K4[i][3]};
;                 }
;                 f32x2 y0 = {0.f, 0.f}, y1 = {0.f, 0.f};
; #pragma unroll
;                 for (int i = 0; i < 4; ++i) { y0 += S[2 * i] * (f32x2){R4[i][0], R4[i][1]}; y1 += S[2 * i + 1] * (f32x2){R4[i][2], R4[i][3]}; }
;                 const float y = red4((y0[0] + y0[1]) + (y1[0] + y1[1]));
;                 if (kq == 0) YB[t * 64 + vrow] = y;
;             }
	ds_read_b128 v[68:71], v64 offset:2560
	ds_read_b128 v[72:75], v64 offset:2576
	ds_read_b128 v[76:79], v64 offset:2816
	ds_read_b128 v[80:83], v64 offset:2832
	v_add_f32_dpp v163, v158, v158 quad_perm:[1,0,3,2] row_mask:0xf bank_mask:0xf bound_ctrl:1
	ds_read_b128 v[84:87], v64 offset:3072
	ds_read_b128 v[88:91], v64 offset:3088
	ds_read_b128 v[92:95], v64 offset:3328
	ds_read_b128 v[96:99], v64 offset:3344
	v_add_f32_dpp v160, v163, v163 quad_perm:[2,3,0,1] row_mask:0xf bank_mask:0xf bound_ctrl:1
	ds_read_b128 v[100:103], v64 offset:3584
	ds_read_b128 v[104:107], v64 offset:3600
	ds_read_b32 v108, v66 offset:25088
	ds_write_b32 v66, v160 offset:32768
	v_pk_mul_f32 v[152:153], v[38:39], v[110:111]
	v_mul_f32_dpp v154, v110, v46 row_ror:8 row_mask:0xf bank_mask:0xf
	v_mul_f32_dpp v155, v111, v47 row_ror:8 row_mask:0xf bank_mask:0xf
	v_pk_fma_f32 v[152:153], v[40:41], v[112:113], v[152:153]
	v_fmac_f32_dpp v154, v112, v48 row_ror:8 row_mask:0xf bank_mask:0xf
	v_fmac_f32_dpp v155, v113, v49 row_ror:8 row_mask:0xf bank_mask:0xf
	v_pk_fma_f32 v[152:153], v[42:43], v[114:115], v[152:153]
	v_fmac_f32_dpp v154, v114, v50 row_ror:8 row_mask:0xf bank_mask:0xf
	v_fmac_f32_dpp v155, v115, v51 row_ror:8 row_mask:0xf bank_mask:0xf
	v_pk_fma_f32 v[152:153], v[44:45], v[116:117], v[152:153]
	v_fmac_f32_dpp v154, v116, v52 row_ror:8 row_mask:0xf bank_mask:0xf
	v_fmac_f32_dpp v155, v117, v53 row_ror:8 row_mask:0xf bank_mask:0xf
	v_add_f32_e32 v154, v154, v155
	v_add_f32_e32 v152, v152, v153
	v_add_f32_e32 v152, v152, v154
	v_pk_mul_f32 v[38:39], v[38:39], v[126:127]
	v_pk_mul_f32 v[40:41], v[40:41], v[128:129]
	v_add_f32_dpp v162, v152, v152 quad_perm:[1,0,3,2] row_mask:0xf bank_mask:0xf bound_ctrl:1
	v_pk_mul_f32 v[42:43], v[42:43], v[130:131]
	v_pk_mul_f32 v[44:45], v[44:45], v[132:133]
	v_add_f32_dpp v156, v162, v162 quad_perm:[2,3,0,1] row_mask:0xf bank_mask:0xf bound_ctrl:1
	v_mul_f32_dpp v46, v126, v46 row_ror:8 row_mask:0xf bank_mask:0xf
	v_mul_f32_dpp v47, v127, v47 row_ror:8 row_mask:0xf bank_mask:0xf
	v_mul_f32_dpp v48, v128, v48 row_ror:8 row_mask:0xf bank_mask:0xf
	v_mul_f32_dpp v49, v129, v49 row_ror:8 row_mask:0xf bank_mask:0xf
	v_mul_f32_dpp v50, v130, v50 row_ror:8 row_mask:0xf bank_mask:0xf
	v_mul_f32_dpp v51, v131, v51 row_ror:8 row_mask:0xf bank_mask:0xf
	v_mul_f32_dpp v52, v132, v52 row_ror:8 row_mask:0xf bank_mask:0xf
	v_mul_f32_dpp v53, v133, v53 row_ror:8 row_mask:0xf bank_mask:0xf
	v_pk_fma_f32 v[38:39], v[118:119], v[156:157], v[38:39] op_sel_hi:[1,0,1]
	v_pk_fma_f32 v[40:41], v[120:121], v[156:157], v[40:41] op_sel_hi:[1,0,1]
	v_pk_fma_f32 v[42:43], v[122:123], v[156:157], v[42:43] op_sel_hi:[1,0,1]
	v_pk_fma_f32 v[44:45], v[124:125], v[156:157], v[44:45] op_sel_hi:[1,0,1]
	v_fmac_f32_dpp v46, v118, v156 row_ror:8 row_mask:0xf bank_mask:0xf
	v_fmac_f32_dpp v47, v119, v156 row_ror:8 row_mask:0xf bank_mask:0xf
	v_fmac_f32_dpp v48, v120, v156 row_ror:8 row_mask:0xf bank_mask:0xf
	v_fmac_f32_dpp v49, v121, v156 row_ror:8 row_mask:0xf bank_mask:0xf
	v_fmac_f32_dpp v50, v122, v156 row_ror:8 row_mask:0xf bank_mask:0xf
	v_fmac_f32_dpp v51, v123, v156 row_ror:8 row_mask:0xf bank_mask:0xf
	v_fmac_f32_dpp v52, v124, v156 row_ror:8 row_mask:0xf bank_mask:0xf
	v_fmac_f32_dpp v53, v125, v156 row_ror:8 row_mask:0xf bank_mask:0xf
	v_pk_fma_f32 v[38:39], v[134:135], v[150:151], v[38:39] op_sel_hi:[1,0,1]
	v_pk_fma_f32 v[40:41], v[136:137], v[150:151], v[40:41] op_sel_hi:[1,0,1]
	v_pk_fma_f32 v[42:43], v[138:139], v[150:151], v[42:43] op_sel_hi:[1,0,1]
	v_pk_fma_f32 v[44:45], v[140:141], v[150:151], v[44:45] op_sel_hi:[1,0,1]
	v_fmac_f32_dpp v46, v134, v150 row_ror:8 row_mask:0xf bank_mask:0xf
	v_fmac_f32_dpp v47, v135, v150 row_ror:8 row_mask:0xf bank_mask:0xf
	v_fmac_f32_dpp v48, v136, v150 row_ror:8 row_mask:0xf bank_mask:0xf
	v_fmac_f32_dpp v49, v137, v150 row_ror:8 row_mask:0xf bank_mask:0xf
	v_fmac_f32_dpp v50, v138, v150 row_ror:8 row_mask:0xf bank_mask:0xf
	v_fmac_f32_dpp v51, v139, v150 row_ror:8 row_mask:0xf bank_mask:0xf
	v_fmac_f32_dpp v52, v140, v150 row_ror:8 row_mask:0xf bank_mask:0xf
	v_fmac_f32_dpp v53, v141, v150 row_ror:8 row_mask:0xf bank_mask:0xf
	v_pk_mul_f32 v[158:159], v[38:39], v[142:143]
	v_mul_f32_dpp v160, v142, v46 row_ror:8 row_mask:0xf bank_mask:0xf
	v_mul_f32_dpp v161, v143, v47 row_ror:8 row_mask:0xf bank_mask:0xf
	v_pk_fma_f32 v[158:159], v[40:41], v[144:145], v[158:159]
	v_fmac_f32_dpp v160, v144, v48 row_ror:8 row_mask:0xf bank_mask:0xf
	v_fmac_f32_dpp v161, v145, v49 row_ror:8 row_mask:0xf bank_mask:0xf
	v_pk_fma_f32 v[158:159], v[42:43], v[146:147], v[158:159]
	v_fmac_f32_dpp v160, v146, v50 row_ror:8 row_mask:0xf bank_mask:0xf
	v_fmac_f32_dpp v161, v147, v51 row_ror:8 row_mask:0xf bank_mask:0xf
	v_pk_fma_f32 v[158:159], v[44:45], v[148:149], v[158:159]
	v_fmac_f32_dpp v160, v148, v52 row_ror:8 row_mask:0xf bank_mask:0xf
	v_fmac_f32_dpp v161, v149, v53 row_ror:8 row_mask:0xf bank_mask:0xf
	v_add_f32_e32 v160, v160, v161
	v_add_f32_e32 v158, v158, v159
	v_add_f32_e32 v158, v158, v160
	s_waitcnt lgkmcnt(0)
; __device__ __forceinline__ float red4(float x) { x += dppf(x, 0); x += dppf(x, 1); return x; }
; __device__ __forceinline__ void scan_phase(const Params& p, int j, unsigned char* smem) {
;     ...
;             for (int t = 0; t < 16; ++t) {
;                 const float* op = OPS + t * 320 + kq * 16;
;                 f32x4 A4[4], B4[4], W4[4], K4[4], R4[4];
; #pragma unroll
;                 for (int i = 0; i < 4; ++i) A4[i] = *(const f32x4*)(op + i * 4);
; #pragma unroll
;                 for (int i = 0; i < 4; ++i) { W4[i] = *(const f32x4*)(op + 128 + i * 4); B4[i] = *(const f32x4*)(op + 64 + i * 4); K4[i] = *(const f32x4*)(op + 192 + i * 4); }
; #pragma unroll
;                 for (int i = 0; i < 4; ++i) R4[i] = *(const f32x4*)(op + 256 + i * 4);
;                 const float vv = VB[t * 64 + vrow];
;                 f32x2 s0 = {0.f, 0.f}, s1 = {0.f, 0.f};
; #pragma unroll
;                 for (int i = 0; i < 4; ++i) { s0 += S[2 * i] * (f32x2){A4[i][0], A4[i][1]}; s1 += S[2 * i + 1] * (f32x2){A4[i][2], A4[i][3]}; }
;                 const float sa = red4((s0[0] + s0[1]) + (s1[0] + s1[1]));
;                 const f32x2 sa2 = {sa, sa}, vv2 = {vv, vv};
; #pragma unroll
;                 for (int i = 0; i < 4; ++i) {
;                     S[2 * i] = S[2 * i] * (f32x2){W4[i][0], W4[i][1]} + sa2 * (f32x2){B4[i][0], B4[i][1]} + vv2 * (f32x2){K4[i][0], K4[i][1]};
;                     S[2 * i + 1] = S[2 * i + 1] * (f32x2){W4[i][2], W4[i][3]} + sa2 * (f32x2){B4[i][2], B4[i][3]} + vv2 * (f32x2){K4[i][2], K4[i][3]};
;                 }
;                 f32x2 y0 = {0.f, 0.f}, y1 = {0.f, 0.f};
; #pragma unroll
;                 for (int i = 0; i < 4; ++i) { y0 += S[2 * i] * (f32x2){R4[i][0], R4[i][1]}; y1 += S[2 * i + 1] * (f32x2){R4[i][2], R4[i][3]}; }
;                 const float y = red4((y0[0] + y0[1]) + (y1[0] + y1[1]));
;                 if (kq == 0) YB[t * 64 + vrow] = y;
;             }
	ds_read_b128 v[110:113], v64 offset:3840
	ds_read_b128 v[114:117], v64 offset:3856
	ds_read_b128 v[118:121], v64 offset:4096
	ds_read_b128 v[122:125], v64 offset:4112
	v_add_f32_dpp v163, v158, v158 quad_perm:[1,0,3,2] row_mask:0xf bank_mask:0xf bound_ctrl:1
	ds_read_b128 v[126:129], v64 offset:4352
	ds_read_b128 v[130:133], v64 offset:4368
	ds_read_b128 v[134:137], v64 offset:4608
	ds_read_b128 v[138:141], v64 offset:4624
	v_add_f32_dpp v160, v163, v163 quad_perm:[2,3,0,1] row_mask:0xf bank_mask:0xf bound_ctrl:1
	ds_read_b128 v[142:145], v64 offset:4864
	ds_read_b128 v[146:149], v64 offset:4880
	ds_read_b32 v150, v66 offset:25344
	ds_write_b32 v66, v160 offset:33024
	v_pk_mul_f32 v[152:153], v[38:39], v[68:69]
	v_mul_f32_dpp v154, v68, v46 row_ror:8 row_mask:0xf bank_mask:0xf
	v_mul_f32_dpp v155, v69, v47 row_ror:8 row_mask:0xf bank_mask:0xf
	v_pk_fma_f32 v[152:153], v[40:41], v[70:71], v[152:153]
	v_fmac_f32_dpp v154, v70, v48 row_ror:8 row_mask:0xf bank_mask:0xf
	v_fmac_f32_dpp v155, v71, v49 row_ror:8 row_mask:0xf bank_mask:0xf
	v_pk_fma_f32 v[152:153], v[42:43], v[72:73], v[152:153]
	v_fmac_f32_dpp v154, v72, v50 row_ror:8 row_mask:0xf bank_mask:0xf
	v_fmac_f32_dpp v155, v73, v51 row_ror:8 row_mask:0xf bank_mask:0xf
	v_pk_fma_f32 v[152:153], v[44:45], v[74:75], v[152:153]
	v_fmac_f32_dpp v154, v74, v52 row_ror:8 row_mask:0xf bank_mask:0xf
	v_fmac_f32_dpp v155, v75, v53 row_ror:8 row_mask:0xf bank_mask:0xf
	v_add_f32_e32 v154, v154, v155
	v_add_f32_e32 v152, v152, v153
	v_add_f32_e32 v152, v152, v154
	v_pk_mul_f32 v[38:39], v[38:39], v[84:85]
	v_pk_mul_f32 v[40:41], v[40:41], v[86:87]
	v_add_f32_dpp v162, v152, v152 quad_perm:[1,0,3,2] row_mask:0xf bank_mask:0xf bound_ctrl:1
	v_pk_mul_f32 v[42:43], v[42:43], v[88:89]
	v_pk_mul_f32 v[44:45], v[44:45], v[90:91]
	v_add_f32_dpp v156, v162, v162 quad_perm:[2,3,0,1] row_mask:0xf bank_mask:0xf bound_ctrl:1
	v_mul_f32_dpp v46, v84, v46 row_ror:8 row_mask:0xf bank_mask:0xf
	v_mul_f32_dpp v47, v85, v47 row_ror:8 row_mask:0xf bank_mask:0xf
	v_mul_f32_dpp v48, v86, v48 row_ror:8 row_mask:0xf bank_mask:0xf
	v_mul_f32_dpp v49, v87, v49 row_ror:8 row_mask:0xf bank_mask:0xf
	v_mul_f32_dpp v50, v88, v50 row_ror:8 row_mask:0xf bank_mask:0xf
	v_mul_f32_dpp v51, v89, v51 row_ror:8 row_mask:0xf bank_mask:0xf
	v_mul_f32_dpp v52, v90, v52 row_ror:8 row_mask:0xf bank_mask:0xf
	v_mul_f32_dpp v53, v91, v53 row_ror:8 row_mask:0xf bank_mask:0xf
	v_pk_fma_f32 v[38:39], v[76:77], v[156:157], v[38:39] op_sel_hi:[1,0,1]
	v_pk_fma_f32 v[40:41], v[78:79], v[156:157], v[40:41] op_sel_hi:[1,0,1]
	v_pk_fma_f32 v[42:43], v[80:81], v[156:157], v[42:43] op_sel_hi:[1,0,1]
	v_pk_fma_f32 v[44:45], v[82:83], v[156:157], v[44:45] op_sel_hi:[1,0,1]
	v_fmac_f32_dpp v46, v76, v156 row_ror:8 row_mask:0xf bank_mask:0xf
	v_fmac_f32_dpp v47, v77, v156 row_ror:8 row_mask:0xf bank_mask:0xf
	v_fmac_f32_dpp v48, v78, v156 row_ror:8 row_mask:0xf bank_mask:0xf
	v_fmac_f32_dpp v49, v79, v156 row_ror:8 row_mask:0xf bank_mask:0xf
	v_fmac_f32_dpp v50, v80, v156 row_ror:8 row_mask:0xf bank_mask:0xf
	v_fmac_f32_dpp v51, v81, v156 row_ror:8 row_mask:0xf bank_mask:0xf
	v_fmac_f32_dpp v52, v82, v156 row_ror:8 row_mask:0xf bank_mask:0xf
	v_fmac_f32_dpp v53, v83, v156 row_ror:8 row_mask:0xf bank_mask:0xf
	v_pk_fma_f32 v[38:39], v[92:93], v[108:109], v[38:39] op_sel_hi:[1,0,1]
	v_pk_fma_f32 v[40:41], v[94:95], v[108:109], v[40:41] op_sel_hi:[1,0,1]
	v_pk_fma_f32 v[42:43], v[96:97], v[108:109], v[42:43] op_sel_hi:[1,0,1]
	v_pk_fma_f32 v[44:45], v[98:99], v[108:109], v[44:45] op_sel_hi:[1,0,1]
	v_fmac_f32_dpp v46, v92, v108 row_ror:8 row_mask:0xf bank_mask:0xf
	v_fmac_f32_dpp v47, v93, v108 row_ror:8 row_mask:0xf bank_mask:0xf
	v_fmac_f32_dpp v48, v94, v108 row_ror:8 row_mask:0xf bank_mask:0xf
	v_fmac_f32_dpp v49, v95, v108 row_ror:8 row_mask:0xf bank_mask:0xf
	v_fmac_f32_dpp v50, v96, v108 row_ror:8 row_mask:0xf bank_mask:0xf
	v_fmac_f32_dpp v51, v97, v108 row_ror:8 row_mask:0xf bank_mask:0xf
	v_fmac_f32_dpp v52, v98, v108 row_ror:8 row_mask:0xf bank_mask:0xf
	v_fmac_f32_dpp v53, v99, v108 row_ror:8 row_mask:0xf bank_mask:0xf
	v_pk_mul_f32 v[158:159], v[38:39], v[100:101]
	v_mul_f32_dpp v160, v100, v46 row_ror:8 row_mask:0xf bank_mask:0xf
	v_mul_f32_dpp v161, v101, v47 row_ror:8 row_mask:0xf bank_mask:0xf
	v_pk_fma_f32 v[158:159], v[40:41], v[102:103], v[158:159]
	v_fmac_f32_dpp v160, v102, v48 row_ror:8 row_mask:0xf bank_mask:0xf
	v_fmac_f32_dpp v161, v103, v49 row_ror:8 row_mask:0xf bank_mask:0xf
	v_pk_fma_f32 v[158:159], v[42:43], v[104:105], v[158:159]
	v_fmac_f32_dpp v160, v104, v50 row_ror:8 row_mask:0xf bank_mask:0xf
	v_fmac_f32_dpp v161, v105, v51 row_ror:8 row_mask:0xf bank_mask:0xf
	v_pk_fma_f32 v[158:159], v[44:45], v[106:107], v[158:159]
	v_fmac_f32_dpp v160, v106, v52 row_ror:8 row_mask:0xf bank_mask:0xf
	v_fmac_f32_dpp v161, v107, v53 row_ror:8 row_mask:0xf bank_mask:0xf
	v_add_f32_e32 v160, v160, v161
	v_add_f32_e32 v158, v158, v159
	v_add_f32_e32 v158, v158, v160
	s_waitcnt lgkmcnt(0)
; __device__ __forceinline__ float red4(float x) { x += dppf(x, 0); x += dppf(x, 1); return x; }
; __device__ __forceinline__ void scan_phase(const Params& p, int j, unsigned char* smem) {
;     ...
;             for (int t = 0; t < 16; ++t) {
;                 const float* op = OPS + t * 320 + kq * 16;
;                 f32x4 A4[4], B4[4], W4[4], K4[4], R4[4];
; #pragma unroll
;                 for (int i = 0; i < 4; ++i) A4[i] = *(const f32x4*)(op + i * 4);
; #pragma unroll
;                 for (int i = 0; i < 4; ++i) { W4[i] = *(const f32x4*)(op + 128 + i * 4); B4[i] = *(const f32x4*)(op + 64 + i * 4); K4[i] = *(const f32x4*)(op + 192 + i * 4); }
; #pragma unroll
;                 for (int i = 0; i < 4; ++i) R4[i] = *(const f32x4*)(op + 256 + i * 4);
;                 const float vv = VB[t * 64 + vrow];
;                 f32x2 s0 = {0.f, 0.f}, s1 = {0.f, 0.f};
; #pragma unroll
;                 for (int i = 0; i < 4; ++i) { s0 += S[2 * i] * (f32x2){A4[i][0], A4[i][1]}; s1 += S[2 * i + 1] * (f32x2){A4[i][2], A4[i][3]}; }
;                 const float sa = red4((s0[0] + s0[1]) + (s1[0] + s1[1]));
;                 const f32x2 sa2 = {sa, sa}, vv2 = {vv, vv};
; #pragma unroll
;                 for (int i = 0; i < 4; ++i) {
;                     S[2 * i] = S[2 * i] * (f32x2){W4[i][0], W4[i][1]} + sa2 * (f32x2){B4[i][0], B4[i][1]} + vv2 * (f32x2){K4[i][0], K4[i][1]};
;                     S[2 * i + 1] = S[2 * i + 1] * (f32x2){W4[i][2], W4[i][3]} + sa2 * (f32x2){B4[i][2], B4[i][3]} + vv2 * (f32x2){K4[i][2], K4[i][3]};
;                 }
;                 f32x2 y0 = {0.f, 0.f}, y1 = {0.f, 0.f};
; #pragma unroll
;                 for (int i = 0; i < 4; ++i) { y0 += S[2 * i] * (f32x2){R4[i][0], R4[i][1]}; y1 += S[2 * i + 1] * (f32x2){R4[i][2], R4[i][3]}; }
;                 const float y = red4((y0[0] + y0[1]) + (y1[0] + y1[1]));
;                 if (kq == 0) YB[t * 64 + vrow] = y;
;             }
	ds_read_b128 v[68:71], v64 offset:5120
	ds_read_b128 v[72:75], v64 offset:5136
	ds_read_b128 v[76:79], v64 offset:5376
	ds_read_b128 v[80:83], v64 offset:5392
	v_add_f32_dpp v163, v158, v158 quad_perm:[1,0,3,2] row_mask:0xf bank_mask:0xf bound_ctrl:1
	ds_read_b128 v[84:87], v64 offset:5632
	ds_read_b128 v[88:91], v64 offset:5648
	ds_read_b128 v[92:95], v64 offset:5888
	ds_read_b128 v[96:99], v64 offset:5904
	v_add_f32_dpp v160, v163, v163 quad_perm:[2,3,0,1] row_mask:0xf bank_mask:0xf bound_ctrl:1
	ds_read_b128 v[100:103], v64 offset:6144
	ds_read_b128 v[104:107], v64 offset:6160
	ds_read_b32 v108, v66 offset:25600
	ds_write_b32 v66, v160 offset:33280
	v_pk_mul_f32 v[152:153], v[38:39], v[110:111]
	v_mul_f32_dpp v154, v110, v46 row_ror:8 row_mask:0xf bank_mask:0xf
	v_mul_f32_dpp v155, v111, v47 row_ror:8 row_mask:0xf bank_mask:0xf
	v_pk_fma_f32 v[152:153], v[40:41], v[112:113], v[152:153]
	v_fmac_f32_dpp v154, v112, v48 row_ror:8 row_mask:0xf bank_mask:0xf
	v_fmac_f32_dpp v155, v113, v49 row_ror:8 row_mask:0xf bank_mask:0xf
	v_pk_fma_f32 v[152:153], v[42:43], v[114:115], v[152:153]
	v_fmac_f32_dpp v154, v114, v50 row_ror:8 row_mask:0xf bank_mask:0xf
	v_fmac_f32_dpp v155, v115, v51 row_ror:8 row_mask:0xf bank_mask:0xf
	v_pk_fma_f32 v[152:153], v[44:45], v[116:117], v[152:153]
	v_fmac_f32_dpp v154, v116, v52 row_ror:8 row_mask:0xf bank_mask:0xf
	v_fmac_f32_dpp v155, v117, v53 row_ror:8 row_mask:0xf bank_mask:0xf
	v_add_f32_e32 v154, v154, v155
	v_add_f32_e32 v152, v152, v153
	v_add_f32_e32 v152, v152, v154
	v_pk_mul_f32 v[38:39], v[38:39], v[126:127]
	v_pk_mul_f32 v[40:41], v[40:41], v[128:129]
	v_add_f32_dpp v162, v152, v152 quad_perm:[1,0,3,2] row_mask:0xf bank_mask:0xf bound_ctrl:1
	v_pk_mul_f32 v[42:43], v[42:43], v[130:131]
	v_pk_mul_f32 v[44:45], v[44:45], v[132:133]
	v_add_f32_dpp v156, v162, v162 quad_perm:[2,3,0,1] row_mask:0xf bank_mask:0xf bound_ctrl:1
	v_mul_f32_dpp v46, v126, v46 row_ror:8 row_mask:0xf bank_mask:0xf
	v_mul_f32_dpp v47, v127, v47 row_ror:8 row_mask:0xf bank_mask:0xf
	v_mul_f32_dpp v48, v128, v48 row_ror:8 row_mask:0xf bank_mask:0xf
	v_mul_f32_dpp v49, v129, v49 row_ror:8 row_mask:0xf bank_mask:0xf
	v_mul_f32_dpp v50, v130, v50 row_ror:8 row_mask:0xf bank_mask:0xf
	v_mul_f32_dpp v51, v131, v51 row_ror:8 row_mask:0xf bank_mask:0xf
	v_mul_f32_dpp v52, v132, v52 row_ror:8 row_mask:0xf bank_mask:0xf
	v_mul_f32_dpp v53, v133, v53 row_ror:8 row_mask:0xf bank_mask:0xf
	v_pk_fma_f32 v[38:39], v[118:119], v[156:157], v[38:39] op_sel_hi:[1,0,1]
	v_pk_fma_f32 v[40:41], v[120:121], v[156:157], v[40:41] op_sel_hi:[1,0,1]
	v_pk_fma_f32 v[42:43], v[122:123], v[156:157], v[42:43] op_sel_hi:[1,0,1]
	v_pk_fma_f32 v[44:45], v[124:125], v[156:157], v[44:45] op_sel_hi:[1,0,1]
	v_fmac_f32_dpp v46, v118, v156 row_ror:8 row_mask:0xf bank_mask:0xf
	v_fmac_f32_dpp v47, v119, v156 row_ror:8 row_mask:0xf bank_mask:0xf
	v_fmac_f32_dpp v48, v120, v156 row_ror:8 row_mask:0xf bank_mask:0xf
	v_fmac_f32_dpp v49, v121, v156 row_ror:8 row_mask:0xf bank_mask:0xf
	v_fmac_f32_dpp v50, v122, v156 row_ror:8 row_mask:0xf bank_mask:0xf
	v_fmac_f32_dpp v51, v123, v156 row_ror:8 row_mask:0xf bank_mask:0xf
	v_fmac_f32_dpp v52, v124, v156 row_ror:8 row_mask:0xf bank_mask:0xf
	v_fmac_f32_dpp v53, v125, v156 row_ror:8 row_mask:0xf bank_mask:0xf
	v_pk_fma_f32 v[38:39], v[134:135], v[150:151], v[38:39] op_sel_hi:[1,0,1]
	v_pk_fma_f32 v[40:41], v[136:137], v[150:151], v[40:41] op_sel_hi:[1,0,1]
	v_pk_fma_f32 v[42:43], v[138:139], v[150:151], v[42:43] op_sel_hi:[1,0,1]
	v_pk_fma_f32 v[44:45], v[140:141], v[150:151], v[44:45] op_sel_hi:[1,0,1]
	v_fmac_f32_dpp v46, v134, v150 row_ror:8 row_mask:0xf bank_mask:0xf
	v_fmac_f32_dpp v47, v135, v150 row_ror:8 row_mask:0xf bank_mask:0xf
	v_fmac_f32_dpp v48, v136, v150 row_ror:8 row_mask:0xf bank_mask:0xf
	v_fmac_f32_dpp v49, v137, v150 row_ror:8 row_mask:0xf bank_mask:0xf
	v_fmac_f32_dpp v50, v138, v150 row_ror:8 row_mask:0xf bank_mask:0xf
	v_fmac_f32_dpp v51, v139, v150 row_ror:8 row_mask:0xf bank_mask:0xf
	v_fmac_f32_dpp v52, v140, v150 row_ror:8 row_mask:0xf bank_mask:0xf
	v_fmac_f32_dpp v53, v141, v150 row_ror:8 row_mask:0xf bank_mask:0xf
	v_pk_mul_f32 v[158:159], v[38:39], v[142:143]
	v_mul_f32_dpp v160, v142, v46 row_ror:8 row_mask:0xf bank_mask:0xf
	v_mul_f32_dpp v161, v143, v47 row_ror:8 row_mask:0xf bank_mask:0xf
	v_pk_fma_f32 v[158:159], v[40:41], v[144:145], v[158:159]
	v_fmac_f32_dpp v160, v144, v48 row_ror:8 row_mask:0xf bank_mask:0xf
	v_fmac_f32_dpp v161, v145, v49 row_ror:8 row_mask:0xf bank_mask:0xf
	v_pk_fma_f32 v[158:159], v[42:43], v[146:147], v[158:159]
	v_fmac_f32_dpp v160, v146, v50 row_ror:8 row_mask:0xf bank_mask:0xf
	v_fmac_f32_dpp v161, v147, v51 row_ror:8 row_mask:0xf bank_mask:0xf
	v_pk_fma_f32 v[158:159], v[44:45], v[148:149], v[158:159]
	v_fmac_f32_dpp v160, v148, v52 row_ror:8 row_mask:0xf bank_mask:0xf
	v_fmac_f32_dpp v161, v149, v53 row_ror:8 row_mask:0xf bank_mask:0xf
	v_add_f32_e32 v160, v160, v161
	v_add_f32_e32 v158, v158, v159
	v_add_f32_e32 v158, v158, v160
	s_waitcnt lgkmcnt(0)
	ds_read_b128 v[110:113], v64 offset:6400
	ds_read_b128 v[114:117], v64 offset:6416
	ds_read_b128 v[118:121], v64 offset:6656
	ds_read_b128 v[122:125], v64 offset:6672
	v_add_f32_dpp v163, v158, v158 quad_perm:[1,0,3,2] row_mask:0xf bank_mask:0xf bound_ctrl:1
	ds_read_b128 v[126:129], v64 offset:6912
	ds_read_b128 v[130:133], v64 offset:6928
	ds_read_b128 v[134:137], v64 offset:7168
	ds_read_b128 v[138:141], v64 offset:7184
	v_add_f32_dpp v160, v163, v163 quad_perm:[2,3,0,1] row_mask:0xf bank_mask:0xf bound_ctrl:1
	ds_read_b128 v[142:145], v64 offset:7424
	ds_read_b128 v[146:149], v64 offset:7440
	ds_read_b32 v150, v66 offset:25856
	ds_write_b32 v66, v160 offset:33536
	s_branch .LBB0_510

; __device__ __forceinline__ void prep_phase(const Params& p, unsigned char* smem) {
;     ...
;         const float* uq = p.in[25] + (size_t)j * 256 * 1024 + (size_t)(qg * 16) * 1024 + h * 64;
;         const float* uk = p.in[26] + (size_t)j * 16 * 64 * 128 + (size_t)h * 64 * 128 + c;
;         float acc[16];
; #pragma unroll
;         for (int i = 0; i < 16; ++i) acc[i] = 0.f;
;         for (int d = 0; d < 64; ++d) {
;             const float kv = uk[d * 128];
; #pragma unroll
;             for (int i = 0; i < 16; ++i) acc[i] += uq[i * 1024 + d] * kv;
;         }
.LBB0_527:
	s_mov_b64 s[4:5], 0x1000
	v_lshl_add_u64 v[168:169], v[14:15], 0, s[4:5]
	s_mov_b64 s[4:5], 0x3000
	v_lshl_add_u64 v[170:171], v[14:15], 0, s[4:5]
	s_mov_b64 s[4:5], 0x5000
	v_lshl_add_u64 v[172:173], v[14:15], 0, s[4:5]
	s_mov_b64 s[4:5], 0x7000
	v_lshl_add_u64 v[174:175], v[14:15], 0, s[4:5]
	s_mov_b64 s[4:5], 0x9000
	v_lshl_add_u64 v[176:177], v[14:15], 0, s[4:5]
	s_mov_b64 s[4:5], 0xb000
	v_lshl_add_u64 v[178:179], v[14:15], 0, s[4:5]
	s_mov_b64 s[4:5], 0xd000
	v_lshl_add_u64 v[180:181], v[14:15], 0, s[4:5]
	s_mov_b64 s[4:5], 0xf000
	v_lshl_add_u64 v[182:183], v[14:15], 0, s[4:5]
	v_mov_b64_e32 v[184:185], v[10:11]
	s_mov_b64 s[4:5], 0x800
	s_waitcnt vmcnt(0)
	global_load_dwordx4 v[32:35], v[168:169], off offset:-4096
	global_load_dwordx4 v[36:39], v[168:169], off
	global_load_dwordx4 v[40:43], v[170:171], off offset:-4096
	global_load_dwordx4 v[44:47], v[170:171], off
	global_load_dwordx4 v[48:51], v[172:173], off offset:-4096
	global_load_dwordx4 v[52:55], v[172:173], off
	global_load_dwordx4 v[56:59], v[174:175], off offset:-4096
	global_load_dwordx4 v[60:63], v[174:175], off
	global_load_dwordx4 v[64:67], v[176:177], off offset:-4096
	global_load_dwordx4 v[68:71], v[176:177], off
	global_load_dwordx4 v[72:75], v[178:179], off offset:-4096
	global_load_dwordx4 v[76:79], v[178:179], off
	global_load_dwordx4 v[80:83], v[180:181], off offset:-4096
	global_load_dwordx4 v[84:87], v[180:181], off
	global_load_dwordx4 v[88:91], v[182:183], off offset:-4096
	global_load_dwordx4 v[92:95], v[182:183], off
	global_load_dword v96, v[184:185], off offset:-512
	global_load_dword v97, v[184:185], off
	global_load_dword v98, v[184:185], off offset:512
	global_load_dword v99, v[184:185], off offset:1024
	v_lshl_add_u64 v[184:185], v[184:185], 0, s[4:5]
	global_load_dwordx4 v[100:103], v[168:169], off offset:-4080
	global_load_dwordx4 v[104:107], v[168:169], off offset:16
	global_load_dwordx4 v[108:111], v[170:171], off offset:-4080
	global_load_dwordx4 v[112:115], v[170:171], off offset:16
	global_load_dwordx4 v[116:119], v[172:173], off offset:-4080
	global_load_dwordx4 v[120:123], v[172:173], off offset:16
	global_load_dwordx4 v[124:127], v[174:175], off offset:-4080
	global_load_dwordx4 v[128:131], v[174:175], off offset:16
	global_load_dwordx4 v[132:135], v[176:177], off offset:-4080
	global_load_dwordx4 v[136:139], v[176:177], off offset:16
	global_load_dwordx4 v[140:143], v[178:179], off offset:-4080
	global_load_dwordx4 v[144:147], v[178:179], off offset:16
	global_load_dwordx4 v[148:151], v[180:181], off offset:-4080
	global_load_dwordx4 v[152:155], v[180:181], off offset:16
	global_load_dwordx4 v[156:159], v[182:183], off offset:-4080
	global_load_dwordx4 v[160:163], v[182:183], off offset:16
	global_load_dword v164, v[184:185], off offset:-512
	global_load_dword v165, v[184:185], off
	global_load_dword v166, v[184:185], off offset:512
	global_load_dword v167, v[184:185], off offset:1024
	v_lshl_add_u64 v[184:185], v[184:185], 0, s[4:5]
	s_waitcnt vmcnt(20)
	v_fmac_f32_e32 v28, v32, v96
	v_fmac_f32_e32 v29, v36, v96
	v_fmac_f32_e32 v26, v40, v96
	v_fmac_f32_e32 v27, v44, v96
	v_fmac_f32_e32 v24, v48, v96
	v_fmac_f32_e32 v25, v52, v96
	v_fmac_f32_e32 v22, v56, v96
	v_fmac_f32_e32 v23, v60, v96
	v_fmac_f32_e32 v20, v64, v96
	v_fmac_f32_e32 v21, v68, v96
	v_fmac_f32_e32 v18, v72, v96
	v_fmac_f32_e32 v19, v76, v96
	v_fmac_f32_e32 v16, v80, v96
	v_fmac_f32_e32 v17, v84, v96
	v_fmac_f32_e32 v12, v88, v96
	v_fmac_f32_e32 v13, v92, v96
	v_fmac_f32_e32 v28, v33, v97
	v_fmac_f32_e32 v29, v37, v97
	v_fmac_f32_e32 v26, v41, v97
	v_fmac_f32_e32 v27, v45, v97
	v_fmac_f32_e32 v24, v49, v97
	v_fmac_f32_e32 v25, v53, v97
	v_fmac_f32_e32 v22, v57, v97
	v_fmac_f32_e32 v23, v61, v97
	v_fmac_f32_e32 v20, v65, v97
	v_fmac_f32_e32 v21, v69, v97
	v_fmac_f32_e32 v18, v73, v97
	v_fmac_f32_e32 v19, v77, v97
	v_fmac_f32_e32 v16, v81, v97
	v_fmac_f32_e32 v17, v85, v97
	v_fmac_f32_e32 v12, v89, v97
	v_fmac_f32_e32 v13, v93, v97
	v_fmac_f32_e32 v28, v34, v98
	v_fmac_f32_e32 v29, v38, v98
	v_fmac_f32_e32 v26, v42, v98
	v_fmac_f32_e32 v27, v46, v98
	v_fmac_f32_e32 v24, v50, v98
	v_fmac_f32_e32 v25, v54, v98
	v_fmac_f32_e32 v22, v58, v98
	v_fmac_f32_e32 v23, v62, v98
	v_fmac_f32_e32 v20, v66, v98
	v_fmac_f32_e32 v21, v70, v98
	v_fmac_f32_e32 v18, v74, v98
	v_fmac_f32_e32 v19, v78, v98
	v_fmac_f32_e32 v16, v82, v98
	v_fmac_f32_e32 v17, v86, v98
	v_fmac_f32_e32 v12, v90, v98
	v_fmac_f32_e32 v13, v94, v98
	v_fmac_f32_e32 v28, v35, v99
	v_fmac_f32_e32 v29, v39, v99
	v_fmac_f32_e32 v26, v43, v99
	v_fmac_f32_e32 v27, v47, v99
	v_fmac_f32_e32 v24, v51, v99
	v_fmac_f32_e32 v25, v55, v99
	v_fmac_f32_e32 v22, v59, v99
	v_fmac_f32_e32 v23, v63, v99
	v_fmac_f32_e32 v20, v67, v99
	v_fmac_f32_e32 v21, v71, v99
	v_fmac_f32_e32 v18, v75, v99
	v_fmac_f32_e32 v19, v79, v99
	v_fmac_f32_e32 v16, v83, v99
	v_fmac_f32_e32 v17, v87, v99
	v_fmac_f32_e32 v12, v91, v99
	v_fmac_f32_e32 v13, v95, v99
	global_load_dwordx4 v[32:35], v[168:169], off offset:-4064
	global_load_dwordx4 v[36:39], v[168:169], off offset:32
	global_load_dwordx4 v[40:43], v[170:171], off offset:-4064
	global_load_dwordx4 v[44:47], v[170:171], off offset:32
	global_load_dwordx4 v[48:51], v[172:173], off offset:-4064
	global_load_dwordx4 v[52:55], v[172:173], off offset:32
	global_load_dwordx4 v[56:59], v[174:175], off offset:-4064
	global_load_dwordx4 v[60:63], v[174:175], off offset:32
	global_load_dwordx4 v[64:67], v[176:177], off offset:-4064
	global_load_dwordx4 v[68:71], v[176:177], off offset:32
	global_load_dwordx4 v[72:75], v[178:179], off offset:-4064
	global_load_dwordx4 v[76:79], v[178:179], off offset:32
	global_load_dwordx4 v[80:83], v[180:181], off offset:-4064
	global_load_dwordx4 v[84:87], v[180:181], off offset:32
	global_load_dwordx4 v[88:91], v[182:183], off offset:-4064
	global_load_dwordx4 v[92:95], v[182:183], off offset:32
	global_load_dword v96, v[184:185], off offset:-512
	global_load_dword v97, v[184:185], off
	global_load_dword v98, v[184:185], off offset:512
	global_load_dword v99, v[184:185], off offset:1024
	v_lshl_add_u64 v[184:185], v[184:185], 0, s[4:5]
	s_waitcnt vmcnt(20)
; __device__ __forceinline__ void prep_phase(const Params& p, unsigned char* smem) {
;     ...
;         const float* uq = p.in[25] + (size_t)j * 256 * 1024 + (size_t)(qg * 16) * 1024 + h * 64;
;         const float* uk = p.in[26] + (size_t)j * 16 * 64 * 128 + (size_t)h * 64 * 128 + c;
;         float acc[16];
; #pragma unroll
;         for (int i = 0; i < 16; ++i) acc[i] = 0.f;
;         for (int d = 0; d < 64; ++d) {
;             const float kv = uk[d * 128];
; #pragma unroll
;             for (int i = 0; i < 16; ++i) acc[i] += uq[i * 1024 + d] * kv;
;         }
	v_fmac_f32_e32 v28, v100, v164
	v_fmac_f32_e32 v29, v104, v164
	v_fmac_f32_e32 v26, v108, v164
	v_fmac_f32_e32 v27, v112, v164
	v_fmac_f32_e32 v24, v116, v164
	v_fmac_f32_e32 v25, v120, v164
	v_fmac_f32_e32 v22, v124, v164
	v_fmac_f32_e32 v23, v128, v164
	v_fmac_f32_e32 v20, v132, v164
	v_fmac_f32_e32 v21, v136, v164
	v_fmac_f32_e32 v18, v140, v164
	v_fmac_f32_e32 v19, v144, v164
	v_fmac_f32_e32 v16, v148, v164
	v_fmac_f32_e32 v17, v152, v164
	v_fmac_f32_e32 v12, v156, v164
	v_fmac_f32_e32 v13, v160, v164
	v_fmac_f32_e32 v28, v101, v165
	v_fmac_f32_e32 v29, v105, v165
	v_fmac_f32_e32 v26, v109, v165
	v_fmac_f32_e32 v27, v113, v165
	v_fmac_f32_e32 v24, v117, v165
	v_fmac_f32_e32 v25, v121, v165
	v_fmac_f32_e32 v22, v125, v165
	v_fmac_f32_e32 v23, v129, v165
	v_fmac_f32_e32 v20, v133, v165
	v_fmac_f32_e32 v21, v137, v165
	v_fmac_f32_e32 v18, v141, v165
	v_fmac_f32_e32 v19, v145, v165
	v_fmac_f32_e32 v16, v149, v165
	v_fmac_f32_e32 v17, v153, v165
	v_fmac_f32_e32 v12, v157, v165
	v_fmac_f32_e32 v13, v161, v165
	v_fmac_f32_e32 v28, v102, v166
	v_fmac_f32_e32 v29, v106, v166
	v_fmac_f32_e32 v26, v110, v166
	v_fmac_f32_e32 v27, v114, v166
	v_fmac_f32_e32 v24, v118, v166
	v_fmac_f32_e32 v25, v122, v166
	v_fmac_f32_e32 v22, v126, v166
	v_fmac_f32_e32 v23, v130, v166
	v_fmac_f32_e32 v20, v134, v166
	v_fmac_f32_e32 v21, v138, v166
	v_fmac_f32_e32 v18, v142, v166
	v_fmac_f32_e32 v19, v146, v166
	v_fmac_f32_e32 v16, v150, v166
	v_fmac_f32_e32 v17, v154, v166
	v_fmac_f32_e32 v12, v158, v166
	v_fmac_f32_e32 v13, v162, v166
	v_fmac_f32_e32 v28, v103, v167
	v_fmac_f32_e32 v29, v107, v167
	v_fmac_f32_e32 v26, v111, v167
	v_fmac_f32_e32 v27, v115, v167
	v_fmac_f32_e32 v24, v119, v167
	v_fmac_f32_e32 v25, v123, v167
	v_fmac_f32_e32 v22, v127, v167
	v_fmac_f32_e32 v23, v131, v167
	v_fmac_f32_e32 v20, v135, v167
	v_fmac_f32_e32 v21, v139, v167
	v_fmac_f32_e32 v18, v143, v167
	v_fmac_f32_e32 v19, v147, v167
	v_fmac_f32_e32 v16, v151, v167
	v_fmac_f32_e32 v17, v155, v167
	v_fmac_f32_e32 v12, v159, v167
	v_fmac_f32_e32 v13, v163, v167
	global_load_dwordx4 v[100:103], v[168:169], off offset:-4048
	global_load_dwordx4 v[104:107], v[168:169], off offset:48
	global_load_dwordx4 v[108:111], v[170:171], off offset:-4048
	global_load_dwordx4 v[112:115], v[170:171], off offset:48
	global_load_dwordx4 v[116:119], v[172:173], off offset:-4048
	global_load_dwordx4 v[120:123], v[172:173], off offset:48
	global_load_dwordx4 v[124:127], v[174:175], off offset:-4048
	global_load_dwordx4 v[128:131], v[174:175], off offset:48
	global_load_dwordx4 v[132:135], v[176:177], off offset:-4048
	global_load_dwordx4 v[136:139], v[176:177], off offset:48
	global_load_dwordx4 v[140:143], v[178:179], off offset:-4048
	global_load_dwordx4 v[144:147], v[178:179], off offset:48
	global_load_dwordx4 v[148:151], v[180:181], off offset:-4048
	global_load_dwordx4 v[152:155], v[180:181], off offset:48
	global_load_dwordx4 v[156:159], v[182:183], off offset:-4048
	global_load_dwordx4 v[160:163], v[182:183], off offset:48
	global_load_dword v164, v[184:185], off offset:-512
	global_load_dword v165, v[184:185], off
	global_load_dword v166, v[184:185], off offset:512
	global_load_dword v167, v[184:185], off offset:1024
	v_lshl_add_u64 v[184:185], v[184:185], 0, s[4:5]
	s_waitcnt vmcnt(20)
	v_fmac_f32_e32 v28, v32, v96
	v_fmac_f32_e32 v29, v36, v96
	v_fmac_f32_e32 v26, v40, v96
	v_fmac_f32_e32 v27, v44, v96
	v_fmac_f32_e32 v24, v48, v96
	v_fmac_f32_e32 v25, v52, v96
	v_fmac_f32_e32 v22, v56, v96
	v_fmac_f32_e32 v23, v60, v96
	v_fmac_f32_e32 v20, v64, v96
	v_fmac_f32_e32 v21, v68, v96
	v_fmac_f32_e32 v18, v72, v96
	v_fmac_f32_e32 v19, v76, v96
	v_fmac_f32_e32 v16, v80, v96
	v_fmac_f32_e32 v17, v84, v96
	v_fmac_f32_e32 v12, v88, v96
	v_fmac_f32_e32 v13, v92, v96
	v_fmac_f32_e32 v28, v33, v97
	v_fmac_f32_e32 v29, v37, v97
	v_fmac_f32_e32 v26, v41, v97
	v_fmac_f32_e32 v27, v45, v97
	v_fmac_f32_e32 v24, v49, v97
	v_fmac_f32_e32 v25, v53, v97
	v_fmac_f32_e32 v22, v57, v97
	v_fmac_f32_e32 v23, v61, v97
	v_fmac_f32_e32 v20, v65, v97
	v_fmac_f32_e32 v21, v69, v97
	v_fmac_f32_e32 v18, v73, v97
	v_fmac_f32_e32 v19, v77, v97
	v_fmac_f32_e32 v16, v81, v97
	v_fmac_f32_e32 v17, v85, v97
	v_fmac_f32_e32 v12, v89, v97
	v_fmac_f32_e32 v13, v93, v97
	v_fmac_f32_e32 v28, v34, v98
	v_fmac_f32_e32 v29, v38, v98
	v_fmac_f32_e32 v26, v42, v98
	v_fmac_f32_e32 v27, v46, v98
	v_fmac_f32_e32 v24, v50, v98
	v_fmac_f32_e32 v25, v54, v98
	v_fmac_f32_e32 v22, v58, v98
	v_fmac_f32_e32 v23, v62, v98
	v_fmac_f32_e32 v20, v66, v98
	v_fmac_f32_e32 v21, v70, v98
	v_fmac_f32_e32 v18, v74, v98
	v_fmac_f32_e32 v19, v78, v98
	v_fmac_f32_e32 v16, v82, v98
	v_fmac_f32_e32 v17, v86, v98
	v_fmac_f32_e32 v12, v90, v98
	v_fmac_f32_e32 v13, v94, v98
	v_fmac_f32_e32 v28, v35, v99
	v_fmac_f32_e32 v29, v39, v99
	v_fmac_f32_e32 v26, v43, v99
	v_fmac_f32_e32 v27, v47, v99
	v_fmac_f32_e32 v24, v51, v99
	v_fmac_f32_e32 v25, v55, v99
	v_fmac_f32_e32 v22, v59, v99
	v_fmac_f32_e32 v23, v63, v99
	v_fmac_f32_e32 v20, v67, v99
	v_fmac_f32_e32 v21, v71, v99
	v_fmac_f32_e32 v18, v75, v99
	v_fmac_f32_e32 v19, v79, v99
	v_fmac_f32_e32 v16, v83, v99
	v_fmac_f32_e32 v17, v87, v99
	v_fmac_f32_e32 v12, v91, v99
	v_fmac_f32_e32 v13, v95, v99
	global_load_dwordx4 v[32:35], v[168:169], off offset:-4032
	global_load_dwordx4 v[36:39], v[168:169], off offset:64
	global_load_dwordx4 v[40:43], v[170:171], off offset:-4032
	global_load_dwordx4 v[44:47], v[170:171], off offset:64
	global_load_dwordx4 v[48:51], v[172:173], off offset:-4032
	global_load_dwordx4 v[52:55], v[172:173], off offset:64
	global_load_dwordx4 v[56:59], v[174:175], off offset:-4032
	global_load_dwordx4 v[60:63], v[174:175], off offset:64
	global_load_dwordx4 v[64:67], v[176:177], off offset:-4032
	global_load_dwordx4 v[68:71], v[176:177], off offset:64
	global_load_dwordx4 v[72:75], v[178:179], off offset:-4032
	global_load_dwordx4 v[76:79], v[178:179], off offset:64
	global_load_dwordx4 v[80:83], v[180:181], off offset:-4032
	global_load_dwordx4 v[84:87], v[180:181], off offset:64
	global_load_dwordx4 v[88:91], v[182:183], off offset:-4032
	global_load_dwordx4 v[92:95], v[182:183], off offset:64
	global_load_dword v96, v[184:185], off offset:-512
	global_load_dword v97, v[184:185], off
	global_load_dword v98, v[184:185], off offset:512
	global_load_dword v99, v[184:185], off offset:1024
	v_lshl_add_u64 v[184:185], v[184:185], 0, s[4:5]
	s_waitcnt vmcnt(20)
; __device__ __forceinline__ void prep_phase(const Params& p, unsigned char* smem) {
;     ...
;     for (size_t it = gtid; it < (size_t)2 * 16 * 2048; it += nth) {
;         const int j = (int)(it >> 15), rem = (int)(it & 32767), qg = rem >> 11, n = rem & 2047, h = n >> 7, c = n & 127;
;         const float* uq = p.in[25] + (size_t)j * 256 * 1024 + (size_t)(qg * 16) * 1024 + h * 64;
;         const float* uk = p.in[26] + (size_t)j * 16 * 64 * 128 + (size_t)h * 64 * 128 + c;
;         float acc[16];
; #pragma unroll
;         for (int i = 0; i < 16; ++i) acc[i] = 0.f;
;         for (int d = 0; d < 64; ++d) {
;             const float kv = uk[d * 128];
; #pragma unroll
;             for (int i = 0; i < 16; ++i) acc[i] += uq[i * 1024 + d] * kv;
;         }
	v_fmac_f32_e32 v28, v100, v164
	v_fmac_f32_e32 v29, v104, v164
	v_fmac_f32_e32 v26, v108, v164
	v_fmac_f32_e32 v27, v112, v164
	v_fmac_f32_e32 v24, v116, v164
	v_fmac_f32_e32 v25, v120, v164
	v_fmac_f32_e32 v22, v124, v164
	v_fmac_f32_e32 v23, v128, v164
	v_fmac_f32_e32 v20, v132, v164
	v_fmac_f32_e32 v21, v136, v164
	v_fmac_f32_e32 v18, v140, v164
	v_fmac_f32_e32 v19, v144, v164
	v_fmac_f32_e32 v16, v148, v164
	v_fmac_f32_e32 v17, v152, v164
	v_fmac_f32_e32 v12, v156, v164
	v_fmac_f32_e32 v13, v160, v164
	v_fmac_f32_e32 v28, v101, v165
	v_fmac_f32_e32 v29, v105, v165
	v_fmac_f32_e32 v26, v109, v165
	v_fmac_f32_e32 v27, v113, v165
	v_fmac_f32_e32 v24, v117, v165
	v_fmac_f32_e32 v25, v121, v165
	v_fmac_f32_e32 v22, v125, v165
	v_fmac_f32_e32 v23, v129, v165
	v_fmac_f32_e32 v20, v133, v165
	v_fmac_f32_e32 v21, v137, v165
	v_fmac_f32_e32 v18, v141, v165
	v_fmac_f32_e32 v19, v145, v165
	v_fmac_f32_e32 v16, v149, v165
	v_fmac_f32_e32 v17, v153, v165
	v_fmac_f32_e32 v12, v157, v165
	v_fmac_f32_e32 v13, v161, v165
	v_fmac_f32_e32 v28, v102, v166
	v_fmac_f32_e32 v29, v106, v166
	v_fmac_f32_e32 v26, v110, v166
	v_fmac_f32_e32 v27, v114, v166
	v_fmac_f32_e32 v24, v118, v166
	v_fmac_f32_e32 v25, v122, v166
	v_fmac_f32_e32 v22, v126, v166
	v_fmac_f32_e32 v23, v130, v166
	v_fmac_f32_e32 v20, v134, v166
	v_fmac_f32_e32 v21, v138, v166
	v_fmac_f32_e32 v18, v142, v166
	v_fmac_f32_e32 v19, v146, v166
	v_fmac_f32_e32 v16, v150, v166
	v_fmac_f32_e32 v17, v154, v166
	v_fmac_f32_e32 v12, v158, v166
	v_fmac_f32_e32 v13, v162, v166
	v_fmac_f32_e32 v28, v103, v167
	v_fmac_f32_e32 v29, v107, v167
	v_fmac_f32_e32 v26, v111, v167
	v_fmac_f32_e32 v27, v115, v167
	v_fmac_f32_e32 v24, v119, v167
	v_fmac_f32_e32 v25, v123, v167
	v_fmac_f32_e32 v22, v127, v167
	v_fmac_f32_e32 v23, v131, v167
	v_fmac_f32_e32 v20, v135, v167
	v_fmac_f32_e32 v21, v139, v167
	v_fmac_f32_e32 v18, v143, v167
	v_fmac_f32_e32 v19, v147, v167
	v_fmac_f32_e32 v16, v151, v167
	v_fmac_f32_e32 v17, v155, v167
	v_fmac_f32_e32 v12, v159, v167
	v_fmac_f32_e32 v13, v163, v167
	global_load_dwordx4 v[100:103], v[168:169], off offset:-4016
	global_load_dwordx4 v[104:107], v[168:169], off offset:80
	global_load_dwordx4 v[108:111], v[170:171], off offset:-4016
	global_load_dwordx4 v[112:115], v[170:171], off offset:80
	global_load_dwordx4 v[116:119], v[172:173], off offset:-4016
	global_load_dwordx4 v[120:123], v[172:173], off offset:80
	global_load_dwordx4 v[124:127], v[174:175], off offset:-4016
	global_load_dwordx4 v[128:131], v[174:175], off offset:80
	global_load_dwordx4 v[132:135], v[176:177], off offset:-4016
	global_load_dwordx4 v[136:139], v[176:177], off offset:80
	global_load_dwordx4 v[140:143], v[178:179], off offset:-4016
	global_load_dwordx4 v[144:147], v[178:179], off offset:80
	global_load_dwordx4 v[148:151], v[180:181], off offset:-4016
	global_load_dwordx4 v[152:155], v[180:181], off offset:80
	global_load_dwordx4 v[156:159], v[182:183], off offset:-4016
	global_load_dwordx4 v[160:163], v[182:183], off offset:80
	global_load_dword v164, v[184:185], off offset:-512
	global_load_dword v165, v[184:185], off
	global_load_dword v166, v[184:185], off offset:512
	global_load_dword v167, v[184:185], off offset:1024
	v_lshl_add_u64 v[184:185], v[184:185], 0, s[4:5]
	s_waitcnt vmcnt(20)
	v_fmac_f32_e32 v28, v32, v96
	v_fmac_f32_e32 v29, v36, v96
	v_fmac_f32_e32 v26, v40, v96
	v_fmac_f32_e32 v27, v44, v96
	v_fmac_f32_e32 v24, v48, v96
	v_fmac_f32_e32 v25, v52, v96
	v_fmac_f32_e32 v22, v56, v96
	v_fmac_f32_e32 v23, v60, v96
	v_fmac_f32_e32 v20, v64, v96
	v_fmac_f32_e32 v21, v68, v96
	v_fmac_f32_e32 v18, v72, v96
	v_fmac_f32_e32 v19, v76, v96
	v_fmac_f32_e32 v16, v80, v96
	v_fmac_f32_e32 v17, v84, v96
	v_fmac_f32_e32 v12, v88, v96
	v_fmac_f32_e32 v13, v92, v96
	v_fmac_f32_e32 v28, v33, v97
	v_fmac_f32_e32 v29, v37, v97
	v_fmac_f32_e32 v26, v41, v97
	v_fmac_f32_e32 v27, v45, v97
	v_fmac_f32_e32 v24, v49, v97
	v_fmac_f32_e32 v25, v53, v97
	v_fmac_f32_e32 v22, v57, v97
	v_fmac_f32_e32 v23, v61, v97
	v_fmac_f32_e32 v20, v65, v97
	v_fmac_f32_e32 v21, v69, v97
	v_fmac_f32_e32 v18, v73, v97
	v_fmac_f32_e32 v19, v77, v97
	v_fmac_f32_e32 v16, v81, v97
	v_fmac_f32_e32 v17, v85, v97
	v_fmac_f32_e32 v12, v89, v97
	v_fmac_f32_e32 v13, v93, v97
	v_fmac_f32_e32 v28, v34, v98
	v_fmac_f32_e32 v29, v38, v98
	v_fmac_f32_e32 v26, v42, v98
	v_fmac_f32_e32 v27, v46, v98
	v_fmac_f32_e32 v24, v50, v98
	v_fmac_f32_e32 v25, v54, v98
	v_fmac_f32_e32 v22, v58, v98
	v_fmac_f32_e32 v23, v62, v98
	v_fmac_f32_e32 v20, v66, v98
	v_fmac_f32_e32 v21, v70, v98
	v_fmac_f32_e32 v18, v74, v98
	v_fmac_f32_e32 v19, v78, v98
	v_fmac_f32_e32 v16, v82, v98
	v_fmac_f32_e32 v17, v86, v98
	v_fmac_f32_e32 v12, v90, v98
	v_fmac_f32_e32 v13, v94, v98
	v_fmac_f32_e32 v28, v35, v99
	v_fmac_f32_e32 v29, v39, v99
	v_fmac_f32_e32 v26, v43, v99
	v_fmac_f32_e32 v27, v47, v99
	v_fmac_f32_e32 v24, v51, v99
	v_fmac_f32_e32 v25, v55, v99
	v_fmac_f32_e32 v22, v59, v99
	v_fmac_f32_e32 v23, v63, v99
	v_fmac_f32_e32 v20, v67, v99
	v_fmac_f32_e32 v21, v71, v99
	v_fmac_f32_e32 v18, v75, v99
	v_fmac_f32_e32 v19, v79, v99
	v_fmac_f32_e32 v16, v83, v99
	v_fmac_f32_e32 v17, v87, v99
	v_fmac_f32_e32 v12, v91, v99
	v_fmac_f32_e32 v13, v95, v99
	global_load_dwordx4 v[32:35], v[168:169], off offset:-4000
	global_load_dwordx4 v[36:39], v[168:169], off offset:96
	global_load_dwordx4 v[40:43], v[170:171], off offset:-4000
	global_load_dwordx4 v[44:47], v[170:171], off offset:96
	global_load_dwordx4 v[48:51], v[172:173], off offset:-4000
	global_load_dwordx4 v[52:55], v[172:173], off offset:96
	global_load_dwordx4 v[56:59], v[174:175], off offset:-4000
	global_load_dwordx4 v[60:63], v[174:175], off offset:96
	global_load_dwordx4 v[64:67], v[176:177], off offset:-4000
	global_load_dwordx4 v[68:71], v[176:177], off offset:96
	global_load_dwordx4 v[72:75], v[178:179], off offset:-4000
	global_load_dwordx4 v[76:79], v[178:179], off offset:96
	global_load_dwordx4 v[80:83], v[180:181], off offset:-4000
	global_load_dwordx4 v[84:87], v[180:181], off offset:96
	global_load_dwordx4 v[88:91], v[182:183], off offset:-4000
	global_load_dwordx4 v[92:95], v[182:183], off offset:96
	global_load_dword v96, v[184:185], off offset:-512
	global_load_dword v97, v[184:185], off
	global_load_dword v98, v[184:185], off offset:512
	global_load_dword v99, v[184:185], off offset:1024
	v_lshl_add_u64 v[184:185], v[184:185], 0, s[4:5]
	s_waitcnt vmcnt(20)
; __device__ __forceinline__ void prep_phase(const Params& p, unsigned char* smem) {
;     ...
;     for (size_t it = gtid; it < (size_t)2 * 16 * 2048; it += nth) {
;         const int j = (int)(it >> 15), rem = (int)(it & 32767), qg = rem >> 11, n = rem & 2047, h = n >> 7, c = n & 127;
;         const float* uq = p.in[25] + (size_t)j * 256 * 1024 + (size_t)(qg * 16) * 1024 + h * 64;
;         const float* uk = p.in[26] + (size_t)j * 16 * 64 * 128 + (size_t)h * 64 * 128 + c;
;         float acc[16];
; #pragma unroll
;         for (int i = 0; i < 16; ++i) acc[i] = 0.f;
;         for (int d = 0; d < 64; ++d) {
;             const float kv = uk[d * 128];
; #pragma unroll
;             for (int i = 0; i < 16; ++i) acc[i] += uq[i * 1024 + d] * kv;
;         }
	v_fmac_f32_e32 v28, v100, v164
	v_fmac_f32_e32 v29, v104, v164
	v_fmac_f32_e32 v26, v108, v164
	v_fmac_f32_e32 v27, v112, v164
	v_fmac_f32_e32 v24, v116, v164
	v_fmac_f32_e32 v25, v120, v164
	v_fmac_f32_e32 v22, v124, v164
	v_fmac_f32_e32 v23, v128, v164
	v_fmac_f32_e32 v20, v132, v164
	v_fmac_f32_e32 v21, v136, v164
	v_fmac_f32_e32 v18, v140, v164
	v_fmac_f32_e32 v19, v144, v164
	v_fmac_f32_e32 v16, v148, v164
	v_fmac_f32_e32 v17, v152, v164
	v_fmac_f32_e32 v12, v156, v164
	v_fmac_f32_e32 v13, v160, v164
	v_fmac_f32_e32 v28, v101, v165
	v_fmac_f32_e32 v29, v105, v165
	v_fmac_f32_e32 v26, v109, v165
	v_fmac_f32_e32 v27, v113, v165
	v_fmac_f32_e32 v24, v117, v165
	v_fmac_f32_e32 v25, v121, v165
	v_fmac_f32_e32 v22, v125, v165
	v_fmac_f32_e32 v23, v129, v165
	v_fmac_f32_e32 v20, v133, v165
	v_fmac_f32_e32 v21, v137, v165
	v_fmac_f32_e32 v18, v141, v165
	v_fmac_f32_e32 v19, v145, v165
	v_fmac_f32_e32 v16, v149, v165
	v_fmac_f32_e32 v17, v153, v165
	v_fmac_f32_e32 v12, v157, v165
	v_fmac_f32_e32 v13, v161, v165
	v_fmac_f32_e32 v28, v102, v166
	v_fmac_f32_e32 v29, v106, v166
	v_fmac_f32_e32 v26, v110, v166
	v_fmac_f32_e32 v27, v114, v166
	v_fmac_f32_e32 v24, v118, v166
	v_fmac_f32_e32 v25, v122, v166
	v_fmac_f32_e32 v22, v126, v166
	v_fmac_f32_e32 v23, v130, v166
	v_fmac_f32_e32 v20, v134, v166
	v_fmac_f32_e32 v21, v138, v166
	v_fmac_f32_e32 v18, v142, v166
	v_fmac_f32_e32 v19, v146, v166
	v_fmac_f32_e32 v16, v150, v166
	v_fmac_f32_e32 v17, v154, v166
	v_fmac_f32_e32 v12, v158, v166
	v_fmac_f32_e32 v13, v162, v166
	v_fmac_f32_e32 v28, v103, v167
	v_fmac_f32_e32 v29, v107, v167
	v_fmac_f32_e32 v26, v111, v167
	v_fmac_f32_e32 v27, v115, v167
	v_fmac_f32_e32 v24, v119, v167
	v_fmac_f32_e32 v25, v123, v167
	v_fmac_f32_e32 v22, v127, v167
	v_fmac_f32_e32 v23, v131, v167
	v_fmac_f32_e32 v20, v135, v167
	v_fmac_f32_e32 v21, v139, v167
	v_fmac_f32_e32 v18, v143, v167
	v_fmac_f32_e32 v19, v147, v167
	v_fmac_f32_e32 v16, v151, v167
	v_fmac_f32_e32 v17, v155, v167
	v_fmac_f32_e32 v12, v159, v167
	v_fmac_f32_e32 v13, v163, v167
	global_load_dwordx4 v[100:103], v[168:169], off offset:-3984
	global_load_dwordx4 v[104:107], v[168:169], off offset:112
	global_load_dwordx4 v[108:111], v[170:171], off offset:-3984
	global_load_dwordx4 v[112:115], v[170:171], off offset:112
	global_load_dwordx4 v[116:119], v[172:173], off offset:-3984
	global_load_dwordx4 v[120:123], v[172:173], off offset:112
	global_load_dwordx4 v[124:127], v[174:175], off offset:-3984
	global_load_dwordx4 v[128:131], v[174:175], off offset:112
	global_load_dwordx4 v[132:135], v[176:177], off offset:-3984
	global_load_dwordx4 v[136:139], v[176:177], off offset:112
	global_load_dwordx4 v[140:143], v[178:179], off offset:-3984
	global_load_dwordx4 v[144:147], v[178:179], off offset:112
	global_load_dwordx4 v[148:151], v[180:181], off offset:-3984
	global_load_dwordx4 v[152:155], v[180:181], off offset:112
	global_load_dwordx4 v[156:159], v[182:183], off offset:-3984
	global_load_dwordx4 v[160:163], v[182:183], off offset:112
	global_load_dword v164, v[184:185], off offset:-512
	global_load_dword v165, v[184:185], off
	global_load_dword v166, v[184:185], off offset:512
	global_load_dword v167, v[184:185], off offset:1024
	v_lshl_add_u64 v[184:185], v[184:185], 0, s[4:5]
	s_waitcnt vmcnt(20)
	v_fmac_f32_e32 v28, v32, v96
	v_fmac_f32_e32 v29, v36, v96
	v_fmac_f32_e32 v26, v40, v96
	v_fmac_f32_e32 v27, v44, v96
	v_fmac_f32_e32 v24, v48, v96
	v_fmac_f32_e32 v25, v52, v96
	v_fmac_f32_e32 v22, v56, v96
	v_fmac_f32_e32 v23, v60, v96
	v_fmac_f32_e32 v20, v64, v96
	v_fmac_f32_e32 v21, v68, v96
	v_fmac_f32_e32 v18, v72, v96
	v_fmac_f32_e32 v19, v76, v96
	v_fmac_f32_e32 v16, v80, v96
	v_fmac_f32_e32 v17, v84, v96
	v_fmac_f32_e32 v12, v88, v96
	v_fmac_f32_e32 v13, v92, v96
	v_fmac_f32_e32 v28, v33, v97
	v_fmac_f32_e32 v29, v37, v97
	v_fmac_f32_e32 v26, v41, v97
	v_fmac_f32_e32 v27, v45, v97
	v_fmac_f32_e32 v24, v49, v97
	v_fmac_f32_e32 v25, v53, v97
	v_fmac_f32_e32 v22, v57, v97
	v_fmac_f32_e32 v23, v61, v97
	v_fmac_f32_e32 v20, v65, v97
	v_fmac_f32_e32 v21, v69, v97
	v_fmac_f32_e32 v18, v73, v97
	v_fmac_f32_e32 v19, v77, v97
	v_fmac_f32_e32 v16, v81, v97
	v_fmac_f32_e32 v17, v85, v97
	v_fmac_f32_e32 v12, v89, v97
	v_fmac_f32_e32 v13, v93, v97
	v_fmac_f32_e32 v28, v34, v98
	v_fmac_f32_e32 v29, v38, v98
	v_fmac_f32_e32 v26, v42, v98
	v_fmac_f32_e32 v27, v46, v98
	v_fmac_f32_e32 v24, v50, v98
	v_fmac_f32_e32 v25, v54, v98
	v_fmac_f32_e32 v22, v58, v98
	v_fmac_f32_e32 v23, v62, v98
	v_fmac_f32_e32 v20, v66, v98
	v_fmac_f32_e32 v21, v70, v98
	v_fmac_f32_e32 v18, v74, v98
	v_fmac_f32_e32 v19, v78, v98
	v_fmac_f32_e32 v16, v82, v98
	v_fmac_f32_e32 v17, v86, v98
	v_fmac_f32_e32 v12, v90, v98
	v_fmac_f32_e32 v13, v94, v98
	v_fmac_f32_e32 v28, v35, v99
	v_fmac_f32_e32 v29, v39, v99
	v_fmac_f32_e32 v26, v43, v99
	v_fmac_f32_e32 v27, v47, v99
	v_fmac_f32_e32 v24, v51, v99
	v_fmac_f32_e32 v25, v55, v99
	v_fmac_f32_e32 v22, v59, v99
	v_fmac_f32_e32 v23, v63, v99
	v_fmac_f32_e32 v20, v67, v99
	v_fmac_f32_e32 v21, v71, v99
	v_fmac_f32_e32 v18, v75, v99
	v_fmac_f32_e32 v19, v79, v99
	v_fmac_f32_e32 v16, v83, v99
	v_fmac_f32_e32 v17, v87, v99
	v_fmac_f32_e32 v12, v91, v99
	v_fmac_f32_e32 v13, v95, v99
	global_load_dwordx4 v[32:35], v[168:169], off offset:-3968
	global_load_dwordx4 v[36:39], v[168:169], off offset:128
	global_load_dwordx4 v[40:43], v[170:171], off offset:-3968
	global_load_dwordx4 v[44:47], v[170:171], off offset:128
	global_load_dwordx4 v[48:51], v[172:173], off offset:-3968
	global_load_dwordx4 v[52:55], v[172:173], off offset:128
	global_load_dwordx4 v[56:59], v[174:175], off offset:-3968
	global_load_dwordx4 v[60:63], v[174:175], off offset:128
	global_load_dwordx4 v[64:67], v[176:177], off offset:-3968
	global_load_dwordx4 v[68:71], v[176:177], off offset:128
	global_load_dwordx4 v[72:75], v[178:179], off offset:-3968
	global_load_dwordx4 v[76:79], v[178:179], off offset:128
	global_load_dwordx4 v[80:83], v[180:181], off offset:-3968
	global_load_dwordx4 v[84:87], v[180:181], off offset:128
	global_load_dwordx4 v[88:91], v[182:183], off offset:-3968
	global_load_dwordx4 v[92:95], v[182:183], off offset:128
	global_load_dword v96, v[184:185], off offset:-512
	global_load_dword v97, v[184:185], off
	global_load_dword v98, v[184:185], off offset:512
	global_load_dword v99, v[184:185], off offset:1024
	v_lshl_add_u64 v[184:185], v[184:185], 0, s[4:5]
	s_waitcnt vmcnt(20)
; __device__ __forceinline__ void prep_phase(const Params& p, unsigned char* smem) {
;     ...
;     for (size_t it = gtid; it < (size_t)2 * 16 * 2048; it += nth) {
;         const int j = (int)(it >> 15), rem = (int)(it & 32767), qg = rem >> 11, n = rem & 2047, h = n >> 7, c = n & 127;
;         const float* uq = p.in[25] + (size_t)j * 256 * 1024 + (size_t)(qg * 16) * 1024 + h * 64;
;         const float* uk = p.in[26] + (size_t)j * 16 * 64 * 128 + (size_t)h * 64 * 128 + c;
;         float acc[16];
; #pragma unroll
;         for (int i = 0; i < 16; ++i) acc[i] = 0.f;
;         for (int d = 0; d < 64; ++d) {
;             const float kv = uk[d * 128];
; #pragma unroll
;             for (int i = 0; i < 16; ++i) acc[i] += uq[i * 1024 + d] * kv;
;         }
	v_fmac_f32_e32 v28, v100, v164
	v_fmac_f32_e32 v29, v104, v164
	v_fmac_f32_e32 v26, v108, v164
	v_fmac_f32_e32 v27, v112, v164
	v_fmac_f32_e32 v24, v116, v164
	v_fmac_f32_e32 v25, v120, v164
	v_fmac_f32_e32 v22, v124, v164
	v_fmac_f32_e32 v23, v128, v164
	v_fmac_f32_e32 v20, v132, v164
	v_fmac_f32_e32 v21, v136, v164
	v_fmac_f32_e32 v18, v140, v164
	v_fmac_f32_e32 v19, v144, v164
	v_fmac_f32_e32 v16, v148, v164
	v_fmac_f32_e32 v17, v152, v164
	v_fmac_f32_e32 v12, v156, v164
	v_fmac_f32_e32 v13, v160, v164
	v_fmac_f32_e32 v28, v101, v165
	v_fmac_f32_e32 v29, v105, v165
	v_fmac_f32_e32 v26, v109, v165
	v_fmac_f32_e32 v27, v113, v165
	v_fmac_f32_e32 v24, v117, v165
	v_fmac_f32_e32 v25, v121, v165
	v_fmac_f32_e32 v22, v125, v165
	v_fmac_f32_e32 v23, v129, v165
	v_fmac_f32_e32 v20, v133, v165
	v_fmac_f32_e32 v21, v137, v165
	v_fmac_f32_e32 v18, v141, v165
	v_fmac_f32_e32 v19, v145, v165
	v_fmac_f32_e32 v16, v149, v165
	v_fmac_f32_e32 v17, v153, v165
	v_fmac_f32_e32 v12, v157, v165
	v_fmac_f32_e32 v13, v161, v165
	v_fmac_f32_e32 v28, v102, v166
	v_fmac_f32_e32 v29, v106, v166
	v_fmac_f32_e32 v26, v110, v166
	v_fmac_f32_e32 v27, v114, v166
	v_fmac_f32_e32 v24, v118, v166
	v_fmac_f32_e32 v25, v122, v166
	v_fmac_f32_e32 v22, v126, v166
	v_fmac_f32_e32 v23, v130, v166
	v_fmac_f32_e32 v20, v134, v166
	v_fmac_f32_e32 v21, v138, v166
	v_fmac_f32_e32 v18, v142, v166
	v_fmac_f32_e32 v19, v146, v166
	v_fmac_f32_e32 v16, v150, v166
	v_fmac_f32_e32 v17, v154, v166
	v_fmac_f32_e32 v12, v158, v166
	v_fmac_f32_e32 v13, v162, v166
	v_fmac_f32_e32 v28, v103, v167
	v_fmac_f32_e32 v29, v107, v167
	v_fmac_f32_e32 v26, v111, v167
	v_fmac_f32_e32 v27, v115, v167
	v_fmac_f32_e32 v24, v119, v167
	v_fmac_f32_e32 v25, v123, v167
	v_fmac_f32_e32 v22, v127, v167
	v_fmac_f32_e32 v23, v131, v167
	v_fmac_f32_e32 v20, v135, v167
	v_fmac_f32_e32 v21, v139, v167
	v_fmac_f32_e32 v18, v143, v167
	v_fmac_f32_e32 v19, v147, v167
	v_fmac_f32_e32 v16, v151, v167
	v_fmac_f32_e32 v17, v155, v167
	v_fmac_f32_e32 v12, v159, v167
	v_fmac_f32_e32 v13, v163, v167
	global_load_dwordx4 v[100:103], v[168:169], off offset:-3952
	global_load_dwordx4 v[104:107], v[168:169], off offset:144
	global_load_dwordx4 v[108:111], v[170:171], off offset:-3952
	global_load_dwordx4 v[112:115], v[170:171], off offset:144
	global_load_dwordx4 v[116:119], v[172:173], off offset:-3952
	global_load_dwordx4 v[120:123], v[172:173], off offset:144
	global_load_dwordx4 v[124:127], v[174:175], off offset:-3952
	global_load_dwordx4 v[128:131], v[174:175], off offset:144
	global_load_dwordx4 v[132:135], v[176:177], off offset:-3952
	global_load_dwordx4 v[136:139], v[176:177], off offset:144
	global_load_dwordx4 v[140:143], v[178:179], off offset:-3952
	global_load_dwordx4 v[144:147], v[178:179], off offset:144
	global_load_dwordx4 v[148:151], v[180:181], off offset:-3952
	global_load_dwordx4 v[152:155], v[180:181], off offset:144
	global_load_dwordx4 v[156:159], v[182:183], off offset:-3952
	global_load_dwordx4 v[160:163], v[182:183], off offset:144
	global_load_dword v164, v[184:185], off offset:-512
	global_load_dword v165, v[184:185], off
	global_load_dword v166, v[184:185], off offset:512
	global_load_dword v167, v[184:185], off offset:1024
	v_lshl_add_u64 v[184:185], v[184:185], 0, s[4:5]
	s_waitcnt vmcnt(20)
	v_fmac_f32_e32 v28, v32, v96
	v_fmac_f32_e32 v29, v36, v96
	v_fmac_f32_e32 v26, v40, v96
	v_fmac_f32_e32 v27, v44, v96
	v_fmac_f32_e32 v24, v48, v96
	v_fmac_f32_e32 v25, v52, v96
	v_fmac_f32_e32 v22, v56, v96
	v_fmac_f32_e32 v23, v60, v96
	v_fmac_f32_e32 v20, v64, v96
	v_fmac_f32_e32 v21, v68, v96
	v_fmac_f32_e32 v18, v72, v96
	v_fmac_f32_e32 v19, v76, v96
	v_fmac_f32_e32 v16, v80, v96
	v_fmac_f32_e32 v17, v84, v96
	v_fmac_f32_e32 v12, v88, v96
	v_fmac_f32_e32 v13, v92, v96
	v_fmac_f32_e32 v28, v33, v97
	v_fmac_f32_e32 v29, v37, v97
	v_fmac_f32_e32 v26, v41, v97
	v_fmac_f32_e32 v27, v45, v97
	v_fmac_f32_e32 v24, v49, v97
	v_fmac_f32_e32 v25, v53, v97
	v_fmac_f32_e32 v22, v57, v97
	v_fmac_f32_e32 v23, v61, v97
	v_fmac_f32_e32 v20, v65, v97
	v_fmac_f32_e32 v21, v69, v97
	v_fmac_f32_e32 v18, v73, v97
	v_fmac_f32_e32 v19, v77, v97
	v_fmac_f32_e32 v16, v81, v97
	v_fmac_f32_e32 v17, v85, v97
	v_fmac_f32_e32 v12, v89, v97
	v_fmac_f32_e32 v13, v93, v97
	v_fmac_f32_e32 v28, v34, v98
	v_fmac_f32_e32 v29, v38, v98
	v_fmac_f32_e32 v26, v42, v98
	v_fmac_f32_e32 v27, v46, v98
	v_fmac_f32_e32 v24, v50, v98
	v_fmac_f32_e32 v25, v54, v98
	v_fmac_f32_e32 v22, v58, v98
	v_fmac_f32_e32 v23, v62, v98
	v_fmac_f32_e32 v20, v66, v98
	v_fmac_f32_e32 v21, v70, v98
	v_fmac_f32_e32 v18, v74, v98
	v_fmac_f32_e32 v19, v78, v98
	v_fmac_f32_e32 v16, v82, v98
	v_fmac_f32_e32 v17, v86, v98
	v_fmac_f32_e32 v12, v90, v98
	v_fmac_f32_e32 v13, v94, v98
	v_fmac_f32_e32 v28, v35, v99
	v_fmac_f32_e32 v29, v39, v99
	v_fmac_f32_e32 v26, v43, v99
	v_fmac_f32_e32 v27, v47, v99
	v_fmac_f32_e32 v24, v51, v99
	v_fmac_f32_e32 v25, v55, v99
	v_fmac_f32_e32 v22, v59, v99
	v_fmac_f32_e32 v23, v63, v99
	v_fmac_f32_e32 v20, v67, v99
	v_fmac_f32_e32 v21, v71, v99
	v_fmac_f32_e32 v18, v75, v99
	v_fmac_f32_e32 v19, v79, v99
	v_fmac_f32_e32 v16, v83, v99
	v_fmac_f32_e32 v17, v87, v99
	v_fmac_f32_e32 v12, v91, v99
	v_fmac_f32_e32 v13, v95, v99
	global_load_dwordx4 v[32:35], v[168:169], off offset:-3936
	global_load_dwordx4 v[36:39], v[168:169], off offset:160
	global_load_dwordx4 v[40:43], v[170:171], off offset:-3936
	global_load_dwordx4 v[44:47], v[170:171], off offset:160
	global_load_dwordx4 v[48:51], v[172:173], off offset:-3936
	global_load_dwordx4 v[52:55], v[172:173], off offset:160
	global_load_dwordx4 v[56:59], v[174:175], off offset:-3936
	global_load_dwordx4 v[60:63], v[174:175], off offset:160
	global_load_dwordx4 v[64:67], v[176:177], off offset:-3936
	global_load_dwordx4 v[68:71], v[176:177], off offset:160
	global_load_dwordx4 v[72:75], v[178:179], off offset:-3936
	global_load_dwordx4 v[76:79], v[178:179], off offset:160
	global_load_dwordx4 v[80:83], v[180:181], off offset:-3936
	global_load_dwordx4 v[84:87], v[180:181], off offset:160
	global_load_dwordx4 v[88:91], v[182:183], off offset:-3936
	global_load_dwordx4 v[92:95], v[182:183], off offset:160
	global_load_dword v96, v[184:185], off offset:-512
	global_load_dword v97, v[184:185], off
	global_load_dword v98, v[184:185], off offset:512
	global_load_dword v99, v[184:185], off offset:1024
	v_lshl_add_u64 v[184:185], v[184:185], 0, s[4:5]
	s_waitcnt vmcnt(20)
; __device__ __forceinline__ void prep_phase(const Params& p, unsigned char* smem) {
;     ...
;     for (size_t it = gtid; it < (size_t)2 * 16 * 2048; it += nth) {
;         const int j = (int)(it >> 15), rem = (int)(it & 32767), qg = rem >> 11, n = rem & 2047, h = n >> 7, c = n & 127;
;         const float* uq = p.in[25] + (size_t)j * 256 * 1024 + (size_t)(qg * 16) * 1024 + h * 64;
;         const float* uk = p.in[26] + (size_t)j * 16 * 64 * 128 + (size_t)h * 64 * 128 + c;
;         float acc[16];
; #pragma unroll
;         for (int i = 0; i < 16; ++i) acc[i] = 0.f;
;         for (int d = 0; d < 64; ++d) {
;             const float kv = uk[d * 128];
; #pragma unroll
;             for (int i = 0; i < 16; ++i) acc[i] += uq[i * 1024 + d] * kv;
;         }
	v_fmac_f32_e32 v28, v100, v164
	v_fmac_f32_e32 v29, v104, v164
	v_fmac_f32_e32 v26, v108, v164
	v_fmac_f32_e32 v27, v112, v164
	v_fmac_f32_e32 v24, v116, v164
	v_fmac_f32_e32 v25, v120, v164
	v_fmac_f32_e32 v22, v124, v164
	v_fmac_f32_e32 v23, v128, v164
	v_fmac_f32_e32 v20, v132, v164
	v_fmac_f32_e32 v21, v136, v164
	v_fmac_f32_e32 v18, v140, v164
	v_fmac_f32_e32 v19, v144, v164
	v_fmac_f32_e32 v16, v148, v164
	v_fmac_f32_e32 v17, v152, v164
	v_fmac_f32_e32 v12, v156, v164
	v_fmac_f32_e32 v13, v160, v164
	v_fmac_f32_e32 v28, v101, v165
	v_fmac_f32_e32 v29, v105, v165
	v_fmac_f32_e32 v26, v109, v165
	v_fmac_f32_e32 v27, v113, v165
	v_fmac_f32_e32 v24, v117, v165
	v_fmac_f32_e32 v25, v121, v165
	v_fmac_f32_e32 v22, v125, v165
	v_fmac_f32_e32 v23, v129, v165
	v_fmac_f32_e32 v20, v133, v165
	v_fmac_f32_e32 v21, v137, v165
	v_fmac_f32_e32 v18, v141, v165
	v_fmac_f32_e32 v19, v145, v165
	v_fmac_f32_e32 v16, v149, v165
	v_fmac_f32_e32 v17, v153, v165
	v_fmac_f32_e32 v12, v157, v165
	v_fmac_f32_e32 v13, v161, v165
	v_fmac_f32_e32 v28, v102, v166
	v_fmac_f32_e32 v29, v106, v166
	v_fmac_f32_e32 v26, v110, v166
	v_fmac_f32_e32 v27, v114, v166
	v_fmac_f32_e32 v24, v118, v166
	v_fmac_f32_e32 v25, v122, v166
	v_fmac_f32_e32 v22, v126, v166
	v_fmac_f32_e32 v23, v130, v166
	v_fmac_f32_e32 v20, v134, v166
	v_fmac_f32_e32 v21, v138, v166
	v_fmac_f32_e32 v18, v142, v166
	v_fmac_f32_e32 v19, v146, v166
	v_fmac_f32_e32 v16, v150, v166
	v_fmac_f32_e32 v17, v154, v166
	v_fmac_f32_e32 v12, v158, v166
	v_fmac_f32_e32 v13, v162, v166
	v_fmac_f32_e32 v28, v103, v167
	v_fmac_f32_e32 v29, v107, v167
	v_fmac_f32_e32 v26, v111, v167
	v_fmac_f32_e32 v27, v115, v167
	v_fmac_f32_e32 v24, v119, v167
	v_fmac_f32_e32 v25, v123, v167
	v_fmac_f32_e32 v22, v127, v167
	v_fmac_f32_e32 v23, v131, v167
	v_fmac_f32_e32 v20, v135, v167
	v_fmac_f32_e32 v21, v139, v167
	v_fmac_f32_e32 v18, v143, v167
	v_fmac_f32_e32 v19, v147, v167
	v_fmac_f32_e32 v16, v151, v167
	v_fmac_f32_e32 v17, v155, v167
	v_fmac_f32_e32 v12, v159, v167
	v_fmac_f32_e32 v13, v163, v167
	global_load_dwordx4 v[100:103], v[168:169], off offset:-3920
	global_load_dwordx4 v[104:107], v[168:169], off offset:176
	global_load_dwordx4 v[108:111], v[170:171], off offset:-3920
	global_load_dwordx4 v[112:115], v[170:171], off offset:176
	global_load_dwordx4 v[116:119], v[172:173], off offset:-3920
	global_load_dwordx4 v[120:123], v[172:173], off offset:176
	global_load_dwordx4 v[124:127], v[174:175], off offset:-3920
	global_load_dwordx4 v[128:131], v[174:175], off offset:176
	global_load_dwordx4 v[132:135], v[176:177], off offset:-3920
	global_load_dwordx4 v[136:139], v[176:177], off offset:176
	global_load_dwordx4 v[140:143], v[178:179], off offset:-3920
	global_load_dwordx4 v[144:147], v[178:179], off offset:176
	global_load_dwordx4 v[148:151], v[180:181], off offset:-3920
	global_load_dwordx4 v[152:155], v[180:181], off offset:176
	global_load_dwordx4 v[156:159], v[182:183], off offset:-3920
	global_load_dwordx4 v[160:163], v[182:183], off offset:176
	global_load_dword v164, v[184:185], off offset:-512
	global_load_dword v165, v[184:185], off
	global_load_dword v166, v[184:185], off offset:512
	global_load_dword v167, v[184:185], off offset:1024
	v_lshl_add_u64 v[184:185], v[184:185], 0, s[4:5]
	s_waitcnt vmcnt(20)
	v_fmac_f32_e32 v28, v32, v96
	v_fmac_f32_e32 v29, v36, v96
	v_fmac_f32_e32 v26, v40, v96
	v_fmac_f32_e32 v27, v44, v96
	v_fmac_f32_e32 v24, v48, v96
	v_fmac_f32_e32 v25, v52, v96
	v_fmac_f32_e32 v22, v56, v96
	v_fmac_f32_e32 v23, v60, v96
	v_fmac_f32_e32 v20, v64, v96
	v_fmac_f32_e32 v21, v68, v96
	v_fmac_f32_e32 v18, v72, v96
	v_fmac_f32_e32 v19, v76, v96
	v_fmac_f32_e32 v16, v80, v96
	v_fmac_f32_e32 v17, v84, v96
	v_fmac_f32_e32 v12, v88, v96
	v_fmac_f32_e32 v13, v92, v96
	v_fmac_f32_e32 v28, v33, v97
	v_fmac_f32_e32 v29, v37, v97
	v_fmac_f32_e32 v26, v41, v97
	v_fmac_f32_e32 v27, v45, v97
	v_fmac_f32_e32 v24, v49, v97
	v_fmac_f32_e32 v25, v53, v97
	v_fmac_f32_e32 v22, v57, v97
	v_fmac_f32_e32 v23, v61, v97
	v_fmac_f32_e32 v20, v65, v97
	v_fmac_f32_e32 v21, v69, v97
	v_fmac_f32_e32 v18, v73, v97
	v_fmac_f32_e32 v19, v77, v97
	v_fmac_f32_e32 v16, v81, v97
	v_fmac_f32_e32 v17, v85, v97
	v_fmac_f32_e32 v12, v89, v97
	v_fmac_f32_e32 v13, v93, v97
	v_fmac_f32_e32 v28, v34, v98
	v_fmac_f32_e32 v29, v38, v98
	v_fmac_f32_e32 v26, v42, v98
	v_fmac_f32_e32 v27, v46, v98
	v_fmac_f32_e32 v24, v50, v98
	v_fmac_f32_e32 v25, v54, v98
	v_fmac_f32_e32 v22, v58, v98
	v_fmac_f32_e32 v23, v62, v98
	v_fmac_f32_e32 v20, v66, v98
	v_fmac_f32_e32 v21, v70, v98
	v_fmac_f32_e32 v18, v74, v98
	v_fmac_f32_e32 v19, v78, v98
	v_fmac_f32_e32 v16, v82, v98
	v_fmac_f32_e32 v17, v86, v98
	v_fmac_f32_e32 v12, v90, v98
	v_fmac_f32_e32 v13, v94, v98
	v_fmac_f32_e32 v28, v35, v99
	v_fmac_f32_e32 v29, v39, v99
	v_fmac_f32_e32 v26, v43, v99
	v_fmac_f32_e32 v27, v47, v99
	v_fmac_f32_e32 v24, v51, v99
	v_fmac_f32_e32 v25, v55, v99
	v_fmac_f32_e32 v22, v59, v99
	v_fmac_f32_e32 v23, v63, v99
	v_fmac_f32_e32 v20, v67, v99
	v_fmac_f32_e32 v21, v71, v99
	v_fmac_f32_e32 v18, v75, v99
	v_fmac_f32_e32 v19, v79, v99
	v_fmac_f32_e32 v16, v83, v99
	v_fmac_f32_e32 v17, v87, v99
	v_fmac_f32_e32 v12, v91, v99
	v_fmac_f32_e32 v13, v95, v99
	global_load_dwordx4 v[32:35], v[168:169], off offset:-3904
	global_load_dwordx4 v[36:39], v[168:169], off offset:192
	global_load_dwordx4 v[40:43], v[170:171], off offset:-3904
	global_load_dwordx4 v[44:47], v[170:171], off offset:192
	global_load_dwordx4 v[48:51], v[172:173], off offset:-3904
	global_load_dwordx4 v[52:55], v[172:173], off offset:192
	global_load_dwordx4 v[56:59], v[174:175], off offset:-3904
	global_load_dwordx4 v[60:63], v[174:175], off offset:192
	global_load_dwordx4 v[64:67], v[176:177], off offset:-3904
	global_load_dwordx4 v[68:71], v[176:177], off offset:192
	global_load_dwordx4 v[72:75], v[178:179], off offset:-3904
	global_load_dwordx4 v[76:79], v[178:179], off offset:192
	global_load_dwordx4 v[80:83], v[180:181], off offset:-3904
	global_load_dwordx4 v[84:87], v[180:181], off offset:192
	global_load_dwordx4 v[88:91], v[182:183], off offset:-3904
	global_load_dwordx4 v[92:95], v[182:183], off offset:192
	global_load_dword v96, v[184:185], off offset:-512
	global_load_dword v97, v[184:185], off
	global_load_dword v98, v[184:185], off offset:512
	global_load_dword v99, v[184:185], off offset:1024
	v_lshl_add_u64 v[184:185], v[184:185], 0, s[4:5]
	s_waitcnt vmcnt(20)
; __device__ __forceinline__ void prep_phase(const Params& p, unsigned char* smem) {
;     ...
;     for (size_t it = gtid; it < (size_t)2 * 16 * 2048; it += nth) {
;         const int j = (int)(it >> 15), rem = (int)(it & 32767), qg = rem >> 11, n = rem & 2047, h = n >> 7, c = n & 127;
;         const float* uq = p.in[25] + (size_t)j * 256 * 1024 + (size_t)(qg * 16) * 1024 + h * 64;
;         const float* uk = p.in[26] + (size_t)j * 16 * 64 * 128 + (size_t)h * 64 * 128 + c;
;         float acc[16];
; #pragma unroll
;         for (int i = 0; i < 16; ++i) acc[i] = 0.f;
;         for (int d = 0; d < 64; ++d) {
;             const float kv = uk[d * 128];
; #pragma unroll
;             for (int i = 0; i < 16; ++i) acc[i] += uq[i * 1024 + d] * kv;
;         }
	v_fmac_f32_e32 v28, v100, v164
	v_fmac_f32_e32 v29, v104, v164
	v_fmac_f32_e32 v26, v108, v164
	v_fmac_f32_e32 v27, v112, v164
	v_fmac_f32_e32 v24, v116, v164
	v_fmac_f32_e32 v25, v120, v164
	v_fmac_f32_e32 v22, v124, v164
	v_fmac_f32_e32 v23, v128, v164
	v_fmac_f32_e32 v20, v132, v164
	v_fmac_f32_e32 v21, v136, v164
	v_fmac_f32_e32 v18, v140, v164
	v_fmac_f32_e32 v19, v144, v164
	v_fmac_f32_e32 v16, v148, v164
	v_fmac_f32_e32 v17, v152, v164
	v_fmac_f32_e32 v12, v156, v164
	v_fmac_f32_e32 v13, v160, v164
	v_fmac_f32_e32 v28, v101, v165
	v_fmac_f32_e32 v29, v105, v165
	v_fmac_f32_e32 v26, v109, v165
	v_fmac_f32_e32 v27, v113, v165
	v_fmac_f32_e32 v24, v117, v165
	v_fmac_f32_e32 v25, v121, v165
	v_fmac_f32_e32 v22, v125, v165
	v_fmac_f32_e32 v23, v129, v165
	v_fmac_f32_e32 v20, v133, v165
	v_fmac_f32_e32 v21, v137, v165
	v_fmac_f32_e32 v18, v141, v165
	v_fmac_f32_e32 v19, v145, v165
	v_fmac_f32_e32 v16, v149, v165
	v_fmac_f32_e32 v17, v153, v165
	v_fmac_f32_e32 v12, v157, v165
	v_fmac_f32_e32 v13, v161, v165
	v_fmac_f32_e32 v28, v102, v166
	v_fmac_f32_e32 v29, v106, v166
	v_fmac_f32_e32 v26, v110, v166
	v_fmac_f32_e32 v27, v114, v166
	v_fmac_f32_e32 v24, v118, v166
	v_fmac_f32_e32 v25, v122, v166
	v_fmac_f32_e32 v22, v126, v166
	v_fmac_f32_e32 v23, v130, v166
	v_fmac_f32_e32 v20, v134, v166
	v_fmac_f32_e32 v21, v138, v166
	v_fmac_f32_e32 v18, v142, v166
	v_fmac_f32_e32 v19, v146, v166
	v_fmac_f32_e32 v16, v150, v166
	v_fmac_f32_e32 v17, v154, v166
	v_fmac_f32_e32 v12, v158, v166
	v_fmac_f32_e32 v13, v162, v166
	v_fmac_f32_e32 v28, v103, v167
	v_fmac_f32_e32 v29, v107, v167
	v_fmac_f32_e32 v26, v111, v167
	v_fmac_f32_e32 v27, v115, v167
	v_fmac_f32_e32 v24, v119, v167
	v_fmac_f32_e32 v25, v123, v167
	v_fmac_f32_e32 v22, v127, v167
	v_fmac_f32_e32 v23, v131, v167
	v_fmac_f32_e32 v20, v135, v167
	v_fmac_f32_e32 v21, v139, v167
	v_fmac_f32_e32 v18, v143, v167
	v_fmac_f32_e32 v19, v147, v167
	v_fmac_f32_e32 v16, v151, v167
	v_fmac_f32_e32 v17, v155, v167
	v_fmac_f32_e32 v12, v159, v167
	v_fmac_f32_e32 v13, v163, v167
	global_load_dwordx4 v[100:103], v[168:169], off offset:-3888
	global_load_dwordx4 v[104:107], v[168:169], off offset:208
	global_load_dwordx4 v[108:111], v[170:171], off offset:-3888
	global_load_dwordx4 v[112:115], v[170:171], off offset:208
	global_load_dwordx4 v[116:119], v[172:173], off offset:-3888
	global_load_dwordx4 v[120:123], v[172:173], off offset:208
	global_load_dwordx4 v[124:127], v[174:175], off offset:-3888
	global_load_dwordx4 v[128:131], v[174:175], off offset:208
	global_load_dwordx4 v[132:135], v[176:177], off offset:-3888
	global_load_dwordx4 v[136:139], v[176:177], off offset:208
	global_load_dwordx4 v[140:143], v[178:179], off offset:-3888
	global_load_dwordx4 v[144:147], v[178:179], off offset:208
	global_load_dwordx4 v[148:151], v[180:181], off offset:-3888
	global_load_dwordx4 v[152:155], v[180:181], off offset:208
	global_load_dwordx4 v[156:159], v[182:183], off offset:-3888
	global_load_dwordx4 v[160:163], v[182:183], off offset:208
	global_load_dword v164, v[184:185], off offset:-512
	global_load_dword v165, v[184:185], off
	global_load_dword v166, v[184:185], off offset:512
	global_load_dword v167, v[184:185], off offset:1024
	v_lshl_add_u64 v[184:185], v[184:185], 0, s[4:5]
	s_waitcnt vmcnt(20)
	v_fmac_f32_e32 v28, v32, v96
	v_fmac_f32_e32 v29, v36, v96
	v_fmac_f32_e32 v26, v40, v96
	v_fmac_f32_e32 v27, v44, v96
	v_fmac_f32_e32 v24, v48, v96
	v_fmac_f32_e32 v25, v52, v96
	v_fmac_f32_e32 v22, v56, v96
	v_fmac_f32_e32 v23, v60, v96
	v_fmac_f32_e32 v20, v64, v96
	v_fmac_f32_e32 v21, v68, v96
	v_fmac_f32_e32 v18, v72, v96
	v_fmac_f32_e32 v19, v76, v96
	v_fmac_f32_e32 v16, v80, v96
	v_fmac_f32_e32 v17, v84, v96
	v_fmac_f32_e32 v12, v88, v96
	v_fmac_f32_e32 v13, v92, v96
	v_fmac_f32_e32 v28, v33, v97
	v_fmac_f32_e32 v29, v37, v97
	v_fmac_f32_e32 v26, v41, v97
	v_fmac_f32_e32 v27, v45, v97
	v_fmac_f32_e32 v24, v49, v97
	v_fmac_f32_e32 v25, v53, v97
	v_fmac_f32_e32 v22, v57, v97
	v_fmac_f32_e32 v23, v61, v97
	v_fmac_f32_e32 v20, v65, v97
	v_fmac_f32_e32 v21, v69, v97
	v_fmac_f32_e32 v18, v73, v97
	v_fmac_f32_e32 v19, v77, v97
	v_fmac_f32_e32 v16, v81, v97
	v_fmac_f32_e32 v17, v85, v97
	v_fmac_f32_e32 v12, v89, v97
	v_fmac_f32_e32 v13, v93, v97
	v_fmac_f32_e32 v28, v34, v98
	v_fmac_f32_e32 v29, v38, v98
	v_fmac_f32_e32 v26, v42, v98
	v_fmac_f32_e32 v27, v46, v98
	v_fmac_f32_e32 v24, v50, v98
	v_fmac_f32_e32 v25, v54, v98
	v_fmac_f32_e32 v22, v58, v98
	v_fmac_f32_e32 v23, v62, v98
	v_fmac_f32_e32 v20, v66, v98
	v_fmac_f32_e32 v21, v70, v98
	v_fmac_f32_e32 v18, v74, v98
	v_fmac_f32_e32 v19, v78, v98
	v_fmac_f32_e32 v16, v82, v98
	v_fmac_f32_e32 v17, v86, v98
	v_fmac_f32_e32 v12, v90, v98
	v_fmac_f32_e32 v13, v94, v98
	v_fmac_f32_e32 v28, v35, v99
	v_fmac_f32_e32 v29, v39, v99
	v_fmac_f32_e32 v26, v43, v99
	v_fmac_f32_e32 v27, v47, v99
	v_fmac_f32_e32 v24, v51, v99
	v_fmac_f32_e32 v25, v55, v99
	v_fmac_f32_e32 v22, v59, v99
	v_fmac_f32_e32 v23, v63, v99
	v_fmac_f32_e32 v20, v67, v99
	v_fmac_f32_e32 v21, v71, v99
	v_fmac_f32_e32 v18, v75, v99
	v_fmac_f32_e32 v19, v79, v99
	v_fmac_f32_e32 v16, v83, v99
	v_fmac_f32_e32 v17, v87, v99
	v_fmac_f32_e32 v12, v91, v99
	v_fmac_f32_e32 v13, v95, v99
	global_load_dwordx4 v[32:35], v[168:169], off offset:-3872
	global_load_dwordx4 v[36:39], v[168:169], off offset:224
	global_load_dwordx4 v[40:43], v[170:171], off offset:-3872
	global_load_dwordx4 v[44:47], v[170:171], off offset:224
	global_load_dwordx4 v[48:51], v[172:173], off offset:-3872
	global_load_dwordx4 v[52:55], v[172:173], off offset:224
	global_load_dwordx4 v[56:59], v[174:175], off offset:-3872
	global_load_dwordx4 v[60:63], v[174:175], off offset:224
	global_load_dwordx4 v[64:67], v[176:177], off offset:-3872
	global_load_dwordx4 v[68:71], v[176:177], off offset:224
	global_load_dwordx4 v[72:75], v[178:179], off offset:-3872
	global_load_dwordx4 v[76:79], v[178:179], off offset:224
	global_load_dwordx4 v[80:83], v[180:181], off offset:-3872
	global_load_dwordx4 v[84:87], v[180:181], off offset:224
	global_load_dwordx4 v[88:91], v[182:183], off offset:-3872
	global_load_dwordx4 v[92:95], v[182:183], off offset:224
	global_load_dword v96, v[184:185], off offset:-512
	global_load_dword v97, v[184:185], off
	global_load_dword v98, v[184:185], off offset:512
	global_load_dword v99, v[184:185], off offset:1024
	v_lshl_add_u64 v[184:185], v[184:185], 0, s[4:5]
	s_waitcnt vmcnt(20)
; __device__ __forceinline__ void prep_phase(const Params& p, unsigned char* smem) {
;     ...
;     for (size_t it = gtid; it < (size_t)2 * 16 * 2048; it += nth) {
;         const int j = (int)(it >> 15), rem = (int)(it & 32767), qg = rem >> 11, n = rem & 2047, h = n >> 7, c = n & 127;
;         const float* uq = p.in[25] + (size_t)j * 256 * 1024 + (size_t)(qg * 16) * 1024 + h * 64;
;         const float* uk = p.in[26] + (size_t)j * 16 * 64 * 128 + (size_t)h * 64 * 128 + c;
;         float acc[16];
; #pragma unroll
;         for (int i = 0; i < 16; ++i) acc[i] = 0.f;
;         for (int d = 0; d < 64; ++d) {
;             const float kv = uk[d * 128];
; #pragma unroll
;             for (int i = 0; i < 16; ++i) acc[i] += uq[i * 1024 + d] * kv;
;         }
	v_fmac_f32_e32 v28, v100, v164
	v_fmac_f32_e32 v29, v104, v164
	v_fmac_f32_e32 v26, v108, v164
	v_fmac_f32_e32 v27, v112, v164
	v_fmac_f32_e32 v24, v116, v164
	v_fmac_f32_e32 v25, v120, v164
	v_fmac_f32_e32 v22, v124, v164
	v_fmac_f32_e32 v23, v128, v164
	v_fmac_f32_e32 v20, v132, v164
	v_fmac_f32_e32 v21, v136, v164
	v_fmac_f32_e32 v18, v140, v164
	v_fmac_f32_e32 v19, v144, v164
	v_fmac_f32_e32 v16, v148, v164
	v_fmac_f32_e32 v17, v152, v164
	v_fmac_f32_e32 v12, v156, v164
	v_fmac_f32_e32 v13, v160, v164
	v_fmac_f32_e32 v28, v101, v165
	v_fmac_f32_e32 v29, v105, v165
	v_fmac_f32_e32 v26, v109, v165
	v_fmac_f32_e32 v27, v113, v165
	v_fmac_f32_e32 v24, v117, v165
	v_fmac_f32_e32 v25, v121, v165
	v_fmac_f32_e32 v22, v125, v165
	v_fmac_f32_e32 v23, v129, v165
	v_fmac_f32_e32 v20, v133, v165
	v_fmac_f32_e32 v21, v137, v165
	v_fmac_f32_e32 v18, v141, v165
	v_fmac_f32_e32 v19, v145, v165
	v_fmac_f32_e32 v16, v149, v165
	v_fmac_f32_e32 v17, v153, v165
	v_fmac_f32_e32 v12, v157, v165
	v_fmac_f32_e32 v13, v161, v165
	v_fmac_f32_e32 v28, v102, v166
	v_fmac_f32_e32 v29, v106, v166
	v_fmac_f32_e32 v26, v110, v166
	v_fmac_f32_e32 v27, v114, v166
	v_fmac_f32_e32 v24, v118, v166
	v_fmac_f32_e32 v25, v122, v166
	v_fmac_f32_e32 v22, v126, v166
	v_fmac_f32_e32 v23, v130, v166
	v_fmac_f32_e32 v20, v134, v166
	v_fmac_f32_e32 v21, v138, v166
	v_fmac_f32_e32 v18, v142, v166
	v_fmac_f32_e32 v19, v146, v166
	v_fmac_f32_e32 v16, v150, v166
	v_fmac_f32_e32 v17, v154, v166
	v_fmac_f32_e32 v12, v158, v166
	v_fmac_f32_e32 v13, v162, v166
	v_fmac_f32_e32 v28, v103, v167
	v_fmac_f32_e32 v29, v107, v167
	v_fmac_f32_e32 v26, v111, v167
	v_fmac_f32_e32 v27, v115, v167
	v_fmac_f32_e32 v24, v119, v167
	v_fmac_f32_e32 v25, v123, v167
	v_fmac_f32_e32 v22, v127, v167
	v_fmac_f32_e32 v23, v131, v167
	v_fmac_f32_e32 v20, v135, v167
	v_fmac_f32_e32 v21, v139, v167
	v_fmac_f32_e32 v18, v143, v167
	v_fmac_f32_e32 v19, v147, v167
	v_fmac_f32_e32 v16, v151, v167
	v_fmac_f32_e32 v17, v155, v167
	v_fmac_f32_e32 v12, v159, v167
	v_fmac_f32_e32 v13, v163, v167
	global_load_dwordx4 v[100:103], v[168:169], off offset:-3856
	global_load_dwordx4 v[104:107], v[168:169], off offset:240
	global_load_dwordx4 v[108:111], v[170:171], off offset:-3856
	global_load_dwordx4 v[112:115], v[170:171], off offset:240
	global_load_dwordx4 v[116:119], v[172:173], off offset:-3856
	global_load_dwordx4 v[120:123], v[172:173], off offset:240
	global_load_dwordx4 v[124:127], v[174:175], off offset:-3856
	global_load_dwordx4 v[128:131], v[174:175], off offset:240
	global_load_dwordx4 v[132:135], v[176:177], off offset:-3856
	global_load_dwordx4 v[136:139], v[176:177], off offset:240
	global_load_dwordx4 v[140:143], v[178:179], off offset:-3856
	global_load_dwordx4 v[144:147], v[178:179], off offset:240
	global_load_dwordx4 v[148:151], v[180:181], off offset:-3856
	global_load_dwordx4 v[152:155], v[180:181], off offset:240
	global_load_dwordx4 v[156:159], v[182:183], off offset:-3856
	global_load_dwordx4 v[160:163], v[182:183], off offset:240
	global_load_dword v164, v[184:185], off offset:-512
	global_load_dword v165, v[184:185], off
	global_load_dword v166, v[184:185], off offset:512
	global_load_dword v167, v[184:185], off offset:1024
	v_lshl_add_u64 v[184:185], v[184:185], 0, s[4:5]
	s_waitcnt vmcnt(20)
	v_fmac_f32_e32 v28, v32, v96
	v_fmac_f32_e32 v29, v36, v96
	v_fmac_f32_e32 v26, v40, v96
	v_fmac_f32_e32 v27, v44, v96
	v_fmac_f32_e32 v24, v48, v96
	v_fmac_f32_e32 v25, v52, v96
	v_fmac_f32_e32 v22, v56, v96
	v_fmac_f32_e32 v23, v60, v96
	v_fmac_f32_e32 v20, v64, v96
	v_fmac_f32_e32 v21, v68, v96
	v_fmac_f32_e32 v18, v72, v96
	v_fmac_f32_e32 v19, v76, v96
	v_fmac_f32_e32 v16, v80, v96
	v_fmac_f32_e32 v17, v84, v96
	v_fmac_f32_e32 v12, v88, v96
	v_fmac_f32_e32 v13, v92, v96
	v_fmac_f32_e32 v28, v33, v97
	v_fmac_f32_e32 v29, v37, v97
	v_fmac_f32_e32 v26, v41, v97
	v_fmac_f32_e32 v27, v45, v97
	v_fmac_f32_e32 v24, v49, v97
	v_fmac_f32_e32 v25, v53, v97
	v_fmac_f32_e32 v22, v57, v97
	v_fmac_f32_e32 v23, v61, v97
	v_fmac_f32_e32 v20, v65, v97
	v_fmac_f32_e32 v21, v69, v97
	v_fmac_f32_e32 v18, v73, v97
	v_fmac_f32_e32 v19, v77, v97
	v_fmac_f32_e32 v16, v81, v97
	v_fmac_f32_e32 v17, v85, v97
	v_fmac_f32_e32 v12, v89, v97
	v_fmac_f32_e32 v13, v93, v97
	v_fmac_f32_e32 v28, v34, v98
	v_fmac_f32_e32 v29, v38, v98
	v_fmac_f32_e32 v26, v42, v98
	v_fmac_f32_e32 v27, v46, v98
	v_fmac_f32_e32 v24, v50, v98
	v_fmac_f32_e32 v25, v54, v98
	v_fmac_f32_e32 v22, v58, v98
	v_fmac_f32_e32 v23, v62, v98
	v_fmac_f32_e32 v20, v66, v98
	v_fmac_f32_e32 v21, v70, v98
	v_fmac_f32_e32 v18, v74, v98
	v_fmac_f32_e32 v19, v78, v98
	v_fmac_f32_e32 v16, v82, v98
	v_fmac_f32_e32 v17, v86, v98
	v_fmac_f32_e32 v12, v90, v98
	v_fmac_f32_e32 v13, v94, v98
	v_fmac_f32_e32 v28, v35, v99
	v_fmac_f32_e32 v29, v39, v99
	v_fmac_f32_e32 v26, v43, v99
	v_fmac_f32_e32 v27, v47, v99
	v_fmac_f32_e32 v24, v51, v99
	v_fmac_f32_e32 v25, v55, v99
	v_fmac_f32_e32 v22, v59, v99
	v_fmac_f32_e32 v23, v63, v99
	v_fmac_f32_e32 v20, v67, v99
	v_fmac_f32_e32 v21, v71, v99
	v_fmac_f32_e32 v18, v75, v99
	v_fmac_f32_e32 v19, v79, v99
	v_fmac_f32_e32 v16, v83, v99
	v_fmac_f32_e32 v17, v87, v99
	v_fmac_f32_e32 v12, v91, v99
	v_fmac_f32_e32 v13, v95, v99
	s_waitcnt vmcnt(0)
; __device__ __forceinline__ u32x4 pack8(f32x4 a, f32x4 b) { u32x4 w; w.x = pk2(a[0], a[1]); w.y = pk2(a[2], a[3]); w.z = pk2(b[0], b[1]); w.w = pk2(b[2], b[3]); return w; }
; __device__ __forceinline__ h16* w_dsa_q(unsigned char* ws, int j) { return w_dsa_in(ws, j) + MiB / 2; }
; __device__ __forceinline__ void prep_phase(const Params& p, unsigned char* smem) {
;     ...
;     for (size_t it = gtid; it < (size_t)2 * 16 * 2048; it += nth) {
;         const int j = (int)(it >> 15), rem = (int)(it & 32767), qg = rem >> 11, n = rem & 2047, h = n >> 7, c = n & 127;
;         const float* uq = p.in[25] + (size_t)j * 256 * 1024 + (size_t)(qg * 16) * 1024 + h * 64;
;         const float* uk = p.in[26] + (size_t)j * 16 * 64 * 128 + (size_t)h * 64 * 128 + c;
;         float acc[16];
; #pragma unroll
;         for (int i = 0; i < 16; ++i) acc[i] = 0.f;
;         for (int d = 0; d < 64; ++d) {
;             const float kv = uk[d * 128];
; #pragma unroll
;             for (int i = 0; i < 16; ++i) acc[i] += uq[i * 1024 + d] * kv;
;         }
;         const float sc = 0.18033688011112042f;
;         h16* dst = w_dsa_q(p.ws, j) + (size_t)n * 256 + qg * 16;
;         *(u32x4*)dst = pack8((f32x4){acc[0] * sc, acc[1] * sc, acc[2] * sc, acc[3] * sc}, (f32x4){acc[4] * sc, acc[5] * sc, acc[6] * sc, acc[7] * sc});
;         *(u32x4*)(dst + 8) = pack8((f32x4){acc[8] * sc, acc[9] * sc, acc[10] * sc, acc[11] * sc}, (f32x4){acc[12] * sc, acc[13] * sc, acc[14] * sc, acc[15] * sc});
	v_fmac_f32_e32 v28, v100, v164
	v_fmac_f32_e32 v29, v104, v164
	v_fmac_f32_e32 v26, v108, v164
	v_fmac_f32_e32 v27, v112, v164
	v_fmac_f32_e32 v24, v116, v164
	v_fmac_f32_e32 v25, v120, v164
	v_fmac_f32_e32 v22, v124, v164
	v_fmac_f32_e32 v23, v128, v164
	v_fmac_f32_e32 v20, v132, v164
	v_fmac_f32_e32 v21, v136, v164
	v_fmac_f32_e32 v18, v140, v164
	v_fmac_f32_e32 v19, v144, v164
	v_fmac_f32_e32 v16, v148, v164
	v_fmac_f32_e32 v17, v152, v164
	v_fmac_f32_e32 v12, v156, v164
	v_fmac_f32_e32 v13, v160, v164
	v_fmac_f32_e32 v28, v101, v165
	v_fmac_f32_e32 v29, v105, v165
	v_fmac_f32_e32 v26, v109, v165
	v_fmac_f32_e32 v27, v113, v165
	v_fmac_f32_e32 v24, v117, v165
	v_fmac_f32_e32 v25, v121, v165
	v_fmac_f32_e32 v22, v125, v165
	v_fmac_f32_e32 v23, v129, v165
	v_fmac_f32_e32 v20, v133, v165
	v_fmac_f32_e32 v21, v137, v165
	v_fmac_f32_e32 v18, v141, v165
	v_fmac_f32_e32 v19, v145, v165
	v_fmac_f32_e32 v16, v149, v165
	v_fmac_f32_e32 v17, v153, v165
	v_fmac_f32_e32 v12, v157, v165
	v_fmac_f32_e32 v13, v161, v165
	v_fmac_f32_e32 v28, v102, v166
	v_fmac_f32_e32 v29, v106, v166
	v_fmac_f32_e32 v26, v110, v166
	v_fmac_f32_e32 v27, v114, v166
	v_fmac_f32_e32 v24, v118, v166
	v_fmac_f32_e32 v25, v122, v166
	v_fmac_f32_e32 v22, v126, v166
	v_fmac_f32_e32 v23, v130, v166
	v_fmac_f32_e32 v20, v134, v166
	v_fmac_f32_e32 v21, v138, v166
	v_fmac_f32_e32 v18, v142, v166
	v_fmac_f32_e32 v19, v146, v166
	v_fmac_f32_e32 v16, v150, v166
	v_fmac_f32_e32 v17, v154, v166
	v_fmac_f32_e32 v12, v158, v166
	v_fmac_f32_e32 v13, v162, v166
	v_fmac_f32_e32 v28, v103, v167
	v_fmac_f32_e32 v29, v107, v167
	v_fmac_f32_e32 v26, v111, v167
	v_fmac_f32_e32 v27, v115, v167
	v_fmac_f32_e32 v24, v119, v167
	v_fmac_f32_e32 v25, v123, v167
	v_fmac_f32_e32 v22, v127, v167
	v_fmac_f32_e32 v23, v131, v167
	v_fmac_f32_e32 v20, v135, v167
	v_fmac_f32_e32 v21, v139, v167
	v_fmac_f32_e32 v18, v143, v167
	v_fmac_f32_e32 v19, v147, v167
	v_fmac_f32_e32 v16, v151, v167
	v_fmac_f32_e32 v17, v155, v167
	v_fmac_f32_e32 v12, v159, v167
	v_fmac_f32_e32 v13, v163, v167
	v_readlane_b32 s4, v251, 19
	v_readlane_b32 s6, v251, 21
	v_readlane_b32 s7, v251, 22
	v_readlane_b32 s5, v251, 20
	v_lshlrev_b32_e32 v1, 9, v6
	v_mov_b64_e32 v[10:11], s[6:7]
	s_mov_b32 s6, 0x500000
	v_mad_u64_u32 v[10:11], s[4:5], v8, s6, v[10:11]
	v_mad_u32_u24 v11, v9, s6, v11
	v_and_b32_e32 v196, 0xffe00, v1
	v_lshrrev_b32_e32 v1, 6, v6
	v_lshl_add_u64 v[8:9], v[10:11], 0, v[196:197]
	v_and_b32_e32 v196, 0x1e0, v1
	v_lshl_add_u64 v[14:15], v[8:9], 0, v[196:197]
	s_mov_b64 s[4:5], 0x6d00000
	v_lshl_add_u64 v[30:31], v[14:15], 0, s[4:5]
	s_mov_b32 s4, 0x6d00000
	s_mov_b32 s6, 0x3e38aa3b
	v_add_co_u32_e32 v14, vcc, s4, v14
	v_readlane_b32 s4, v250, 42
	v_pk_mul_f32 v[8:9], v[28:29], s[6:7] op_sel_hi:[1,0]
	v_pk_mul_f32 v[10:11], v[26:27], s[6:7] op_sel_hi:[1,0]
	v_pk_mul_f32 v[24:25], v[24:25], s[6:7] op_sel_hi:[1,0]
	v_pk_mul_f32 v[22:23], v[22:23], s[6:7] op_sel_hi:[1,0]
	v_readlane_b32 s5, v250, 43
	v_cvt_pk_f16_f32 v8, v8, v9
	v_cvt_pk_f16_f32 v9, v10, v11
	v_cvt_pk_f16_f32 v10, v24, v25
	v_cvt_pk_f16_f32 v11, v22, v23
	v_addc_co_u32_e32 v15, vcc, 0, v15, vcc
	v_lshl_add_u64 v[6:7], v[6:7], 0, s[4:5]
	s_mov_b64 s[4:5], 0xffff
	global_store_dwordx4 v[14:15], v[8:11], off
	v_pk_mul_f32 v[14:15], v[16:17], s[6:7] op_sel_hi:[1,0]
	v_pk_mul_f32 v[12:13], v[12:13], s[6:7] op_sel_hi:[1,0]
	v_pk_mul_f32 v[8:9], v[20:21], s[6:7] op_sel_hi:[1,0]
	v_pk_mul_f32 v[10:11], v[18:19], s[6:7] op_sel_hi:[1,0]
	v_cmp_lt_u64_e32 vcc, s[4:5], v[6:7]
	v_cvt_pk_f16_f32 v8, v8, v9
	v_cvt_pk_f16_f32 v9, v10, v11
	v_cvt_pk_f16_f32 v10, v14, v15
	v_cvt_pk_f16_f32 v11, v12, v13
	s_or_b64 s[2:3], vcc, s[2:3]
	global_store_dwordx4 v[30:31], v[8:11], off offset:16
	s_andn2_b64 exec, exec, s[2:3]
	s_cbranch_execnz .LBB0_526

; __device__ __forceinline__ void prep_phase(const Params& p, unsigned char* smem) {
;     ...
;     for (size_t it = gtid; it < (size_t)2 * 128 * 1024; it += nth) {
;         const int j = (int)(it >> 17), rem = (int)(it & 131071), kg = rem >> 10, n = rem & 1023, h = kg >> 3, c0 = (kg & 7) * 16;
;         const float* uv = p.in[27] + (size_t)((j * 16 + h) * 128 + c0) * 64;
;         const float* wo = p.in[31] + (size_t)j * 1048576 + (size_t)(h * 64) * 1024 + n;
;         float acc[16];
; #pragma unroll
;         for (int i = 0; i < 16; ++i) acc[i] = 0.f;
;         for (int v = 0; v < 64; ++v) {
;             const float wv = wo[(size_t)v * 1024];
; #pragma unroll
;             for (int i = 0; i < 16; ++i) acc[i] += uv[i * 64 + v] * wv;
.LBB0_532:
	v_mov_b64_e32 v[168:169], v[8:9]
	s_mov_b32 s4, 0xffffe000
	s_mov_b32 s5, -1
	v_lshl_add_u64 v[170:171], v[6:7], 0, s[4:5]
	v_mov_b64_e32 v[172:173], v[6:7]
	s_mov_b64 s[4:5], 0x4000
	s_waitcnt vmcnt(0)
	global_load_dwordx4 v[32:35], v[168:169], off
	global_load_dwordx4 v[36:39], v[168:169], off offset:256
	global_load_dwordx4 v[40:43], v[168:169], off offset:512
	global_load_dwordx4 v[44:47], v[168:169], off offset:768
	global_load_dwordx4 v[48:51], v[168:169], off offset:1024
	global_load_dwordx4 v[52:55], v[168:169], off offset:1280
	global_load_dwordx4 v[56:59], v[168:169], off offset:1536
	global_load_dwordx4 v[60:63], v[168:169], off offset:1792
	global_load_dwordx4 v[64:67], v[168:169], off offset:2048
	global_load_dwordx4 v[68:71], v[168:169], off offset:2304
	global_load_dwordx4 v[72:75], v[168:169], off offset:2560
	global_load_dwordx4 v[76:79], v[168:169], off offset:2816
	global_load_dwordx4 v[80:83], v[168:169], off offset:3072
	global_load_dwordx4 v[84:87], v[168:169], off offset:3328
	global_load_dwordx4 v[88:91], v[168:169], off offset:3584
	global_load_dwordx4 v[92:95], v[168:169], off offset:3840
	global_load_dword v96, v[170:171], off offset:-4096
	global_load_dword v97, v[170:171], off
	global_load_dword v98, v[172:173], off offset:-4096
	global_load_dword v99, v[172:173], off
	v_lshl_add_u64 v[170:171], v[170:171], 0, s[4:5]
	v_lshl_add_u64 v[172:173], v[172:173], 0, s[4:5]
	global_load_dwordx4 v[100:103], v[168:169], off offset:16
	global_load_dwordx4 v[104:107], v[168:169], off offset:272
	global_load_dwordx4 v[108:111], v[168:169], off offset:528
	global_load_dwordx4 v[112:115], v[168:169], off offset:784
	global_load_dwordx4 v[116:119], v[168:169], off offset:1040
	global_load_dwordx4 v[120:123], v[168:169], off offset:1296
	global_load_dwordx4 v[124:127], v[168:169], off offset:1552
	global_load_dwordx4 v[128:131], v[168:169], off offset:1808
	global_load_dwordx4 v[132:135], v[168:169], off offset:2064
	global_load_dwordx4 v[136:139], v[168:169], off offset:2320
	global_load_dwordx4 v[140:143], v[168:169], off offset:2576
	global_load_dwordx4 v[144:147], v[168:169], off offset:2832
	global_load_dwordx4 v[148:151], v[168:169], off offset:3088
	global_load_dwordx4 v[152:155], v[168:169], off offset:3344
	global_load_dwordx4 v[156:159], v[168:169], off offset:3600
	global_load_dwordx4 v[160:163], v[168:169], off offset:3856
	global_load_dword v164, v[170:171], off offset:-4096
	global_load_dword v165, v[170:171], off
	global_load_dword v166, v[172:173], off offset:-4096
	global_load_dword v167, v[172:173], off
	v_lshl_add_u64 v[170:171], v[170:171], 0, s[4:5]
	v_lshl_add_u64 v[172:173], v[172:173], 0, s[4:5]
	s_waitcnt vmcnt(20)
	v_fmac_f32_e32 v24, v32, v96
	v_fmac_f32_e32 v25, v36, v96
	v_fmac_f32_e32 v22, v40, v96
	v_fmac_f32_e32 v23, v44, v96
	v_fmac_f32_e32 v20, v48, v96
	v_fmac_f32_e32 v21, v52, v96
	v_fmac_f32_e32 v18, v56, v96
	v_fmac_f32_e32 v19, v60, v96
	v_fmac_f32_e32 v16, v64, v96
	v_fmac_f32_e32 v17, v68, v96
	v_fmac_f32_e32 v14, v72, v96
	v_fmac_f32_e32 v15, v76, v96
	v_fmac_f32_e32 v12, v80, v96
	v_fmac_f32_e32 v13, v84, v96
	v_fmac_f32_e32 v10, v88, v96
	v_fmac_f32_e32 v11, v92, v96
	v_fmac_f32_e32 v24, v33, v97
	v_fmac_f32_e32 v25, v37, v97
	v_fmac_f32_e32 v22, v41, v97
	v_fmac_f32_e32 v23, v45, v97
	v_fmac_f32_e32 v20, v49, v97
	v_fmac_f32_e32 v21, v53, v97
	v_fmac_f32_e32 v18, v57, v97
	v_fmac_f32_e32 v19, v61, v97
	v_fmac_f32_e32 v16, v65, v97
	v_fmac_f32_e32 v17, v69, v97
	v_fmac_f32_e32 v14, v73, v97
	v_fmac_f32_e32 v15, v77, v97
	v_fmac_f32_e32 v12, v81, v97
	v_fmac_f32_e32 v13, v85, v97
	v_fmac_f32_e32 v10, v89, v97
	v_fmac_f32_e32 v11, v93, v97
	v_fmac_f32_e32 v24, v34, v98
	v_fmac_f32_e32 v25, v38, v98
	v_fmac_f32_e32 v22, v42, v98
	v_fmac_f32_e32 v23, v46, v98
	v_fmac_f32_e32 v20, v50, v98
	v_fmac_f32_e32 v21, v54, v98
	v_fmac_f32_e32 v18, v58, v98
	v_fmac_f32_e32 v19, v62, v98
	v_fmac_f32_e32 v16, v66, v98
	v_fmac_f32_e32 v17, v70, v98
	v_fmac_f32_e32 v14, v74, v98
	v_fmac_f32_e32 v15, v78, v98
	v_fmac_f32_e32 v12, v82, v98
	v_fmac_f32_e32 v13, v86, v98
	v_fmac_f32_e32 v10, v90, v98
	v_fmac_f32_e32 v11, v94, v98
	v_fmac_f32_e32 v24, v35, v99
	v_fmac_f32_e32 v25, v39, v99
	v_fmac_f32_e32 v22, v43, v99
	v_fmac_f32_e32 v23, v47, v99
	v_fmac_f32_e32 v20, v51, v99
	v_fmac_f32_e32 v21, v55, v99
	v_fmac_f32_e32 v18, v59, v99
	v_fmac_f32_e32 v19, v63, v99
	v_fmac_f32_e32 v16, v67, v99
	v_fmac_f32_e32 v17, v71, v99
	v_fmac_f32_e32 v14, v75, v99
	v_fmac_f32_e32 v15, v79, v99
	v_fmac_f32_e32 v12, v83, v99
	v_fmac_f32_e32 v13, v87, v99
	v_fmac_f32_e32 v10, v91, v99
	v_fmac_f32_e32 v11, v95, v99
	global_load_dwordx4 v[32:35], v[168:169], off offset:32
	global_load_dwordx4 v[36:39], v[168:169], off offset:288
	global_load_dwordx4 v[40:43], v[168:169], off offset:544
	global_load_dwordx4 v[44:47], v[168:169], off offset:800
	global_load_dwordx4 v[48:51], v[168:169], off offset:1056
	global_load_dwordx4 v[52:55], v[168:169], off offset:1312
	global_load_dwordx4 v[56:59], v[168:169], off offset:1568
	global_load_dwordx4 v[60:63], v[168:169], off offset:1824
	global_load_dwordx4 v[64:67], v[168:169], off offset:2080
	global_load_dwordx4 v[68:71], v[168:169], off offset:2336
	global_load_dwordx4 v[72:75], v[168:169], off offset:2592
	global_load_dwordx4 v[76:79], v[168:169], off offset:2848
	global_load_dwordx4 v[80:83], v[168:169], off offset:3104
	global_load_dwordx4 v[84:87], v[168:169], off offset:3360
	global_load_dwordx4 v[88:91], v[168:169], off offset:3616
	global_load_dwordx4 v[92:95], v[168:169], off offset:3872
	global_load_dword v96, v[170:171], off offset:-4096
	global_load_dword v97, v[170:171], off
	global_load_dword v98, v[172:173], off offset:-4096
	global_load_dword v99, v[172:173], off
	v_lshl_add_u64 v[170:171], v[170:171], 0, s[4:5]
	v_lshl_add_u64 v[172:173], v[172:173], 0, s[4:5]
	s_waitcnt vmcnt(20)
; __device__ __forceinline__ void prep_phase(const Params& p, unsigned char* smem) {
;     ...
;     for (size_t it = gtid; it < (size_t)2 * 128 * 1024; it += nth) {
;         const int j = (int)(it >> 17), rem = (int)(it & 131071), kg = rem >> 10, n = rem & 1023, h = kg >> 3, c0 = (kg & 7) * 16;
;         const float* uv = p.in[27] + (size_t)((j * 16 + h) * 128 + c0) * 64;
;         const float* wo = p.in[31] + (size_t)j * 1048576 + (size_t)(h * 64) * 1024 + n;
;         float acc[16];
; #pragma unroll
;         for (int i = 0; i < 16; ++i) acc[i] = 0.f;
;         for (int v = 0; v < 64; ++v) {
;             const float wv = wo[(size_t)v * 1024];
; #pragma unroll
;             for (int i = 0; i < 16; ++i) acc[i] += uv[i * 64 + v] * wv;
	v_fmac_f32_e32 v24, v100, v164
	v_fmac_f32_e32 v25, v104, v164
	v_fmac_f32_e32 v22, v108, v164
	v_fmac_f32_e32 v23, v112, v164
	v_fmac_f32_e32 v20, v116, v164
	v_fmac_f32_e32 v21, v120, v164
	v_fmac_f32_e32 v18, v124, v164
	v_fmac_f32_e32 v19, v128, v164
	v_fmac_f32_e32 v16, v132, v164
	v_fmac_f32_e32 v17, v136, v164
	v_fmac_f32_e32 v14, v140, v164
	v_fmac_f32_e32 v15, v144, v164
	v_fmac_f32_e32 v12, v148, v164
	v_fmac_f32_e32 v13, v152, v164
	v_fmac_f32_e32 v10, v156, v164
	v_fmac_f32_e32 v11, v160, v164
	v_fmac_f32_e32 v24, v101, v165
	v_fmac_f32_e32 v25, v105, v165
	v_fmac_f32_e32 v22, v109, v165
	v_fmac_f32_e32 v23, v113, v165
	v_fmac_f32_e32 v20, v117, v165
	v_fmac_f32_e32 v21, v121, v165
	v_fmac_f32_e32 v18, v125, v165
	v_fmac_f32_e32 v19, v129, v165
	v_fmac_f32_e32 v16, v133, v165
	v_fmac_f32_e32 v17, v137, v165
	v_fmac_f32_e32 v14, v141, v165
	v_fmac_f32_e32 v15, v145, v165
	v_fmac_f32_e32 v12, v149, v165
	v_fmac_f32_e32 v13, v153, v165
	v_fmac_f32_e32 v10, v157, v165
	v_fmac_f32_e32 v11, v161, v165
	v_fmac_f32_e32 v24, v102, v166
	v_fmac_f32_e32 v25, v106, v166
	v_fmac_f32_e32 v22, v110, v166
	v_fmac_f32_e32 v23, v114, v166
	v_fmac_f32_e32 v20, v118, v166
	v_fmac_f32_e32 v21, v122, v166
	v_fmac_f32_e32 v18, v126, v166
	v_fmac_f32_e32 v19, v130, v166
	v_fmac_f32_e32 v16, v134, v166
	v_fmac_f32_e32 v17, v138, v166
	v_fmac_f32_e32 v14, v142, v166
	v_fmac_f32_e32 v15, v146, v166
	v_fmac_f32_e32 v12, v150, v166
	v_fmac_f32_e32 v13, v154, v166
	v_fmac_f32_e32 v10, v158, v166
	v_fmac_f32_e32 v11, v162, v166
	v_fmac_f32_e32 v24, v103, v167
	v_fmac_f32_e32 v25, v107, v167
	v_fmac_f32_e32 v22, v111, v167
	v_fmac_f32_e32 v23, v115, v167
	v_fmac_f32_e32 v20, v119, v167
	v_fmac_f32_e32 v21, v123, v167
	v_fmac_f32_e32 v18, v127, v167
	v_fmac_f32_e32 v19, v131, v167
	v_fmac_f32_e32 v16, v135, v167
	v_fmac_f32_e32 v17, v139, v167
	v_fmac_f32_e32 v14, v143, v167
	v_fmac_f32_e32 v15, v147, v167
	v_fmac_f32_e32 v12, v151, v167
	v_fmac_f32_e32 v13, v155, v167
	v_fmac_f32_e32 v10, v159, v167
	v_fmac_f32_e32 v11, v163, v167
	global_load_dwordx4 v[100:103], v[168:169], off offset:48
	global_load_dwordx4 v[104:107], v[168:169], off offset:304
	global_load_dwordx4 v[108:111], v[168:169], off offset:560
	global_load_dwordx4 v[112:115], v[168:169], off offset:816
	global_load_dwordx4 v[116:119], v[168:169], off offset:1072
	global_load_dwordx4 v[120:123], v[168:169], off offset:1328
	global_load_dwordx4 v[124:127], v[168:169], off offset:1584
	global_load_dwordx4 v[128:131], v[168:169], off offset:1840
	global_load_dwordx4 v[132:135], v[168:169], off offset:2096
	global_load_dwordx4 v[136:139], v[168:169], off offset:2352
	global_load_dwordx4 v[140:143], v[168:169], off offset:2608
	global_load_dwordx4 v[144:147], v[168:169], off offset:2864
	global_load_dwordx4 v[148:151], v[168:169], off offset:3120
	global_load_dwordx4 v[152:155], v[168:169], off offset:3376
	global_load_dwordx4 v[156:159], v[168:169], off offset:3632
	global_load_dwordx4 v[160:163], v[168:169], off offset:3888
	global_load_dword v164, v[170:171], off offset:-4096
	global_load_dword v165, v[170:171], off
	global_load_dword v166, v[172:173], off offset:-4096
	global_load_dword v167, v[172:173], off
	v_lshl_add_u64 v[170:171], v[170:171], 0, s[4:5]
	v_lshl_add_u64 v[172:173], v[172:173], 0, s[4:5]
	s_waitcnt vmcnt(20)
	v_fmac_f32_e32 v24, v32, v96
	v_fmac_f32_e32 v25, v36, v96
	v_fmac_f32_e32 v22, v40, v96
	v_fmac_f32_e32 v23, v44, v96
	v_fmac_f32_e32 v20, v48, v96
	v_fmac_f32_e32 v21, v52, v96
	v_fmac_f32_e32 v18, v56, v96
	v_fmac_f32_e32 v19, v60, v96
	v_fmac_f32_e32 v16, v64, v96
	v_fmac_f32_e32 v17, v68, v96
	v_fmac_f32_e32 v14, v72, v96
	v_fmac_f32_e32 v15, v76, v96
	v_fmac_f32_e32 v12, v80, v96
	v_fmac_f32_e32 v13, v84, v96
	v_fmac_f32_e32 v10, v88, v96
	v_fmac_f32_e32 v11, v92, v96
	v_fmac_f32_e32 v24, v33, v97
	v_fmac_f32_e32 v25, v37, v97
	v_fmac_f32_e32 v22, v41, v97
	v_fmac_f32_e32 v23, v45, v97
	v_fmac_f32_e32 v20, v49, v97
	v_fmac_f32_e32 v21, v53, v97
	v_fmac_f32_e32 v18, v57, v97
	v_fmac_f32_e32 v19, v61, v97
	v_fmac_f32_e32 v16, v65, v97
	v_fmac_f32_e32 v17, v69, v97
	v_fmac_f32_e32 v14, v73, v97
	v_fmac_f32_e32 v15, v77, v97
	v_fmac_f32_e32 v12, v81, v97
	v_fmac_f32_e32 v13, v85, v97
	v_fmac_f32_e32 v10, v89, v97
	v_fmac_f32_e32 v11, v93, v97
	v_fmac_f32_e32 v24, v34, v98
	v_fmac_f32_e32 v25, v38, v98
	v_fmac_f32_e32 v22, v42, v98
	v_fmac_f32_e32 v23, v46, v98
	v_fmac_f32_e32 v20, v50, v98
	v_fmac_f32_e32 v21, v54, v98
	v_fmac_f32_e32 v18, v58, v98
	v_fmac_f32_e32 v19, v62, v98
	v_fmac_f32_e32 v16, v66, v98
	v_fmac_f32_e32 v17, v70, v98
	v_fmac_f32_e32 v14, v74, v98
	v_fmac_f32_e32 v15, v78, v98
	v_fmac_f32_e32 v12, v82, v98
	v_fmac_f32_e32 v13, v86, v98
	v_fmac_f32_e32 v10, v90, v98
	v_fmac_f32_e32 v11, v94, v98
	v_fmac_f32_e32 v24, v35, v99
	v_fmac_f32_e32 v25, v39, v99
	v_fmac_f32_e32 v22, v43, v99
	v_fmac_f32_e32 v23, v47, v99
	v_fmac_f32_e32 v20, v51, v99
	v_fmac_f32_e32 v21, v55, v99
	v_fmac_f32_e32 v18, v59, v99
	v_fmac_f32_e32 v19, v63, v99
	v_fmac_f32_e32 v16, v67, v99
	v_fmac_f32_e32 v17, v71, v99
	v_fmac_f32_e32 v14, v75, v99
	v_fmac_f32_e32 v15, v79, v99
	v_fmac_f32_e32 v12, v83, v99
	v_fmac_f32_e32 v13, v87, v99
	v_fmac_f32_e32 v10, v91, v99
	v_fmac_f32_e32 v11, v95, v99
	global_load_dwordx4 v[32:35], v[168:169], off offset:64
	global_load_dwordx4 v[36:39], v[168:169], off offset:320
	global_load_dwordx4 v[40:43], v[168:169], off offset:576
	global_load_dwordx4 v[44:47], v[168:169], off offset:832
	global_load_dwordx4 v[48:51], v[168:169], off offset:1088
	global_load_dwordx4 v[52:55], v[168:169], off offset:1344
	global_load_dwordx4 v[56:59], v[168:169], off offset:1600
	global_load_dwordx4 v[60:63], v[168:169], off offset:1856
	global_load_dwordx4 v[64:67], v[168:169], off offset:2112
	global_load_dwordx4 v[68:71], v[168:169], off offset:2368
	global_load_dwordx4 v[72:75], v[168:169], off offset:2624
	global_load_dwordx4 v[76:79], v[168:169], off offset:2880
	global_load_dwordx4 v[80:83], v[168:169], off offset:3136
	global_load_dwordx4 v[84:87], v[168:169], off offset:3392
	global_load_dwordx4 v[88:91], v[168:169], off offset:3648
	global_load_dwordx4 v[92:95], v[168:169], off offset:3904
	global_load_dword v96, v[170:171], off offset:-4096
	global_load_dword v97, v[170:171], off
	global_load_dword v98, v[172:173], off offset:-4096
	global_load_dword v99, v[172:173], off
	v_lshl_add_u64 v[170:171], v[170:171], 0, s[4:5]
	v_lshl_add_u64 v[172:173], v[172:173], 0, s[4:5]
	s_waitcnt vmcnt(20)
; __device__ __forceinline__ void prep_phase(const Params& p, unsigned char* smem) {
;     ...
;     for (size_t it = gtid; it < (size_t)2 * 128 * 1024; it += nth) {
;         const int j = (int)(it >> 17), rem = (int)(it & 131071), kg = rem >> 10, n = rem & 1023, h = kg >> 3, c0 = (kg & 7) * 16;
;         const float* uv = p.in[27] + (size_t)((j * 16 + h) * 128 + c0) * 64;
;         const float* wo = p.in[31] + (size_t)j * 1048576 + (size_t)(h * 64) * 1024 + n;
;         float acc[16];
; #pragma unroll
;         for (int i = 0; i < 16; ++i) acc[i] = 0.f;
;         for (int v = 0; v < 64; ++v) {
;             const float wv = wo[(size_t)v * 1024];
; #pragma unroll
;             for (int i = 0; i < 16; ++i) acc[i] += uv[i * 64 + v] * wv;
	v_fmac_f32_e32 v24, v100, v164
	v_fmac_f32_e32 v25, v104, v164
	v_fmac_f32_e32 v22, v108, v164
	v_fmac_f32_e32 v23, v112, v164
	v_fmac_f32_e32 v20, v116, v164
	v_fmac_f32_e32 v21, v120, v164
	v_fmac_f32_e32 v18, v124, v164
	v_fmac_f32_e32 v19, v128, v164
	v_fmac_f32_e32 v16, v132, v164
	v_fmac_f32_e32 v17, v136, v164
	v_fmac_f32_e32 v14, v140, v164
	v_fmac_f32_e32 v15, v144, v164
	v_fmac_f32_e32 v12, v148, v164
	v_fmac_f32_e32 v13, v152, v164
	v_fmac_f32_e32 v10, v156, v164
	v_fmac_f32_e32 v11, v160, v164
	v_fmac_f32_e32 v24, v101, v165
	v_fmac_f32_e32 v25, v105, v165
	v_fmac_f32_e32 v22, v109, v165
	v_fmac_f32_e32 v23, v113, v165
	v_fmac_f32_e32 v20, v117, v165
	v_fmac_f32_e32 v21, v121, v165
	v_fmac_f32_e32 v18, v125, v165
	v_fmac_f32_e32 v19, v129, v165
	v_fmac_f32_e32 v16, v133, v165
	v_fmac_f32_e32 v17, v137, v165
	v_fmac_f32_e32 v14, v141, v165
	v_fmac_f32_e32 v15, v145, v165
	v_fmac_f32_e32 v12, v149, v165
	v_fmac_f32_e32 v13, v153, v165
	v_fmac_f32_e32 v10, v157, v165
	v_fmac_f32_e32 v11, v161, v165
	v_fmac_f32_e32 v24, v102, v166
	v_fmac_f32_e32 v25, v106, v166
	v_fmac_f32_e32 v22, v110, v166
	v_fmac_f32_e32 v23, v114, v166
	v_fmac_f32_e32 v20, v118, v166
	v_fmac_f32_e32 v21, v122, v166
	v_fmac_f32_e32 v18, v126, v166
	v_fmac_f32_e32 v19, v130, v166
	v_fmac_f32_e32 v16, v134, v166
	v_fmac_f32_e32 v17, v138, v166
	v_fmac_f32_e32 v14, v142, v166
	v_fmac_f32_e32 v15, v146, v166
	v_fmac_f32_e32 v12, v150, v166
	v_fmac_f32_e32 v13, v154, v166
	v_fmac_f32_e32 v10, v158, v166
	v_fmac_f32_e32 v11, v162, v166
	v_fmac_f32_e32 v24, v103, v167
	v_fmac_f32_e32 v25, v107, v167
	v_fmac_f32_e32 v22, v111, v167
	v_fmac_f32_e32 v23, v115, v167
	v_fmac_f32_e32 v20, v119, v167
	v_fmac_f32_e32 v21, v123, v167
	v_fmac_f32_e32 v18, v127, v167
	v_fmac_f32_e32 v19, v131, v167
	v_fmac_f32_e32 v16, v135, v167
	v_fmac_f32_e32 v17, v139, v167
	v_fmac_f32_e32 v14, v143, v167
	v_fmac_f32_e32 v15, v147, v167
	v_fmac_f32_e32 v12, v151, v167
	v_fmac_f32_e32 v13, v155, v167
	v_fmac_f32_e32 v10, v159, v167
	v_fmac_f32_e32 v11, v163, v167
	global_load_dwordx4 v[100:103], v[168:169], off offset:80
	global_load_dwordx4 v[104:107], v[168:169], off offset:336
	global_load_dwordx4 v[108:111], v[168:169], off offset:592
	global_load_dwordx4 v[112:115], v[168:169], off offset:848
	global_load_dwordx4 v[116:119], v[168:169], off offset:1104
	global_load_dwordx4 v[120:123], v[168:169], off offset:1360
	global_load_dwordx4 v[124:127], v[168:169], off offset:1616
	global_load_dwordx4 v[128:131], v[168:169], off offset:1872
	global_load_dwordx4 v[132:135], v[168:169], off offset:2128
	global_load_dwordx4 v[136:139], v[168:169], off offset:2384
	global_load_dwordx4 v[140:143], v[168:169], off offset:2640
	global_load_dwordx4 v[144:147], v[168:169], off offset:2896
	global_load_dwordx4 v[148:151], v[168:169], off offset:3152
	global_load_dwordx4 v[152:155], v[168:169], off offset:3408
	global_load_dwordx4 v[156:159], v[168:169], off offset:3664
	global_load_dwordx4 v[160:163], v[168:169], off offset:3920
	global_load_dword v164, v[170:171], off offset:-4096
	global_load_dword v165, v[170:171], off
	global_load_dword v166, v[172:173], off offset:-4096
	global_load_dword v167, v[172:173], off
	v_lshl_add_u64 v[170:171], v[170:171], 0, s[4:5]
	v_lshl_add_u64 v[172:173], v[172:173], 0, s[4:5]
	s_waitcnt vmcnt(20)
	v_fmac_f32_e32 v24, v32, v96
	v_fmac_f32_e32 v25, v36, v96
	v_fmac_f32_e32 v22, v40, v96
	v_fmac_f32_e32 v23, v44, v96
	v_fmac_f32_e32 v20, v48, v96
	v_fmac_f32_e32 v21, v52, v96
	v_fmac_f32_e32 v18, v56, v96
	v_fmac_f32_e32 v19, v60, v96
	v_fmac_f32_e32 v16, v64, v96
	v_fmac_f32_e32 v17, v68, v96
	v_fmac_f32_e32 v14, v72, v96
	v_fmac_f32_e32 v15, v76, v96
	v_fmac_f32_e32 v12, v80, v96
	v_fmac_f32_e32 v13, v84, v96
	v_fmac_f32_e32 v10, v88, v96
	v_fmac_f32_e32 v11, v92, v96
	v_fmac_f32_e32 v24, v33, v97
	v_fmac_f32_e32 v25, v37, v97
	v_fmac_f32_e32 v22, v41, v97
	v_fmac_f32_e32 v23, v45, v97
	v_fmac_f32_e32 v20, v49, v97
	v_fmac_f32_e32 v21, v53, v97
	v_fmac_f32_e32 v18, v57, v97
	v_fmac_f32_e32 v19, v61, v97
	v_fmac_f32_e32 v16, v65, v97
	v_fmac_f32_e32 v17, v69, v97
	v_fmac_f32_e32 v14, v73, v97
	v_fmac_f32_e32 v15, v77, v97
	v_fmac_f32_e32 v12, v81, v97
	v_fmac_f32_e32 v13, v85, v97
	v_fmac_f32_e32 v10, v89, v97
	v_fmac_f32_e32 v11, v93, v97
	v_fmac_f32_e32 v24, v34, v98
	v_fmac_f32_e32 v25, v38, v98
	v_fmac_f32_e32 v22, v42, v98
	v_fmac_f32_e32 v23, v46, v98
	v_fmac_f32_e32 v20, v50, v98
	v_fmac_f32_e32 v21, v54, v98
	v_fmac_f32_e32 v18, v58, v98
	v_fmac_f32_e32 v19, v62, v98
	v_fmac_f32_e32 v16, v66, v98
	v_fmac_f32_e32 v17, v70, v98
	v_fmac_f32_e32 v14, v74, v98
	v_fmac_f32_e32 v15, v78, v98
	v_fmac_f32_e32 v12, v82, v98
	v_fmac_f32_e32 v13, v86, v98
	v_fmac_f32_e32 v10, v90, v98
	v_fmac_f32_e32 v11, v94, v98
	v_fmac_f32_e32 v24, v35, v99
	v_fmac_f32_e32 v25, v39, v99
	v_fmac_f32_e32 v22, v43, v99
	v_fmac_f32_e32 v23, v47, v99
	v_fmac_f32_e32 v20, v51, v99
	v_fmac_f32_e32 v21, v55, v99
	v_fmac_f32_e32 v18, v59, v99
	v_fmac_f32_e32 v19, v63, v99
	v_fmac_f32_e32 v16, v67, v99
	v_fmac_f32_e32 v17, v71, v99
	v_fmac_f32_e32 v14, v75, v99
	v_fmac_f32_e32 v15, v79, v99
	v_fmac_f32_e32 v12, v83, v99
	v_fmac_f32_e32 v13, v87, v99
	v_fmac_f32_e32 v10, v91, v99
	v_fmac_f32_e32 v11, v95, v99
	global_load_dwordx4 v[32:35], v[168:169], off offset:96
	global_load_dwordx4 v[36:39], v[168:169], off offset:352
	global_load_dwordx4 v[40:43], v[168:169], off offset:608
	global_load_dwordx4 v[44:47], v[168:169], off offset:864
	global_load_dwordx4 v[48:51], v[168:169], off offset:1120
	global_load_dwordx4 v[52:55], v[168:169], off offset:1376
	global_load_dwordx4 v[56:59], v[168:169], off offset:1632
	global_load_dwordx4 v[60:63], v[168:169], off offset:1888
	global_load_dwordx4 v[64:67], v[168:169], off offset:2144
	global_load_dwordx4 v[68:71], v[168:169], off offset:2400
	global_load_dwordx4 v[72:75], v[168:169], off offset:2656
	global_load_dwordx4 v[76:79], v[168:169], off offset:2912
	global_load_dwordx4 v[80:83], v[168:169], off offset:3168
	global_load_dwordx4 v[84:87], v[168:169], off offset:3424
	global_load_dwordx4 v[88:91], v[168:169], off offset:3680
	global_load_dwordx4 v[92:95], v[168:169], off offset:3936
	global_load_dword v96, v[170:171], off offset:-4096
	global_load_dword v97, v[170:171], off
	global_load_dword v98, v[172:173], off offset:-4096
	global_load_dword v99, v[172:173], off
	v_lshl_add_u64 v[170:171], v[170:171], 0, s[4:5]
	v_lshl_add_u64 v[172:173], v[172:173], 0, s[4:5]
	s_waitcnt vmcnt(20)
; __device__ __forceinline__ void prep_phase(const Params& p, unsigned char* smem) {
;     ...
;     for (size_t it = gtid; it < (size_t)2 * 128 * 1024; it += nth) {
;         const int j = (int)(it >> 17), rem = (int)(it & 131071), kg = rem >> 10, n = rem & 1023, h = kg >> 3, c0 = (kg & 7) * 16;
;         const float* uv = p.in[27] + (size_t)((j * 16 + h) * 128 + c0) * 64;
;         const float* wo = p.in[31] + (size_t)j * 1048576 + (size_t)(h * 64) * 1024 + n;
;         float acc[16];
; #pragma unroll
;         for (int i = 0; i < 16; ++i) acc[i] = 0.f;
;         for (int v = 0; v < 64; ++v) {
;             const float wv = wo[(size_t)v * 1024];
; #pragma unroll
;             for (int i = 0; i < 16; ++i) acc[i] += uv[i * 64 + v] * wv;
	v_fmac_f32_e32 v24, v100, v164
	v_fmac_f32_e32 v25, v104, v164
	v_fmac_f32_e32 v22, v108, v164
	v_fmac_f32_e32 v23, v112, v164
	v_fmac_f32_e32 v20, v116, v164
	v_fmac_f32_e32 v21, v120, v164
	v_fmac_f32_e32 v18, v124, v164
	v_fmac_f32_e32 v19, v128, v164
	v_fmac_f32_e32 v16, v132, v164
	v_fmac_f32_e32 v17, v136, v164
	v_fmac_f32_e32 v14, v140, v164
	v_fmac_f32_e32 v15, v144, v164
	v_fmac_f32_e32 v12, v148, v164
	v_fmac_f32_e32 v13, v152, v164
	v_fmac_f32_e32 v10, v156, v164
	v_fmac_f32_e32 v11, v160, v164
	v_fmac_f32_e32 v24, v101, v165
	v_fmac_f32_e32 v25, v105, v165
	v_fmac_f32_e32 v22, v109, v165
	v_fmac_f32_e32 v23, v113, v165
	v_fmac_f32_e32 v20, v117, v165
	v_fmac_f32_e32 v21, v121, v165
	v_fmac_f32_e32 v18, v125, v165
	v_fmac_f32_e32 v19, v129, v165
	v_fmac_f32_e32 v16, v133, v165
	v_fmac_f32_e32 v17, v137, v165
	v_fmac_f32_e32 v14, v141, v165
	v_fmac_f32_e32 v15, v145, v165
	v_fmac_f32_e32 v12, v149, v165
	v_fmac_f32_e32 v13, v153, v165
	v_fmac_f32_e32 v10, v157, v165
	v_fmac_f32_e32 v11, v161, v165
	v_fmac_f32_e32 v24, v102, v166
	v_fmac_f32_e32 v25, v106, v166
	v_fmac_f32_e32 v22, v110, v166
	v_fmac_f32_e32 v23, v114, v166
	v_fmac_f32_e32 v20, v118, v166
	v_fmac_f32_e32 v21, v122, v166
	v_fmac_f32_e32 v18, v126, v166
	v_fmac_f32_e32 v19, v130, v166
	v_fmac_f32_e32 v16, v134, v166
	v_fmac_f32_e32 v17, v138, v166
	v_fmac_f32_e32 v14, v142, v166
	v_fmac_f32_e32 v15, v146, v166
	v_fmac_f32_e32 v12, v150, v166
	v_fmac_f32_e32 v13, v154, v166
	v_fmac_f32_e32 v10, v158, v166
	v_fmac_f32_e32 v11, v162, v166
	v_fmac_f32_e32 v24, v103, v167
	v_fmac_f32_e32 v25, v107, v167
	v_fmac_f32_e32 v22, v111, v167
	v_fmac_f32_e32 v23, v115, v167
	v_fmac_f32_e32 v20, v119, v167
	v_fmac_f32_e32 v21, v123, v167
	v_fmac_f32_e32 v18, v127, v167
	v_fmac_f32_e32 v19, v131, v167
	v_fmac_f32_e32 v16, v135, v167
	v_fmac_f32_e32 v17, v139, v167
	v_fmac_f32_e32 v14, v143, v167
	v_fmac_f32_e32 v15, v147, v167
	v_fmac_f32_e32 v12, v151, v167
	v_fmac_f32_e32 v13, v155, v167
	v_fmac_f32_e32 v10, v159, v167
	v_fmac_f32_e32 v11, v163, v167
	global_load_dwordx4 v[100:103], v[168:169], off offset:112
	global_load_dwordx4 v[104:107], v[168:169], off offset:368
	global_load_dwordx4 v[108:111], v[168:169], off offset:624
	global_load_dwordx4 v[112:115], v[168:169], off offset:880
	global_load_dwordx4 v[116:119], v[168:169], off offset:1136
	global_load_dwordx4 v[120:123], v[168:169], off offset:1392
	global_load_dwordx4 v[124:127], v[168:169], off offset:1648
	global_load_dwordx4 v[128:131], v[168:169], off offset:1904
	global_load_dwordx4 v[132:135], v[168:169], off offset:2160
	global_load_dwordx4 v[136:139], v[168:169], off offset:2416
	global_load_dwordx4 v[140:143], v[168:169], off offset:2672
	global_load_dwordx4 v[144:147], v[168:169], off offset:2928
	global_load_dwordx4 v[148:151], v[168:169], off offset:3184
	global_load_dwordx4 v[152:155], v[168:169], off offset:3440
	global_load_dwordx4 v[156:159], v[168:169], off offset:3696
	global_load_dwordx4 v[160:163], v[168:169], off offset:3952
	global_load_dword v164, v[170:171], off offset:-4096
	global_load_dword v165, v[170:171], off
	global_load_dword v166, v[172:173], off offset:-4096
	global_load_dword v167, v[172:173], off
	v_lshl_add_u64 v[170:171], v[170:171], 0, s[4:5]
	v_lshl_add_u64 v[172:173], v[172:173], 0, s[4:5]
	s_waitcnt vmcnt(20)
	v_fmac_f32_e32 v24, v32, v96
	v_fmac_f32_e32 v25, v36, v96
	v_fmac_f32_e32 v22, v40, v96
	v_fmac_f32_e32 v23, v44, v96
	v_fmac_f32_e32 v20, v48, v96
	v_fmac_f32_e32 v21, v52, v96
	v_fmac_f32_e32 v18, v56, v96
	v_fmac_f32_e32 v19, v60, v96
	v_fmac_f32_e32 v16, v64, v96
	v_fmac_f32_e32 v17, v68, v96
	v_fmac_f32_e32 v14, v72, v96
	v_fmac_f32_e32 v15, v76, v96
	v_fmac_f32_e32 v12, v80, v96
	v_fmac_f32_e32 v13, v84, v96
	v_fmac_f32_e32 v10, v88, v96
	v_fmac_f32_e32 v11, v92, v96
	v_fmac_f32_e32 v24, v33, v97
	v_fmac_f32_e32 v25, v37, v97
	v_fmac_f32_e32 v22, v41, v97
	v_fmac_f32_e32 v23, v45, v97
	v_fmac_f32_e32 v20, v49, v97
	v_fmac_f32_e32 v21, v53, v97
	v_fmac_f32_e32 v18, v57, v97
	v_fmac_f32_e32 v19, v61, v97
	v_fmac_f32_e32 v16, v65, v97
	v_fmac_f32_e32 v17, v69, v97
	v_fmac_f32_e32 v14, v73, v97
	v_fmac_f32_e32 v15, v77, v97
	v_fmac_f32_e32 v12, v81, v97
	v_fmac_f32_e32 v13, v85, v97
	v_fmac_f32_e32 v10, v89, v97
	v_fmac_f32_e32 v11, v93, v97
	v_fmac_f32_e32 v24, v34, v98
	v_fmac_f32_e32 v25, v38, v98
	v_fmac_f32_e32 v22, v42, v98
	v_fmac_f32_e32 v23, v46, v98
	v_fmac_f32_e32 v20, v50, v98
	v_fmac_f32_e32 v21, v54, v98
	v_fmac_f32_e32 v18, v58, v98
	v_fmac_f32_e32 v19, v62, v98
	v_fmac_f32_e32 v16, v66, v98
	v_fmac_f32_e32 v17, v70, v98
	v_fmac_f32_e32 v14, v74, v98
	v_fmac_f32_e32 v15, v78, v98
	v_fmac_f32_e32 v12, v82, v98
	v_fmac_f32_e32 v13, v86, v98
	v_fmac_f32_e32 v10, v90, v98
	v_fmac_f32_e32 v11, v94, v98
	v_fmac_f32_e32 v24, v35, v99
	v_fmac_f32_e32 v25, v39, v99
	v_fmac_f32_e32 v22, v43, v99
	v_fmac_f32_e32 v23, v47, v99
	v_fmac_f32_e32 v20, v51, v99
	v_fmac_f32_e32 v21, v55, v99
	v_fmac_f32_e32 v18, v59, v99
	v_fmac_f32_e32 v19, v63, v99
	v_fmac_f32_e32 v16, v67, v99
	v_fmac_f32_e32 v17, v71, v99
	v_fmac_f32_e32 v14, v75, v99
	v_fmac_f32_e32 v15, v79, v99
	v_fmac_f32_e32 v12, v83, v99
	v_fmac_f32_e32 v13, v87, v99
	v_fmac_f32_e32 v10, v91, v99
	v_fmac_f32_e32 v11, v95, v99
	global_load_dwordx4 v[32:35], v[168:169], off offset:128
	global_load_dwordx4 v[36:39], v[168:169], off offset:384
	global_load_dwordx4 v[40:43], v[168:169], off offset:640
	global_load_dwordx4 v[44:47], v[168:169], off offset:896
	global_load_dwordx4 v[48:51], v[168:169], off offset:1152
	global_load_dwordx4 v[52:55], v[168:169], off offset:1408
	global_load_dwordx4 v[56:59], v[168:169], off offset:1664
	global_load_dwordx4 v[60:63], v[168:169], off offset:1920
	global_load_dwordx4 v[64:67], v[168:169], off offset:2176
	global_load_dwordx4 v[68:71], v[168:169], off offset:2432
	global_load_dwordx4 v[72:75], v[168:169], off offset:2688
	global_load_dwordx4 v[76:79], v[168:169], off offset:2944
	global_load_dwordx4 v[80:83], v[168:169], off offset:3200
	global_load_dwordx4 v[84:87], v[168:169], off offset:3456
	global_load_dwordx4 v[88:91], v[168:169], off offset:3712
	global_load_dwordx4 v[92:95], v[168:169], off offset:3968
	global_load_dword v96, v[170:171], off offset:-4096
	global_load_dword v97, v[170:171], off
	global_load_dword v98, v[172:173], off offset:-4096
	global_load_dword v99, v[172:173], off
	v_lshl_add_u64 v[170:171], v[170:171], 0, s[4:5]
	v_lshl_add_u64 v[172:173], v[172:173], 0, s[4:5]
	s_waitcnt vmcnt(20)
; __device__ __forceinline__ void prep_phase(const Params& p, unsigned char* smem) {
;     ...
;     for (size_t it = gtid; it < (size_t)2 * 128 * 1024; it += nth) {
;         const int j = (int)(it >> 17), rem = (int)(it & 131071), kg = rem >> 10, n = rem & 1023, h = kg >> 3, c0 = (kg & 7) * 16;
;         const float* uv = p.in[27] + (size_t)((j * 16 + h) * 128 + c0) * 64;
;         const float* wo = p.in[31] + (size_t)j * 1048576 + (size_t)(h * 64) * 1024 + n;
;         float acc[16];
; #pragma unroll
;         for (int i = 0; i < 16; ++i) acc[i] = 0.f;
;         for (int v = 0; v < 64; ++v) {
;             const float wv = wo[(size_t)v * 1024];
; #pragma unroll
;             for (int i = 0; i < 16; ++i) acc[i] += uv[i * 64 + v] * wv;
	v_fmac_f32_e32 v24, v100, v164
	v_fmac_f32_e32 v25, v104, v164
	v_fmac_f32_e32 v22, v108, v164
	v_fmac_f32_e32 v23, v112, v164
	v_fmac_f32_e32 v20, v116, v164
	v_fmac_f32_e32 v21, v120, v164
	v_fmac_f32_e32 v18, v124, v164
	v_fmac_f32_e32 v19, v128, v164
	v_fmac_f32_e32 v16, v132, v164
	v_fmac_f32_e32 v17, v136, v164
	v_fmac_f32_e32 v14, v140, v164
	v_fmac_f32_e32 v15, v144, v164
	v_fmac_f32_e32 v12, v148, v164
	v_fmac_f32_e32 v13, v152, v164
	v_fmac_f32_e32 v10, v156, v164
	v_fmac_f32_e32 v11, v160, v164
	v_fmac_f32_e32 v24, v101, v165
	v_fmac_f32_e32 v25, v105, v165
	v_fmac_f32_e32 v22, v109, v165
	v_fmac_f32_e32 v23, v113, v165
	v_fmac_f32_e32 v20, v117, v165
	v_fmac_f32_e32 v21, v121, v165
	v_fmac_f32_e32 v18, v125, v165
	v_fmac_f32_e32 v19, v129, v165
	v_fmac_f32_e32 v16, v133, v165
	v_fmac_f32_e32 v17, v137, v165
	v_fmac_f32_e32 v14, v141, v165
	v_fmac_f32_e32 v15, v145, v165
	v_fmac_f32_e32 v12, v149, v165
	v_fmac_f32_e32 v13, v153, v165
	v_fmac_f32_e32 v10, v157, v165
	v_fmac_f32_e32 v11, v161, v165
	v_fmac_f32_e32 v24, v102, v166
	v_fmac_f32_e32 v25, v106, v166
	v_fmac_f32_e32 v22, v110, v166
	v_fmac_f32_e32 v23, v114, v166
	v_fmac_f32_e32 v20, v118, v166
	v_fmac_f32_e32 v21, v122, v166
	v_fmac_f32_e32 v18, v126, v166
	v_fmac_f32_e32 v19, v130, v166
	v_fmac_f32_e32 v16, v134, v166
	v_fmac_f32_e32 v17, v138, v166
	v_fmac_f32_e32 v14, v142, v166
	v_fmac_f32_e32 v15, v146, v166
	v_fmac_f32_e32 v12, v150, v166
	v_fmac_f32_e32 v13, v154, v166
	v_fmac_f32_e32 v10, v158, v166
	v_fmac_f32_e32 v11, v162, v166
	v_fmac_f32_e32 v24, v103, v167
	v_fmac_f32_e32 v25, v107, v167
	v_fmac_f32_e32 v22, v111, v167
	v_fmac_f32_e32 v23, v115, v167
	v_fmac_f32_e32 v20, v119, v167
	v_fmac_f32_e32 v21, v123, v167
	v_fmac_f32_e32 v18, v127, v167
	v_fmac_f32_e32 v19, v131, v167
	v_fmac_f32_e32 v16, v135, v167
	v_fmac_f32_e32 v17, v139, v167
	v_fmac_f32_e32 v14, v143, v167
	v_fmac_f32_e32 v15, v147, v167
	v_fmac_f32_e32 v12, v151, v167
	v_fmac_f32_e32 v13, v155, v167
	v_fmac_f32_e32 v10, v159, v167
	v_fmac_f32_e32 v11, v163, v167
	global_load_dwordx4 v[100:103], v[168:169], off offset:144
	global_load_dwordx4 v[104:107], v[168:169], off offset:400
	global_load_dwordx4 v[108:111], v[168:169], off offset:656
	global_load_dwordx4 v[112:115], v[168:169], off offset:912
	global_load_dwordx4 v[116:119], v[168:169], off offset:1168
	global_load_dwordx4 v[120:123], v[168:169], off offset:1424
	global_load_dwordx4 v[124:127], v[168:169], off offset:1680
	global_load_dwordx4 v[128:131], v[168:169], off offset:1936
	global_load_dwordx4 v[132:135], v[168:169], off offset:2192
	global_load_dwordx4 v[136:139], v[168:169], off offset:2448
	global_load_dwordx4 v[140:143], v[168:169], off offset:2704
	global_load_dwordx4 v[144:147], v[168:169], off offset:2960
	global_load_dwordx4 v[148:151], v[168:169], off offset:3216
	global_load_dwordx4 v[152:155], v[168:169], off offset:3472
	global_load_dwordx4 v[156:159], v[168:169], off offset:3728
	global_load_dwordx4 v[160:163], v[168:169], off offset:3984
	global_load_dword v164, v[170:171], off offset:-4096
	global_load_dword v165, v[170:171], off
	global_load_dword v166, v[172:173], off offset:-4096
	global_load_dword v167, v[172:173], off
	v_lshl_add_u64 v[170:171], v[170:171], 0, s[4:5]
	v_lshl_add_u64 v[172:173], v[172:173], 0, s[4:5]
	s_waitcnt vmcnt(20)
	v_fmac_f32_e32 v24, v32, v96
	v_fmac_f32_e32 v25, v36, v96
	v_fmac_f32_e32 v22, v40, v96
	v_fmac_f32_e32 v23, v44, v96
	v_fmac_f32_e32 v20, v48, v96
	v_fmac_f32_e32 v21, v52, v96
	v_fmac_f32_e32 v18, v56, v96
	v_fmac_f32_e32 v19, v60, v96
	v_fmac_f32_e32 v16, v64, v96
	v_fmac_f32_e32 v17, v68, v96
	v_fmac_f32_e32 v14, v72, v96
	v_fmac_f32_e32 v15, v76, v96
	v_fmac_f32_e32 v12, v80, v96
	v_fmac_f32_e32 v13, v84, v96
	v_fmac_f32_e32 v10, v88, v96
	v_fmac_f32_e32 v11, v92, v96
	v_fmac_f32_e32 v24, v33, v97
	v_fmac_f32_e32 v25, v37, v97
	v_fmac_f32_e32 v22, v41, v97
	v_fmac_f32_e32 v23, v45, v97
	v_fmac_f32_e32 v20, v49, v97
	v_fmac_f32_e32 v21, v53, v97
	v_fmac_f32_e32 v18, v57, v97
	v_fmac_f32_e32 v19, v61, v97
	v_fmac_f32_e32 v16, v65, v97
	v_fmac_f32_e32 v17, v69, v97
	v_fmac_f32_e32 v14, v73, v97
	v_fmac_f32_e32 v15, v77, v97
	v_fmac_f32_e32 v12, v81, v97
	v_fmac_f32_e32 v13, v85, v97
	v_fmac_f32_e32 v10, v89, v97
	v_fmac_f32_e32 v11, v93, v97
	v_fmac_f32_e32 v24, v34, v98
	v_fmac_f32_e32 v25, v38, v98
	v_fmac_f32_e32 v22, v42, v98
	v_fmac_f32_e32 v23, v46, v98
	v_fmac_f32_e32 v20, v50, v98
	v_fmac_f32_e32 v21, v54, v98
	v_fmac_f32_e32 v18, v58, v98
	v_fmac_f32_e32 v19, v62, v98
	v_fmac_f32_e32 v16, v66, v98
	v_fmac_f32_e32 v17, v70, v98
	v_fmac_f32_e32 v14, v74, v98
	v_fmac_f32_e32 v15, v78, v98
	v_fmac_f32_e32 v12, v82, v98
	v_fmac_f32_e32 v13, v86, v98
	v_fmac_f32_e32 v10, v90, v98
	v_fmac_f32_e32 v11, v94, v98
	v_fmac_f32_e32 v24, v35, v99
	v_fmac_f32_e32 v25, v39, v99
	v_fmac_f32_e32 v22, v43, v99
	v_fmac_f32_e32 v23, v47, v99
	v_fmac_f32_e32 v20, v51, v99
	v_fmac_f32_e32 v21, v55, v99
	v_fmac_f32_e32 v18, v59, v99
	v_fmac_f32_e32 v19, v63, v99
	v_fmac_f32_e32 v16, v67, v99
	v_fmac_f32_e32 v17, v71, v99
	v_fmac_f32_e32 v14, v75, v99
	v_fmac_f32_e32 v15, v79, v99
	v_fmac_f32_e32 v12, v83, v99
	v_fmac_f32_e32 v13, v87, v99
	v_fmac_f32_e32 v10, v91, v99
	v_fmac_f32_e32 v11, v95, v99
	global_load_dwordx4 v[32:35], v[168:169], off offset:160
	global_load_dwordx4 v[36:39], v[168:169], off offset:416
	global_load_dwordx4 v[40:43], v[168:169], off offset:672
	global_load_dwordx4 v[44:47], v[168:169], off offset:928
	global_load_dwordx4 v[48:51], v[168:169], off offset:1184
	global_load_dwordx4 v[52:55], v[168:169], off offset:1440
	global_load_dwordx4 v[56:59], v[168:169], off offset:1696
	global_load_dwordx4 v[60:63], v[168:169], off offset:1952
	global_load_dwordx4 v[64:67], v[168:169], off offset:2208
	global_load_dwordx4 v[68:71], v[168:169], off offset:2464
	global_load_dwordx4 v[72:75], v[168:169], off offset:2720
	global_load_dwordx4 v[76:79], v[168:169], off offset:2976
	global_load_dwordx4 v[80:83], v[168:169], off offset:3232
	global_load_dwordx4 v[84:87], v[168:169], off offset:3488
	global_load_dwordx4 v[88:91], v[168:169], off offset:3744
	global_load_dwordx4 v[92:95], v[168:169], off offset:4000
	global_load_dword v96, v[170:171], off offset:-4096
	global_load_dword v97, v[170:171], off
	global_load_dword v98, v[172:173], off offset:-4096
	global_load_dword v99, v[172:173], off
	v_lshl_add_u64 v[170:171], v[170:171], 0, s[4:5]
	v_lshl_add_u64 v[172:173], v[172:173], 0, s[4:5]
	s_waitcnt vmcnt(20)
; __device__ __forceinline__ void prep_phase(const Params& p, unsigned char* smem) {
;     ...
;     for (size_t it = gtid; it < (size_t)2 * 128 * 1024; it += nth) {
;         const int j = (int)(it >> 17), rem = (int)(it & 131071), kg = rem >> 10, n = rem & 1023, h = kg >> 3, c0 = (kg & 7) * 16;
;         const float* uv = p.in[27] + (size_t)((j * 16 + h) * 128 + c0) * 64;
;         const float* wo = p.in[31] + (size_t)j * 1048576 + (size_t)(h * 64) * 1024 + n;
;         float acc[16];
; #pragma unroll
;         for (int i = 0; i < 16; ++i) acc[i] = 0.f;
;         for (int v = 0; v < 64; ++v) {
;             const float wv = wo[(size_t)v * 1024];
; #pragma unroll
;             for (int i = 0; i < 16; ++i) acc[i] += uv[i * 64 + v] * wv;
	v_fmac_f32_e32 v24, v100, v164
	v_fmac_f32_e32 v25, v104, v164
	v_fmac_f32_e32 v22, v108, v164
	v_fmac_f32_e32 v23, v112, v164
	v_fmac_f32_e32 v20, v116, v164
	v_fmac_f32_e32 v21, v120, v164
	v_fmac_f32_e32 v18, v124, v164
	v_fmac_f32_e32 v19, v128, v164
	v_fmac_f32_e32 v16, v132, v164
	v_fmac_f32_e32 v17, v136, v164
	v_fmac_f32_e32 v14, v140, v164
	v_fmac_f32_e32 v15, v144, v164
	v_fmac_f32_e32 v12, v148, v164
	v_fmac_f32_e32 v13, v152, v164
	v_fmac_f32_e32 v10, v156, v164
	v_fmac_f32_e32 v11, v160, v164
	v_fmac_f32_e32 v24, v101, v165
	v_fmac_f32_e32 v25, v105, v165
	v_fmac_f32_e32 v22, v109, v165
	v_fmac_f32_e32 v23, v113, v165
	v_fmac_f32_e32 v20, v117, v165
	v_fmac_f32_e32 v21, v121, v165
	v_fmac_f32_e32 v18, v125, v165
	v_fmac_f32_e32 v19, v129, v165
	v_fmac_f32_e32 v16, v133, v165
	v_fmac_f32_e32 v17, v137, v165
	v_fmac_f32_e32 v14, v141, v165
	v_fmac_f32_e32 v15, v145, v165
	v_fmac_f32_e32 v12, v149, v165
	v_fmac_f32_e32 v13, v153, v165
	v_fmac_f32_e32 v10, v157, v165
	v_fmac_f32_e32 v11, v161, v165
	v_fmac_f32_e32 v24, v102, v166
	v_fmac_f32_e32 v25, v106, v166
	v_fmac_f32_e32 v22, v110, v166
	v_fmac_f32_e32 v23, v114, v166
	v_fmac_f32_e32 v20, v118, v166
	v_fmac_f32_e32 v21, v122, v166
	v_fmac_f32_e32 v18, v126, v166
	v_fmac_f32_e32 v19, v130, v166
	v_fmac_f32_e32 v16, v134, v166
	v_fmac_f32_e32 v17, v138, v166
	v_fmac_f32_e32 v14, v142, v166
	v_fmac_f32_e32 v15, v146, v166
	v_fmac_f32_e32 v12, v150, v166
	v_fmac_f32_e32 v13, v154, v166
	v_fmac_f32_e32 v10, v158, v166
	v_fmac_f32_e32 v11, v162, v166
	v_fmac_f32_e32 v24, v103, v167
	v_fmac_f32_e32 v25, v107, v167
	v_fmac_f32_e32 v22, v111, v167
	v_fmac_f32_e32 v23, v115, v167
	v_fmac_f32_e32 v20, v119, v167
	v_fmac_f32_e32 v21, v123, v167
	v_fmac_f32_e32 v18, v127, v167
	v_fmac_f32_e32 v19, v131, v167
	v_fmac_f32_e32 v16, v135, v167
	v_fmac_f32_e32 v17, v139, v167
	v_fmac_f32_e32 v14, v143, v167
	v_fmac_f32_e32 v15, v147, v167
	v_fmac_f32_e32 v12, v151, v167
	v_fmac_f32_e32 v13, v155, v167
	v_fmac_f32_e32 v10, v159, v167
	v_fmac_f32_e32 v11, v163, v167
	global_load_dwordx4 v[100:103], v[168:169], off offset:176
	global_load_dwordx4 v[104:107], v[168:169], off offset:432
	global_load_dwordx4 v[108:111], v[168:169], off offset:688
	global_load_dwordx4 v[112:115], v[168:169], off offset:944
	global_load_dwordx4 v[116:119], v[168:169], off offset:1200
	global_load_dwordx4 v[120:123], v[168:169], off offset:1456
	global_load_dwordx4 v[124:127], v[168:169], off offset:1712
	global_load_dwordx4 v[128:131], v[168:169], off offset:1968
	global_load_dwordx4 v[132:135], v[168:169], off offset:2224
	global_load_dwordx4 v[136:139], v[168:169], off offset:2480
	global_load_dwordx4 v[140:143], v[168:169], off offset:2736
	global_load_dwordx4 v[144:147], v[168:169], off offset:2992
	global_load_dwordx4 v[148:151], v[168:169], off offset:3248
	global_load_dwordx4 v[152:155], v[168:169], off offset:3504
	global_load_dwordx4 v[156:159], v[168:169], off offset:3760
	global_load_dwordx4 v[160:163], v[168:169], off offset:4016
	global_load_dword v164, v[170:171], off offset:-4096
	global_load_dword v165, v[170:171], off
	global_load_dword v166, v[172:173], off offset:-4096
	global_load_dword v167, v[172:173], off
	v_lshl_add_u64 v[170:171], v[170:171], 0, s[4:5]
	v_lshl_add_u64 v[172:173], v[172:173], 0, s[4:5]
	s_waitcnt vmcnt(20)
	v_fmac_f32_e32 v24, v32, v96
	v_fmac_f32_e32 v25, v36, v96
	v_fmac_f32_e32 v22, v40, v96
	v_fmac_f32_e32 v23, v44, v96
	v_fmac_f32_e32 v20, v48, v96
	v_fmac_f32_e32 v21, v52, v96
	v_fmac_f32_e32 v18, v56, v96
	v_fmac_f32_e32 v19, v60, v96
	v_fmac_f32_e32 v16, v64, v96
	v_fmac_f32_e32 v17, v68, v96
	v_fmac_f32_e32 v14, v72, v96
	v_fmac_f32_e32 v15, v76, v96
	v_fmac_f32_e32 v12, v80, v96
	v_fmac_f32_e32 v13, v84, v96
	v_fmac_f32_e32 v10, v88, v96
	v_fmac_f32_e32 v11, v92, v96
	v_fmac_f32_e32 v24, v33, v97
	v_fmac_f32_e32 v25, v37, v97
	v_fmac_f32_e32 v22, v41, v97
	v_fmac_f32_e32 v23, v45, v97
	v_fmac_f32_e32 v20, v49, v97
	v_fmac_f32_e32 v21, v53, v97
	v_fmac_f32_e32 v18, v57, v97
	v_fmac_f32_e32 v19, v61, v97
	v_fmac_f32_e32 v16, v65, v97
	v_fmac_f32_e32 v17, v69, v97
	v_fmac_f32_e32 v14, v73, v97
	v_fmac_f32_e32 v15, v77, v97
	v_fmac_f32_e32 v12, v81, v97
	v_fmac_f32_e32 v13, v85, v97
	v_fmac_f32_e32 v10, v89, v97
	v_fmac_f32_e32 v11, v93, v97
	v_fmac_f32_e32 v24, v34, v98
	v_fmac_f32_e32 v25, v38, v98
	v_fmac_f32_e32 v22, v42, v98
	v_fmac_f32_e32 v23, v46, v98
	v_fmac_f32_e32 v20, v50, v98
	v_fmac_f32_e32 v21, v54, v98
	v_fmac_f32_e32 v18, v58, v98
	v_fmac_f32_e32 v19, v62, v98
	v_fmac_f32_e32 v16, v66, v98
	v_fmac_f32_e32 v17, v70, v98
	v_fmac_f32_e32 v14, v74, v98
	v_fmac_f32_e32 v15, v78, v98
	v_fmac_f32_e32 v12, v82, v98
	v_fmac_f32_e32 v13, v86, v98
	v_fmac_f32_e32 v10, v90, v98
	v_fmac_f32_e32 v11, v94, v98
	v_fmac_f32_e32 v24, v35, v99
	v_fmac_f32_e32 v25, v39, v99
	v_fmac_f32_e32 v22, v43, v99
	v_fmac_f32_e32 v23, v47, v99
	v_fmac_f32_e32 v20, v51, v99
	v_fmac_f32_e32 v21, v55, v99
	v_fmac_f32_e32 v18, v59, v99
	v_fmac_f32_e32 v19, v63, v99
	v_fmac_f32_e32 v16, v67, v99
	v_fmac_f32_e32 v17, v71, v99
	v_fmac_f32_e32 v14, v75, v99
	v_fmac_f32_e32 v15, v79, v99
	v_fmac_f32_e32 v12, v83, v99
	v_fmac_f32_e32 v13, v87, v99
	v_fmac_f32_e32 v10, v91, v99
	v_fmac_f32_e32 v11, v95, v99
	global_load_dwordx4 v[32:35], v[168:169], off offset:192
	global_load_dwordx4 v[36:39], v[168:169], off offset:448
	global_load_dwordx4 v[40:43], v[168:169], off offset:704
	global_load_dwordx4 v[44:47], v[168:169], off offset:960
	global_load_dwordx4 v[48:51], v[168:169], off offset:1216
	global_load_dwordx4 v[52:55], v[168:169], off offset:1472
	global_load_dwordx4 v[56:59], v[168:169], off offset:1728
	global_load_dwordx4 v[60:63], v[168:169], off offset:1984
	global_load_dwordx4 v[64:67], v[168:169], off offset:2240
	global_load_dwordx4 v[68:71], v[168:169], off offset:2496
	global_load_dwordx4 v[72:75], v[168:169], off offset:2752
	global_load_dwordx4 v[76:79], v[168:169], off offset:3008
	global_load_dwordx4 v[80:83], v[168:169], off offset:3264
	global_load_dwordx4 v[84:87], v[168:169], off offset:3520
	global_load_dwordx4 v[88:91], v[168:169], off offset:3776
	global_load_dwordx4 v[92:95], v[168:169], off offset:4032
	global_load_dword v96, v[170:171], off offset:-4096
	global_load_dword v97, v[170:171], off
	global_load_dword v98, v[172:173], off offset:-4096
	global_load_dword v99, v[172:173], off
	v_lshl_add_u64 v[170:171], v[170:171], 0, s[4:5]
	v_lshl_add_u64 v[172:173], v[172:173], 0, s[4:5]
	s_waitcnt vmcnt(20)
; __device__ __forceinline__ void prep_phase(const Params& p, unsigned char* smem) {
;     ...
;     for (size_t it = gtid; it < (size_t)2 * 128 * 1024; it += nth) {
;         const int j = (int)(it >> 17), rem = (int)(it & 131071), kg = rem >> 10, n = rem & 1023, h = kg >> 3, c0 = (kg & 7) * 16;
;         const float* uv = p.in[27] + (size_t)((j * 16 + h) * 128 + c0) * 64;
;         const float* wo = p.in[31] + (size_t)j * 1048576 + (size_t)(h * 64) * 1024 + n;
;         float acc[16];
; #pragma unroll
;         for (int i = 0; i < 16; ++i) acc[i] = 0.f;
;         for (int v = 0; v < 64; ++v) {
;             const float wv = wo[(size_t)v * 1024];
; #pragma unroll
;             for (int i = 0; i < 16; ++i) acc[i] += uv[i * 64 + v] * wv;
	v_fmac_f32_e32 v24, v100, v164
	v_fmac_f32_e32 v25, v104, v164
	v_fmac_f32_e32 v22, v108, v164
	v_fmac_f32_e32 v23, v112, v164
	v_fmac_f32_e32 v20, v116, v164
	v_fmac_f32_e32 v21, v120, v164
	v_fmac_f32_e32 v18, v124, v164
	v_fmac_f32_e32 v19, v128, v164
	v_fmac_f32_e32 v16, v132, v164
	v_fmac_f32_e32 v17, v136, v164
	v_fmac_f32_e32 v14, v140, v164
	v_fmac_f32_e32 v15, v144, v164
	v_fmac_f32_e32 v12, v148, v164
	v_fmac_f32_e32 v13, v152, v164
	v_fmac_f32_e32 v10, v156, v164
	v_fmac_f32_e32 v11, v160, v164
	v_fmac_f32_e32 v24, v101, v165
	v_fmac_f32_e32 v25, v105, v165
	v_fmac_f32_e32 v22, v109, v165
	v_fmac_f32_e32 v23, v113, v165
	v_fmac_f32_e32 v20, v117, v165
	v_fmac_f32_e32 v21, v121, v165
	v_fmac_f32_e32 v18, v125, v165
	v_fmac_f32_e32 v19, v129, v165
	v_fmac_f32_e32 v16, v133, v165
	v_fmac_f32_e32 v17, v137, v165
	v_fmac_f32_e32 v14, v141, v165
	v_fmac_f32_e32 v15, v145, v165
	v_fmac_f32_e32 v12, v149, v165
	v_fmac_f32_e32 v13, v153, v165
	v_fmac_f32_e32 v10, v157, v165
	v_fmac_f32_e32 v11, v161, v165
	v_fmac_f32_e32 v24, v102, v166
	v_fmac_f32_e32 v25, v106, v166
	v_fmac_f32_e32 v22, v110, v166
	v_fmac_f32_e32 v23, v114, v166
	v_fmac_f32_e32 v20, v118, v166
	v_fmac_f32_e32 v21, v122, v166
	v_fmac_f32_e32 v18, v126, v166
	v_fmac_f32_e32 v19, v130, v166
	v_fmac_f32_e32 v16, v134, v166
	v_fmac_f32_e32 v17, v138, v166
	v_fmac_f32_e32 v14, v142, v166
	v_fmac_f32_e32 v15, v146, v166
	v_fmac_f32_e32 v12, v150, v166
	v_fmac_f32_e32 v13, v154, v166
	v_fmac_f32_e32 v10, v158, v166
	v_fmac_f32_e32 v11, v162, v166
	v_fmac_f32_e32 v24, v103, v167
	v_fmac_f32_e32 v25, v107, v167
	v_fmac_f32_e32 v22, v111, v167
	v_fmac_f32_e32 v23, v115, v167
	v_fmac_f32_e32 v20, v119, v167
	v_fmac_f32_e32 v21, v123, v167
	v_fmac_f32_e32 v18, v127, v167
	v_fmac_f32_e32 v19, v131, v167
	v_fmac_f32_e32 v16, v135, v167
	v_fmac_f32_e32 v17, v139, v167
	v_fmac_f32_e32 v14, v143, v167
	v_fmac_f32_e32 v15, v147, v167
	v_fmac_f32_e32 v12, v151, v167
	v_fmac_f32_e32 v13, v155, v167
	v_fmac_f32_e32 v10, v159, v167
	v_fmac_f32_e32 v11, v163, v167
	global_load_dwordx4 v[100:103], v[168:169], off offset:208
	global_load_dwordx4 v[104:107], v[168:169], off offset:464
	global_load_dwordx4 v[108:111], v[168:169], off offset:720
	global_load_dwordx4 v[112:115], v[168:169], off offset:976
	global_load_dwordx4 v[116:119], v[168:169], off offset:1232
	global_load_dwordx4 v[120:123], v[168:169], off offset:1488
	global_load_dwordx4 v[124:127], v[168:169], off offset:1744
	global_load_dwordx4 v[128:131], v[168:169], off offset:2000
	global_load_dwordx4 v[132:135], v[168:169], off offset:2256
	global_load_dwordx4 v[136:139], v[168:169], off offset:2512
	global_load_dwordx4 v[140:143], v[168:169], off offset:2768
	global_load_dwordx4 v[144:147], v[168:169], off offset:3024
	global_load_dwordx4 v[148:151], v[168:169], off offset:3280
	global_load_dwordx4 v[152:155], v[168:169], off offset:3536
	global_load_dwordx4 v[156:159], v[168:169], off offset:3792
	global_load_dwordx4 v[160:163], v[168:169], off offset:4048
	global_load_dword v164, v[170:171], off offset:-4096
	global_load_dword v165, v[170:171], off
	global_load_dword v166, v[172:173], off offset:-4096
	global_load_dword v167, v[172:173], off
	v_lshl_add_u64 v[170:171], v[170:171], 0, s[4:5]
	v_lshl_add_u64 v[172:173], v[172:173], 0, s[4:5]
	s_waitcnt vmcnt(20)
	v_fmac_f32_e32 v24, v32, v96
	v_fmac_f32_e32 v25, v36, v96
	v_fmac_f32_e32 v22, v40, v96
	v_fmac_f32_e32 v23, v44, v96
	v_fmac_f32_e32 v20, v48, v96
	v_fmac_f32_e32 v21, v52, v96
	v_fmac_f32_e32 v18, v56, v96
	v_fmac_f32_e32 v19, v60, v96
	v_fmac_f32_e32 v16, v64, v96
	v_fmac_f32_e32 v17, v68, v96
	v_fmac_f32_e32 v14, v72, v96
	v_fmac_f32_e32 v15, v76, v96
	v_fmac_f32_e32 v12, v80, v96
	v_fmac_f32_e32 v13, v84, v96
	v_fmac_f32_e32 v10, v88, v96
	v_fmac_f32_e32 v11, v92, v96
	v_fmac_f32_e32 v24, v33, v97
	v_fmac_f32_e32 v25, v37, v97
	v_fmac_f32_e32 v22, v41, v97
	v_fmac_f32_e32 v23, v45, v97
	v_fmac_f32_e32 v20, v49, v97
	v_fmac_f32_e32 v21, v53, v97
	v_fmac_f32_e32 v18, v57, v97
	v_fmac_f32_e32 v19, v61, v97
	v_fmac_f32_e32 v16, v65, v97
	v_fmac_f32_e32 v17, v69, v97
	v_fmac_f32_e32 v14, v73, v97
	v_fmac_f32_e32 v15, v77, v97
	v_fmac_f32_e32 v12, v81, v97
	v_fmac_f32_e32 v13, v85, v97
	v_fmac_f32_e32 v10, v89, v97
	v_fmac_f32_e32 v11, v93, v97
	v_fmac_f32_e32 v24, v34, v98
	v_fmac_f32_e32 v25, v38, v98
	v_fmac_f32_e32 v22, v42, v98
	v_fmac_f32_e32 v23, v46, v98
	v_fmac_f32_e32 v20, v50, v98
	v_fmac_f32_e32 v21, v54, v98
	v_fmac_f32_e32 v18, v58, v98
	v_fmac_f32_e32 v19, v62, v98
	v_fmac_f32_e32 v16, v66, v98
	v_fmac_f32_e32 v17, v70, v98
	v_fmac_f32_e32 v14, v74, v98
	v_fmac_f32_e32 v15, v78, v98
	v_fmac_f32_e32 v12, v82, v98
	v_fmac_f32_e32 v13, v86, v98
	v_fmac_f32_e32 v10, v90, v98
	v_fmac_f32_e32 v11, v94, v98
	v_fmac_f32_e32 v24, v35, v99
	v_fmac_f32_e32 v25, v39, v99
	v_fmac_f32_e32 v22, v43, v99
	v_fmac_f32_e32 v23, v47, v99
	v_fmac_f32_e32 v20, v51, v99
	v_fmac_f32_e32 v21, v55, v99
	v_fmac_f32_e32 v18, v59, v99
	v_fmac_f32_e32 v19, v63, v99
	v_fmac_f32_e32 v16, v67, v99
	v_fmac_f32_e32 v17, v71, v99
	v_fmac_f32_e32 v14, v75, v99
	v_fmac_f32_e32 v15, v79, v99
	v_fmac_f32_e32 v12, v83, v99
	v_fmac_f32_e32 v13, v87, v99
	v_fmac_f32_e32 v10, v91, v99
	v_fmac_f32_e32 v11, v95, v99
	global_load_dwordx4 v[32:35], v[168:169], off offset:224
	global_load_dwordx4 v[36:39], v[168:169], off offset:480
	global_load_dwordx4 v[40:43], v[168:169], off offset:736
	global_load_dwordx4 v[44:47], v[168:169], off offset:992
	global_load_dwordx4 v[48:51], v[168:169], off offset:1248
	global_load_dwordx4 v[52:55], v[168:169], off offset:1504
	global_load_dwordx4 v[56:59], v[168:169], off offset:1760
	global_load_dwordx4 v[60:63], v[168:169], off offset:2016
	global_load_dwordx4 v[64:67], v[168:169], off offset:2272
	global_load_dwordx4 v[68:71], v[168:169], off offset:2528
	global_load_dwordx4 v[72:75], v[168:169], off offset:2784
	global_load_dwordx4 v[76:79], v[168:169], off offset:3040
	global_load_dwordx4 v[80:83], v[168:169], off offset:3296
	global_load_dwordx4 v[84:87], v[168:169], off offset:3552
	global_load_dwordx4 v[88:91], v[168:169], off offset:3808
	global_load_dwordx4 v[92:95], v[168:169], off offset:4064
	global_load_dword v96, v[170:171], off offset:-4096
	global_load_dword v97, v[170:171], off
	global_load_dword v98, v[172:173], off offset:-4096
	global_load_dword v99, v[172:173], off
	v_lshl_add_u64 v[170:171], v[170:171], 0, s[4:5]
	v_lshl_add_u64 v[172:173], v[172:173], 0, s[4:5]
	s_waitcnt vmcnt(20)
; __device__ __forceinline__ void prep_phase(const Params& p, unsigned char* smem) {
;     ...
;     for (size_t it = gtid; it < (size_t)2 * 128 * 1024; it += nth) {
;         const int j = (int)(it >> 17), rem = (int)(it & 131071), kg = rem >> 10, n = rem & 1023, h = kg >> 3, c0 = (kg & 7) * 16;
;         const float* uv = p.in[27] + (size_t)((j * 16 + h) * 128 + c0) * 64;
;         const float* wo = p.in[31] + (size_t)j * 1048576 + (size_t)(h * 64) * 1024 + n;
;         float acc[16];
; #pragma unroll
;         for (int i = 0; i < 16; ++i) acc[i] = 0.f;
;         for (int v = 0; v < 64; ++v) {
;             const float wv = wo[(size_t)v * 1024];
; #pragma unroll
;             for (int i = 0; i < 16; ++i) acc[i] += uv[i * 64 + v] * wv;
	v_fmac_f32_e32 v24, v100, v164
	v_fmac_f32_e32 v25, v104, v164
	v_fmac_f32_e32 v22, v108, v164
	v_fmac_f32_e32 v23, v112, v164
	v_fmac_f32_e32 v20, v116, v164
	v_fmac_f32_e32 v21, v120, v164
	v_fmac_f32_e32 v18, v124, v164
	v_fmac_f32_e32 v19, v128, v164
	v_fmac_f32_e32 v16, v132, v164
	v_fmac_f32_e32 v17, v136, v164
	v_fmac_f32_e32 v14, v140, v164
	v_fmac_f32_e32 v15, v144, v164
	v_fmac_f32_e32 v12, v148, v164
	v_fmac_f32_e32 v13, v152, v164
	v_fmac_f32_e32 v10, v156, v164
	v_fmac_f32_e32 v11, v160, v164
	v_fmac_f32_e32 v24, v101, v165
	v_fmac_f32_e32 v25, v105, v165
	v_fmac_f32_e32 v22, v109, v165
	v_fmac_f32_e32 v23, v113, v165
	v_fmac_f32_e32 v20, v117, v165
	v_fmac_f32_e32 v21, v121, v165
	v_fmac_f32_e32 v18, v125, v165
	v_fmac_f32_e32 v19, v129, v165
	v_fmac_f32_e32 v16, v133, v165
	v_fmac_f32_e32 v17, v137, v165
	v_fmac_f32_e32 v14, v141, v165
	v_fmac_f32_e32 v15, v145, v165
	v_fmac_f32_e32 v12, v149, v165
	v_fmac_f32_e32 v13, v153, v165
	v_fmac_f32_e32 v10, v157, v165
	v_fmac_f32_e32 v11, v161, v165
	v_fmac_f32_e32 v24, v102, v166
	v_fmac_f32_e32 v25, v106, v166
	v_fmac_f32_e32 v22, v110, v166
	v_fmac_f32_e32 v23, v114, v166
	v_fmac_f32_e32 v20, v118, v166
	v_fmac_f32_e32 v21, v122, v166
	v_fmac_f32_e32 v18, v126, v166
	v_fmac_f32_e32 v19, v130, v166
	v_fmac_f32_e32 v16, v134, v166
	v_fmac_f32_e32 v17, v138, v166
	v_fmac_f32_e32 v14, v142, v166
	v_fmac_f32_e32 v15, v146, v166
	v_fmac_f32_e32 v12, v150, v166
	v_fmac_f32_e32 v13, v154, v166
	v_fmac_f32_e32 v10, v158, v166
	v_fmac_f32_e32 v11, v162, v166
	v_fmac_f32_e32 v24, v103, v167
	v_fmac_f32_e32 v25, v107, v167
	v_fmac_f32_e32 v22, v111, v167
	v_fmac_f32_e32 v23, v115, v167
	v_fmac_f32_e32 v20, v119, v167
	v_fmac_f32_e32 v21, v123, v167
	v_fmac_f32_e32 v18, v127, v167
	v_fmac_f32_e32 v19, v131, v167
	v_fmac_f32_e32 v16, v135, v167
	v_fmac_f32_e32 v17, v139, v167
	v_fmac_f32_e32 v14, v143, v167
	v_fmac_f32_e32 v15, v147, v167
	v_fmac_f32_e32 v12, v151, v167
	v_fmac_f32_e32 v13, v155, v167
	v_fmac_f32_e32 v10, v159, v167
	v_fmac_f32_e32 v11, v163, v167
	global_load_dwordx4 v[100:103], v[168:169], off offset:240
	global_load_dwordx4 v[104:107], v[168:169], off offset:496
	global_load_dwordx4 v[108:111], v[168:169], off offset:752
	global_load_dwordx4 v[112:115], v[168:169], off offset:1008
	global_load_dwordx4 v[116:119], v[168:169], off offset:1264
	global_load_dwordx4 v[120:123], v[168:169], off offset:1520
	global_load_dwordx4 v[124:127], v[168:169], off offset:1776
	global_load_dwordx4 v[128:131], v[168:169], off offset:2032
	global_load_dwordx4 v[132:135], v[168:169], off offset:2288
	global_load_dwordx4 v[136:139], v[168:169], off offset:2544
	global_load_dwordx4 v[140:143], v[168:169], off offset:2800
	global_load_dwordx4 v[144:147], v[168:169], off offset:3056
	global_load_dwordx4 v[148:151], v[168:169], off offset:3312
	global_load_dwordx4 v[152:155], v[168:169], off offset:3568
	global_load_dwordx4 v[156:159], v[168:169], off offset:3824
	global_load_dwordx4 v[160:163], v[168:169], off offset:4080
	global_load_dword v164, v[170:171], off offset:-4096
	global_load_dword v165, v[170:171], off
	global_load_dword v166, v[172:173], off offset:-4096
	global_load_dword v167, v[172:173], off
	v_lshl_add_u64 v[170:171], v[170:171], 0, s[4:5]
	v_lshl_add_u64 v[172:173], v[172:173], 0, s[4:5]
	s_waitcnt vmcnt(20)
; __device__ __forceinline__ u32x4 pack8(f32x4 a, f32x4 b) { u32x4 w; w.x = pk2(a[0], a[1]); w.y = pk2(a[2], a[3]); w.z = pk2(b[0], b[1]); w.w = pk2(b[2], b[3]); return w; }
; __device__ __forceinline__ void prep_phase(const Params& p, unsigned char* smem) {
;     ...
;     for (size_t it = gtid; it < (size_t)2 * 128 * 1024; it += nth) {
;         const int j = (int)(it >> 17), rem = (int)(it & 131071), kg = rem >> 10, n = rem & 1023, h = kg >> 3, c0 = (kg & 7) * 16;
;         const float* uv = p.in[27] + (size_t)((j * 16 + h) * 128 + c0) * 64;
;         const float* wo = p.in[31] + (size_t)j * 1048576 + (size_t)(h * 64) * 1024 + n;
;         float acc[16];
; #pragma unroll
;         for (int i = 0; i < 16; ++i) acc[i] = 0.f;
;         for (int v = 0; v < 64; ++v) {
;             const float wv = wo[(size_t)v * 1024];
; #pragma unroll
;             for (int i = 0; i < 16; ++i) acc[i] += uv[i * 64 + v] * wv;
;         }
;         h16* dst = (h16*)(p.ws + OFF_WOV) + (size_t)j * 2097152 + (size_t)n * 2048 + h * 128 + c0;
;         *(u32x4*)dst = pack8((f32x4){acc[0], acc[1], acc[2], acc[3]}, (f32x4){acc[4], acc[5], acc[6], acc[7]});
;         *(u32x4*)(dst + 8) = pack8((f32x4){acc[8], acc[9], acc[10], acc[11]}, (f32x4){acc[12], acc[13], acc[14], acc[15]});
	v_fmac_f32_e32 v24, v32, v96
	v_fmac_f32_e32 v25, v36, v96
	v_fmac_f32_e32 v22, v40, v96
	v_fmac_f32_e32 v23, v44, v96
	v_fmac_f32_e32 v20, v48, v96
	v_fmac_f32_e32 v21, v52, v96
	v_fmac_f32_e32 v18, v56, v96
	v_fmac_f32_e32 v19, v60, v96
	v_fmac_f32_e32 v16, v64, v96
	v_fmac_f32_e32 v17, v68, v96
	v_fmac_f32_e32 v14, v72, v96
	v_fmac_f32_e32 v15, v76, v96
	v_fmac_f32_e32 v12, v80, v96
	v_fmac_f32_e32 v13, v84, v96
	v_fmac_f32_e32 v10, v88, v96
	v_fmac_f32_e32 v11, v92, v96
	v_fmac_f32_e32 v24, v33, v97
	v_fmac_f32_e32 v25, v37, v97
	v_fmac_f32_e32 v22, v41, v97
	v_fmac_f32_e32 v23, v45, v97
	v_fmac_f32_e32 v20, v49, v97
	v_fmac_f32_e32 v21, v53, v97
	v_fmac_f32_e32 v18, v57, v97
	v_fmac_f32_e32 v19, v61, v97
	v_fmac_f32_e32 v16, v65, v97
	v_fmac_f32_e32 v17, v69, v97
	v_fmac_f32_e32 v14, v73, v97
	v_fmac_f32_e32 v15, v77, v97
	v_fmac_f32_e32 v12, v81, v97
	v_fmac_f32_e32 v13, v85, v97
	v_fmac_f32_e32 v10, v89, v97
	v_fmac_f32_e32 v11, v93, v97
	v_fmac_f32_e32 v24, v34, v98
	v_fmac_f32_e32 v25, v38, v98
	v_fmac_f32_e32 v22, v42, v98
	v_fmac_f32_e32 v23, v46, v98
	v_fmac_f32_e32 v20, v50, v98
	v_fmac_f32_e32 v21, v54, v98
	v_fmac_f32_e32 v18, v58, v98
	v_fmac_f32_e32 v19, v62, v98
	v_fmac_f32_e32 v16, v66, v98
	v_fmac_f32_e32 v17, v70, v98
	v_fmac_f32_e32 v14, v74, v98
	v_fmac_f32_e32 v15, v78, v98
	v_fmac_f32_e32 v12, v82, v98
	v_fmac_f32_e32 v13, v86, v98
	v_fmac_f32_e32 v10, v90, v98
	v_fmac_f32_e32 v11, v94, v98
	v_fmac_f32_e32 v24, v35, v99
	v_fmac_f32_e32 v25, v39, v99
	v_fmac_f32_e32 v22, v43, v99
	v_fmac_f32_e32 v23, v47, v99
	v_fmac_f32_e32 v20, v51, v99
	v_fmac_f32_e32 v21, v55, v99
	v_fmac_f32_e32 v18, v59, v99
	v_fmac_f32_e32 v19, v63, v99
	v_fmac_f32_e32 v16, v67, v99
	v_fmac_f32_e32 v17, v71, v99
	v_fmac_f32_e32 v14, v75, v99
	v_fmac_f32_e32 v15, v79, v99
	v_fmac_f32_e32 v12, v83, v99
	v_fmac_f32_e32 v13, v87, v99
	v_fmac_f32_e32 v10, v91, v99
	v_fmac_f32_e32 v11, v95, v99
	s_waitcnt vmcnt(0)
	v_fmac_f32_e32 v24, v100, v164
	v_fmac_f32_e32 v25, v104, v164
	v_fmac_f32_e32 v22, v108, v164
	v_fmac_f32_e32 v23, v112, v164
	v_fmac_f32_e32 v20, v116, v164
	v_fmac_f32_e32 v21, v120, v164
	v_fmac_f32_e32 v18, v124, v164
	v_fmac_f32_e32 v19, v128, v164
	v_fmac_f32_e32 v16, v132, v164
	v_fmac_f32_e32 v17, v136, v164
	v_fmac_f32_e32 v14, v140, v164
	v_fmac_f32_e32 v15, v144, v164
	v_fmac_f32_e32 v12, v148, v164
	v_fmac_f32_e32 v13, v152, v164
	v_fmac_f32_e32 v10, v156, v164
	v_fmac_f32_e32 v11, v160, v164
	v_fmac_f32_e32 v24, v101, v165
	v_fmac_f32_e32 v25, v105, v165
	v_fmac_f32_e32 v22, v109, v165
	v_fmac_f32_e32 v23, v113, v165
	v_fmac_f32_e32 v20, v117, v165
	v_fmac_f32_e32 v21, v121, v165
	v_fmac_f32_e32 v18, v125, v165
	v_fmac_f32_e32 v19, v129, v165
	v_fmac_f32_e32 v16, v133, v165
	v_fmac_f32_e32 v17, v137, v165
	v_fmac_f32_e32 v14, v141, v165
	v_fmac_f32_e32 v15, v145, v165
	v_fmac_f32_e32 v12, v149, v165
	v_fmac_f32_e32 v13, v153, v165
	v_fmac_f32_e32 v10, v157, v165
	v_fmac_f32_e32 v11, v161, v165
	v_fmac_f32_e32 v24, v102, v166
	v_fmac_f32_e32 v25, v106, v166
	v_fmac_f32_e32 v22, v110, v166
	v_fmac_f32_e32 v23, v114, v166
	v_fmac_f32_e32 v20, v118, v166
	v_fmac_f32_e32 v21, v122, v166
	v_fmac_f32_e32 v18, v126, v166
	v_fmac_f32_e32 v19, v130, v166
	v_fmac_f32_e32 v16, v134, v166
	v_fmac_f32_e32 v17, v138, v166
	v_fmac_f32_e32 v14, v142, v166
	v_fmac_f32_e32 v15, v146, v166
	v_fmac_f32_e32 v12, v150, v166
	v_fmac_f32_e32 v13, v154, v166
	v_fmac_f32_e32 v10, v158, v166
	v_fmac_f32_e32 v11, v162, v166
	v_fmac_f32_e32 v24, v103, v167
	v_fmac_f32_e32 v25, v107, v167
	v_fmac_f32_e32 v22, v111, v167
	v_fmac_f32_e32 v23, v115, v167
	v_fmac_f32_e32 v20, v119, v167
	v_fmac_f32_e32 v21, v123, v167
	v_fmac_f32_e32 v18, v127, v167
	v_fmac_f32_e32 v19, v131, v167
	v_fmac_f32_e32 v16, v135, v167
	v_fmac_f32_e32 v17, v139, v167
	v_fmac_f32_e32 v14, v143, v167
	v_fmac_f32_e32 v15, v147, v167
	v_fmac_f32_e32 v12, v151, v167
	v_fmac_f32_e32 v13, v155, v167
	v_fmac_f32_e32 v10, v159, v167
	v_fmac_f32_e32 v11, v163, v167
	v_readlane_b32 s4, v250, 48
	v_and_b32_e32 v6, 0x3ff, v2
	v_readlane_b32 s5, v250, 49
	v_lshlrev_b32_e32 v196, 12, v6
	v_lshrrev_b32_e32 v6, 5, v2
	v_lshl_add_u64 v[4:5], s[4:5], 0, v[4:5]
	v_readlane_b32 s4, v250, 42
	v_lshl_add_u64 v[4:5], v[4:5], 0, v[196:197]
	v_and_b32_e32 v196, 0xf00, v6
	v_readlane_b32 s5, v250, 43
	v_lshl_add_u64 v[4:5], v[4:5], 0, v[196:197]
	v_and_b32_e32 v196, 0xe0, v6
	v_lshl_add_u64 v[2:3], v[2:3], 0, s[4:5]
	s_mov_b64 s[4:5], 0x3ffff
	v_lshl_add_u64 v[8:9], v[4:5], 0, v[196:197]
	v_cvt_pk_f16_f32 v4, v24, v25
	v_cvt_pk_f16_f32 v5, v22, v23
	v_cvt_pk_f16_f32 v6, v20, v21
	v_cvt_pk_f16_f32 v7, v18, v19
	v_readlane_b32 s6, v251, 48
	v_cmp_lt_u64_e32 vcc, s[4:5], v[2:3]
	global_store_dwordx4 v[8:9], v[4:7], off
	v_add_u32_e32 v1, s6, v1
	s_or_b64 s[2:3], vcc, s[2:3]
	v_cvt_pk_f16_f32 v4, v16, v17
	v_cvt_pk_f16_f32 v5, v14, v15
	v_cvt_pk_f16_f32 v6, v12, v13
	v_cvt_pk_f16_f32 v7, v10, v11
	v_subrev_u16_e32 v26, s6, v26
	global_store_dwordx4 v[8:9], v[4:7], off offset:16
	s_andn2_b64 exec, exec, s[2:3]
	s_cbranch_execnz .LBB0_531

; __device__ __forceinline__ void prep_phase(const Params& p, unsigned char* smem) {
;     ...
;         for (int tix = (int)((blockIdx.x + gridDim.x - (unsigned)(id * 37) % gridDim.x) % gridDim.x); tix < ntile; tix += gridDim.x) {
;             const int k0 = (tix % tk) * 64, n0 = (tix / tk) * 64;
; #pragma unroll
;             for (int i = 0; i < 8; ++i) {
;                 const int k = i * 8 + (tid >> 6), n = tid & 63, kk = k0 + k, nn = n0 + n;
;                 float v = 0.f;
;                 if (nn < J.N && J.mode != 2) {
;                     if (J.mode == 1) { const int ks = kk & 1023; const float mx = J.mix[ks]; v = J.src[(size_t)ks * J.ld + nn] * (kk < 1024 ? 1.0f - mx : mx); }
;                     else if (kk >= J.koff && kk < J.koff + J.K) v = J.src[(size_t)(kk - J.koff) * J.ld + nn];
;                 }
;                 tile[k * 65 + n] = v;
;             }
.LBB0_599:
	s_abs_i32 s1, s26
	s_mul_hi_u32 s4, s1, s28
	s_mul_i32 s5, s4, s24
	s_sub_i32 s1, s1, s5
	s_ashr_i32 s0, s26, 31
	s_add_i32 s5, s4, 1
	s_sub_i32 s14, s1, s24
	s_cmp_ge_u32 s1, s24
	s_cselect_b32 s4, s5, s4
	s_cselect_b32 s1, s14, s1
	s_add_i32 s5, s4, 1
	s_cmp_ge_u32 s1, s24
	s_cselect_b32 s1, s5, s4
	s_xor_b32 s1, s1, s0
	s_sub_i32 s14, s1, s0
	s_lshl_b32 s31, s14, 6
	v_or_b32_e32 v4, s31, v0
	v_cmp_le_i32_e32 vcc, s21, v4
	s_or_b64 s[16:17], s[12:13], vcc
	s_and_saveexec_b64 s[0:1], s[16:17]
	s_xor_b64 s[0:1], exec, s[0:1]
	ds_write_b32 v14, v197
	s_or_saveexec_b64 s[4:5], s[0:1]
	s_mul_i32 s0, s29, s14
	v_ashrrev_i32_e32 v5, 31, v4
	s_add_i32 s14, s0, s30
	v_lshl_add_u64 v[4:5], v[4:5], 2, s[2:3]
	s_waitcnt vmcnt(0)
	v_add_u32_e32 v16, s14, v1
	v_mov_b32_e32 v18, 0
	s_xor_b64 exec, exec, s[4:5]
	s_cbranch_execz .LBB0_614
	s_cmp_lg_u64 s[10:11], 0
	s_cbranch_scc0 .Ltr_slow
	s_cmp_lg_u32 s7, 0
	s_cbranch_scc1 .Ltr_slow
	s_cmp_le_i32 s23, s14
	s_cbranch_scc0 .Ltr_slow
	s_add_i32 s18, s14, 64
	s_cmp_le_i32 s18, s27
	s_cbranch_scc0 .Ltr_slow
	v_add_u32_e32 v17, s14, v15
	v_mad_u64_u32 v[110:111], s[18:19], s6, v17, 0
	v_lshl_add_u64 v[110:111], v[110:111], 2, v[4:5]
	global_load_dword v100, v[110:111], off
	v_add_u32_e32 v126, 8, v17
	v_mad_u64_u32 v[112:113], s[18:19], s6, v126, 0
	v_lshl_add_u64 v[112:113], v[112:113], 2, v[4:5]
	global_load_dword v101, v[112:113], off
	v_add_u32_e32 v126, 16, v17
	v_mad_u64_u32 v[114:115], s[18:19], s6, v126, 0
	v_lshl_add_u64 v[114:115], v[114:115], 2, v[4:5]
	global_load_dword v102, v[114:115], off
	v_add_u32_e32 v126, 24, v17
	v_mad_u64_u32 v[116:117], s[18:19], s6, v126, 0
	v_lshl_add_u64 v[116:117], v[116:117], 2, v[4:5]
	global_load_dword v103, v[116:117], off
	v_add_u32_e32 v126, 32, v17
	v_mad_u64_u32 v[118:119], s[18:19], s6, v126, 0
	v_lshl_add_u64 v[118:119], v[118:119], 2, v[4:5]
	global_load_dword v104, v[118:119], off
	v_add_u32_e32 v126, 40, v17
	v_mad_u64_u32 v[120:121], s[18:19], s6, v126, 0
	v_lshl_add_u64 v[120:121], v[120:121], 2, v[4:5]
	global_load_dword v105, v[120:121], off
	v_add_u32_e32 v126, 48, v17
	v_mad_u64_u32 v[122:123], s[18:19], s6, v126, 0
	v_lshl_add_u64 v[122:123], v[122:123], 2, v[4:5]
	global_load_dword v106, v[122:123], off
	v_add_u32_e32 v126, 56, v17
	v_mad_u64_u32 v[124:125], s[18:19], s6, v126, 0
	v_lshl_add_u64 v[124:125], v[124:125], 2, v[4:5]
	global_load_dword v107, v[124:125], off
	s_waitcnt vmcnt(0)
	ds_write_b32 v14, v100
	ds_write_b32 v14, v101 offset:2080
	ds_write_b32 v14, v102 offset:4160
	ds_write_b32 v14, v103 offset:6240
	ds_write_b32 v14, v104 offset:8320
	ds_write_b32 v14, v105 offset:10400
	ds_write_b32 v14, v106 offset:12480
	ds_write_b32 v14, v107 offset:14560
	s_or_b64 exec, exec, s[4:5]
	s_and_saveexec_b64 s[0:1], s[16:17]
	ds_write_b32 v14, v197 offset:2080
	ds_write_b32 v14, v197 offset:4160
	ds_write_b32 v14, v197 offset:6240
	ds_write_b32 v14, v197 offset:8320
	ds_write_b32 v14, v197 offset:10400
	ds_write_b32 v14, v197 offset:12480
	ds_write_b32 v14, v197 offset:14560
	s_or_b64 exec, exec, s[0:1]
	s_ashr_i32 s15, s14, 31
	v_add_u32_e32 v16, s31, v1
	v_lshl_add_u64 v[4:5], s[14:15], 1, v[2:3]
	v_cmp_gt_i32_e32 vcc, s21, v16
	s_branch .Ltr_join
.Ltr_slow:
	s_mov_b64 s[0:1], -1
	s_and_b64 vcc, exec, s[10:11]
	s_cbranch_vccz .LBB0_606
	v_cmp_le_i32_e32 vcc, s23, v16
	v_cmp_gt_i32_e64 s[0:1], s27, v16
	s_and_b64 s[18:19], vcc, s[0:1]
	v_mov_b32_e32 v17, 0
	s_and_saveexec_b64 s[0:1], s[18:19]
	s_cbranch_execz .LBB0_605
	v_add_u32_e32 v17, s14, v15
	v_mad_u64_u32 v[18:19], s[18:19], s6, v17, 0
	s_waitcnt vmcnt(0)
	v_mov_b32_e32 v20, v19
	v_mad_u64_u32 v[20:21], s[18:19], s7, v17, v[20:21]
	v_mov_b32_e32 v19, v20
	v_lshl_add_u64 v[18:19], v[18:19], 2, v[4:5]
	global_load_dword v17, v[18:19], off

; __device__ __forceinline__ void prep_phase(const Params& p, unsigned char* smem) {
;     ...
;             __syncthreads();
; #pragma unroll
;             for (int i = 0; i < 8; ++i) {
;                 const int n = i * 8 + (tid >> 6), k = tid & 63, nn = n0 + n;
;                 if (nn < J.N) J.dst[(size_t)nn * J.ldd + k0 + k] = (h16)tile[k * 65 + n];
;             }
.Ltr_join:
	s_waitcnt lgkmcnt(0)
	s_barrier
	s_and_saveexec_b64 s[0:1], vcc
	s_cbranch_execz .LBB0_661
	ds_read_b32 v19, v13
	v_ashrrev_i32_e32 v20, 31, v16
	v_mad_u64_u32 v[16:17], s[4:5], v16, s22, 0
	v_mov_b32_e32 v18, v17
	s_waitcnt lgkmcnt(0)
	v_cvt_f16_f32_e32 v21, v19
	v_mad_u64_u32 v[18:19], s[4:5], v20, s22, v[18:19]
	v_mov_b32_e32 v17, v18
	v_lshl_add_u64 v[16:17], v[16:17], 1, v[4:5]
	global_store_short v[16:17], v21, off
